# stack on v10: static s_setprio 1 for waves 4-7 in attention, per-unit kernarg load hoisted, MIX1 no-op phase skipped, tile-header wait moved after acc zeroing, PROJA/BRA2 epilogue ssq hoist, RNN gate-
# speedup vs baseline: 1.0221x; 1.0057x over previous
; #define PG8_STAGE(bufoff, gbase, voff) do { _Pragma("unroll") for (int _i = 0; _i < 2; ++_i) \
;         __builtin_amdgcn_global_load_lds((const unsigned*)((const char*)(gbase) + (voff)[_i]), (LAS unsigned*)(lds + (bufoff) + ldsw + _i * 8192), 16, 0, 0); } while (0)
; #define PG8_LDA(dst, b, h) do { _Pragma("unroll") for (int m = 0; m < 4; ++m) _Pragma("unroll") for (int k = 0; k < 2; ++k) dst[m][k] = *(const LAS bf16x8*)(lds + PG8_SA(b, h) + aoff + m * 2048 + k * 1024); } while (0)
; #define PG8_LDB(dst, b, h) do { _Pragma("unroll") for (int n = 0; n < 2; ++n) _Pragma("unroll") for (int k = 0; k < 2; ++k) dst[n][k] = *(const LAS bf16x8*)(lds + PG8_SB(b, h) + boff + n * 2048 + k * 1024); } while (0)
; #define PG8_WAIT_V(n) asm volatile("s_waitcnt vmcnt(" #n ")" ::: "memory")
; #define PG8_WAIT_L(n) asm volatile("s_waitcnt lgkmcnt(" #n ")" ::: "memory")
; #define PG8_BAR __builtin_amdgcn_s_barrier()
; #define PG8_SCHED __builtin_amdgcn_sched_barrier(0)
;     ...
;         for (int t = 0; t < nt; t += 2) {
;             const bool last = (t == nt - 2);
;             const char* a1 = cA + (size_t)(t + 1) * kstep;
;             const char* a2 = last ? nA : cA + (size_t)(t + 2) * kstep; const char* b2 = last ? nB : cB + (size_t)(t + 2) * kstep;
;             const char* a3 = a2 + kstep; const char* b3 = b2 + kstep;
;             if constexpr (SP2) {
;             PG8_LDB(B0, 0, 0); PG8_LDB(B1, 0, 1); PG8_SCHED; PG8_LDA(At, 0, 0); PG8_STAGE(PG8_SA(1, 1), a1 + hstepA, voffA);
;             PG8_WAIT_V(8); PG8_WAIT_L(0); PG8_BAR; PG8_MMA(0, 0, At, B0); PG8_MMA(0, 1, At, B1); PG8_BAR; PG8_SCHED;
;             PG8_LDA(At, 0, 1); PG8_STAGE(PG8_SB(0, 0), b2, voffB); PG8_STAGE(PG8_SB(0, 1), b2 + hstepB, voffB); PG8_STAGE(PG8_SA(0, 0), a2, voffA);
;             PG8_WAIT_V(8); PG8_WAIT_L(0); PG8_BAR; PG8_MMA(1, 0, At, B0); PG8_MMA(1, 1, At, B1); PG8_BAR; PG8_SCHED;
;             PG8_LDB(B0, 1, 0); PG8_LDB(B1, 1, 1); PG8_SCHED; PG8_LDA(At, 1, 0); PG8_STAGE(PG8_SA(0, 1), a2 + hstepA, voffA);
;             PG8_WAIT_V(8); PG8_WAIT_L(0); PG8_BAR; PG8_MMA(0, 0, At, B0); PG8_MMA(0, 1, At, B1); PG8_BAR; PG8_SCHED;
;             PG8_LDA(At, 1, 1); PG8_STAGE(PG8_SB(1, 0), b3, voffB); PG8_STAGE(PG8_SB(1, 1), b3 + hstepB, voffB); PG8_STAGE(PG8_SA(1, 0), a3, voffA);
;             PG8_WAIT_V(8); PG8_WAIT_L(0); PG8_BAR; PG8_MMA(1, 0, At, B0); PG8_MMA(1, 1, At, B1); PG8_BAR; PG8_SCHED;
.LBB0_58:
	s_add_u32 s75, s76, 0xfffc0080
	s_addc_u32 s78, s77, -1
	s_add_i32 s86, 0, 0x10000
	s_cmp_eq_u32 s61, 12
	s_cselect_b32 s81, s11, s78
	s_cselect_b32 s80, s34, s75
	v_add_u32_e32 v144, s86, v146
	s_cselect_b32 s79, s9, s60
	s_cselect_b32 s78, s35, s42
	s_add_i32 s75, 0, 0x14000
	ds_read_b128 v[166:169], v144
	ds_read_b128 v[170:173], v144 offset:1024
	ds_read_b128 v[174:177], v144 offset:2048
	ds_read_b128 v[192:195], v144 offset:3072
	v_add_u32_e32 v144, s75, v146
	ds_read_b128 v[196:199], v144
	ds_read_b128 v[200:203], v144 offset:1024
	ds_read_b128 v[204:207], v144 offset:2048
	ds_read_b128 v[208:211], v144 offset:3072
	v_lshl_add_u64 v[144:145], s[76:77], 0, v[142:143]
	s_add_i32 m0, s30, 0xc000
	ds_read_b128 v[212:215], v164
	ds_read_b128 v[216:219], v164 offset:1024
	ds_read_b128 v[220:223], v164 offset:2048
	ds_read_b128 v[224:227], v164 offset:3072
	ds_read_b128 v[228:231], v164 offset:4096
	ds_read_b128 v[232:235], v164 offset:5120
	ds_read_b128 v[236:239], v164 offset:6144
	ds_read_b128 v[240:243], v164 offset:7168
	global_load_lds_dwordx4 v[144:145], off
	v_lshl_add_u64 v[144:145], s[76:77], 0, v[140:141]
	s_add_i32 m0, s30, 0xe000
	s_nop 0
	global_load_lds_dwordx4 v[144:145], off
	s_waitcnt vmcnt(8)
	s_waitcnt lgkmcnt(0)
	s_barrier
	s_setprio 3
	s_waitcnt lgkmcnt(0)
	v_mfma_f32_16x16x32_bf16 v[126:129], v[166:169], v[212:215], v[126:129]
	v_mfma_f32_16x16x32_bf16 v[122:125], v[174:177], v[212:215], v[122:125]
	v_mfma_f32_16x16x32_bf16 v[110:113], v[166:169], v[220:223], v[110:113]
	v_mfma_f32_16x16x32_bf16 v[106:109], v[174:177], v[220:223], v[106:109]
	v_mfma_f32_16x16x32_bf16 v[94:97], v[166:169], v[228:231], v[94:97]
	v_mfma_f32_16x16x32_bf16 v[90:93], v[174:177], v[228:231], v[90:93]
	v_mfma_f32_16x16x32_bf16 v[78:81], v[166:169], v[236:239], v[78:81]
	v_mfma_f32_16x16x32_bf16 v[74:77], v[174:177], v[236:239], v[74:77]
	v_mfma_f32_16x16x32_bf16 v[126:129], v[170:173], v[216:219], v[126:129]
	v_mfma_f32_16x16x32_bf16 v[122:125], v[192:195], v[216:219], v[122:125]
	v_mfma_f32_16x16x32_bf16 v[110:113], v[170:173], v[224:227], v[110:113]
	v_mfma_f32_16x16x32_bf16 v[106:109], v[192:195], v[224:227], v[106:109]
	v_mfma_f32_16x16x32_bf16 v[94:97], v[170:173], v[232:235], v[94:97]
	v_mfma_f32_16x16x32_bf16 v[90:93], v[192:195], v[232:235], v[90:93]
	v_mfma_f32_16x16x32_bf16 v[78:81], v[170:173], v[240:243], v[78:81]
	v_mfma_f32_16x16x32_bf16 v[74:77], v[192:195], v[240:243], v[74:77]
	s_setprio 0
	s_setprio 3
	v_mfma_f32_16x16x32_bf16 v[118:121], v[196:199], v[212:215], v[118:121]
	v_mfma_f32_16x16x32_bf16 v[114:117], v[204:207], v[212:215], v[114:117]
	v_mfma_f32_16x16x32_bf16 v[102:105], v[196:199], v[220:223], v[102:105]
	v_mfma_f32_16x16x32_bf16 v[98:101], v[204:207], v[220:223], v[98:101]
	v_mfma_f32_16x16x32_bf16 v[86:89], v[196:199], v[228:231], v[86:89]
	v_mfma_f32_16x16x32_bf16 v[82:85], v[204:207], v[228:231], v[82:85]
	v_mfma_f32_16x16x32_bf16 v[70:73], v[196:199], v[236:239], v[70:73]
	v_mfma_f32_16x16x32_bf16 v[66:69], v[204:207], v[236:239], v[66:69]
	v_mfma_f32_16x16x32_bf16 v[118:121], v[200:203], v[216:219], v[118:121]
	v_mfma_f32_16x16x32_bf16 v[114:117], v[208:211], v[216:219], v[114:117]
	v_mfma_f32_16x16x32_bf16 v[102:105], v[200:203], v[224:227], v[102:105]
	v_mfma_f32_16x16x32_bf16 v[98:101], v[208:211], v[224:227], v[98:101]
	v_mfma_f32_16x16x32_bf16 v[86:89], v[200:203], v[232:235], v[86:89]
	v_mfma_f32_16x16x32_bf16 v[82:85], v[208:211], v[232:235], v[82:85]
	v_mfma_f32_16x16x32_bf16 v[70:73], v[200:203], v[240:243], v[70:73]
	v_mfma_f32_16x16x32_bf16 v[66:69], v[208:211], v[240:243], v[66:69]
	s_setprio 0
	s_barrier
	s_add_i32 s86, s86, s17
	v_lshl_add_u64 v[144:145], s[78:79], 0, v[134:135]
	s_mov_b32 m0, s86
	ds_read_b128 v[212:215], v164 offset:16384
	ds_read_b128 v[216:219], v164 offset:17408
	ds_read_b128 v[220:223], v164 offset:18432
	ds_read_b128 v[224:227], v164 offset:19456
	ds_read_b128 v[228:231], v164 offset:20480
	ds_read_b128 v[232:235], v164 offset:21504
	ds_read_b128 v[236:239], v164 offset:22528
	ds_read_b128 v[240:243], v164 offset:23552
	global_load_lds_dwordx4 v[144:145], off
	s_add_i32 m0, s86, 0x2000
	s_add_u32 s86, s78, 0x10000
	v_lshl_add_u64 v[244:245], s[78:79], 0, v[130:131]
	s_addc_u32 s87, s79, 0
	s_add_i32 s75, s75, s17
	global_load_lds_dwordx4 v[244:245], off
	v_lshl_add_u64 v[246:247], s[86:87], 0, v[134:135]
	s_mov_b32 m0, s75
	v_lshl_add_u64 v[248:249], s[80:81], 0, v[132:133]
	global_load_lds_dwordx4 v[246:247], off
	v_lshl_add_u64 v[246:247], s[86:87], 0, v[130:131]
	s_add_i32 m0, s75, 0x2000
	s_nop 0
	global_load_lds_dwordx4 v[246:247], off
	v_lshl_add_u64 v[246:247], s[80:81], 0, v[136:137]
	s_mov_b32 m0, s30
	s_nop 0
	global_load_lds_dwordx4 v[246:247], off
	s_mov_b32 m0, s31
	s_nop 0
	global_load_lds_dwordx4 v[248:249], off
	s_waitcnt vmcnt(8)
	s_waitcnt lgkmcnt(0)
	s_barrier
; #define PG8_STAGE(bufoff, gbase, voff) do { _Pragma("unroll") for (int _i = 0; _i < 2; ++_i) \
;         __builtin_amdgcn_global_load_lds((const unsigned*)((const char*)(gbase) + (voff)[_i]), (LAS unsigned*)(lds + (bufoff) + ldsw + _i * 8192), 16, 0, 0); } while (0)
; #define PG8_LDA(dst, b, h) do { _Pragma("unroll") for (int m = 0; m < 4; ++m) _Pragma("unroll") for (int k = 0; k < 2; ++k) dst[m][k] = *(const LAS bf16x8*)(lds + PG8_SA(b, h) + aoff + m * 2048 + k * 1024); } while (0)
; #define PG8_LDB(dst, b, h) do { _Pragma("unroll") for (int n = 0; n < 2; ++n) _Pragma("unroll") for (int k = 0; k < 2; ++k) dst[n][k] = *(const LAS bf16x8*)(lds + PG8_SB(b, h) + boff + n * 2048 + k * 1024); } while (0)
; #define PG8_MMA(ai, bj, At, Bt) do { __builtin_amdgcn_s_setprio(3); _Pragma("unroll") for (int m = 0; m < 4; ++m) _Pragma("unroll") for (int n = 0; n < 2; ++n) _Pragma("unroll") for (int k = 0; k < 2; ++k) \
;         acc[ai][bj][m][n] = __builtin_amdgcn_mfma_f32_16x16x32_bf16(Bt[n][k], At[m][k], acc[ai][bj][m][n], 0, 0, 0); __builtin_amdgcn_s_setprio(0); } while (0)
; #define PG8_WAIT_V(n) asm volatile("s_waitcnt vmcnt(" #n ")" ::: "memory")
; #define PG8_WAIT_L(n) asm volatile("s_waitcnt lgkmcnt(" #n ")" ::: "memory")
; #define PG8_BAR __builtin_amdgcn_s_barrier()
; #define PG8_SCHED __builtin_amdgcn_sched_barrier(0)
;     ...
;             PG8_LDB(B0, 0, 0); PG8_LDB(B1, 0, 1); PG8_SCHED; PG8_LDA(At, 0, 0); PG8_STAGE(PG8_SA(1, 1), a1 + hstepA, voffA);
;             PG8_WAIT_V(8); PG8_WAIT_L(0); PG8_BAR; PG8_MMA(0, 0, At, B0); PG8_MMA(0, 1, At, B1); PG8_BAR; PG8_SCHED;
;             PG8_LDA(At, 0, 1); PG8_STAGE(PG8_SB(0, 0), b2, voffB); PG8_STAGE(PG8_SB(0, 1), b2 + hstepB, voffB); PG8_STAGE(PG8_SA(0, 0), a2, voffA);
;             PG8_WAIT_V(8); PG8_WAIT_L(0); PG8_BAR; PG8_MMA(1, 0, At, B0); PG8_MMA(1, 1, At, B1); PG8_BAR; PG8_SCHED;
;             PG8_LDB(B0, 1, 0); PG8_LDB(B1, 1, 1); PG8_SCHED; PG8_LDA(At, 1, 0); PG8_STAGE(PG8_SA(0, 1), a2 + hstepA, voffA);
;             PG8_WAIT_V(8); PG8_WAIT_L(0); PG8_BAR; PG8_MMA(0, 0, At, B0); PG8_MMA(0, 1, At, B1); PG8_BAR; PG8_SCHED;
;             PG8_LDA(At, 1, 1); PG8_STAGE(PG8_SB(1, 0), b3, voffB); PG8_STAGE(PG8_SB(1, 1), b3 + hstepB, voffB); PG8_STAGE(PG8_SA(1, 0), a3, voffA);
;             PG8_WAIT_V(8); PG8_WAIT_L(0); PG8_BAR; PG8_MMA(1, 0, At, B0); PG8_MMA(1, 1, At, B1); PG8_BAR; PG8_SCHED;
	s_setprio 3
	s_waitcnt lgkmcnt(0)
	v_mfma_f32_16x16x32_bf16 v[62:65], v[166:169], v[212:215], v[62:65]
	v_mfma_f32_16x16x32_bf16 v[58:61], v[174:177], v[212:215], v[58:61]
	v_mfma_f32_16x16x32_bf16 v[46:49], v[166:169], v[220:223], v[46:49]
	v_mfma_f32_16x16x32_bf16 v[42:45], v[174:177], v[220:223], v[42:45]
	v_mfma_f32_16x16x32_bf16 v[30:33], v[166:169], v[228:231], v[30:33]
	v_mfma_f32_16x16x32_bf16 v[26:29], v[174:177], v[228:231], v[26:29]
	v_mfma_f32_16x16x32_bf16 v[14:17], v[166:169], v[236:239], v[14:17]
	v_mfma_f32_16x16x32_bf16 v[10:13], v[174:177], v[236:239], v[10:13]
	v_mfma_f32_16x16x32_bf16 v[62:65], v[170:173], v[216:219], v[62:65]
	v_mfma_f32_16x16x32_bf16 v[58:61], v[192:195], v[216:219], v[58:61]
	v_mfma_f32_16x16x32_bf16 v[46:49], v[170:173], v[224:227], v[46:49]
	v_mfma_f32_16x16x32_bf16 v[42:45], v[192:195], v[224:227], v[42:45]
	v_mfma_f32_16x16x32_bf16 v[30:33], v[170:173], v[232:235], v[30:33]
	v_mfma_f32_16x16x32_bf16 v[26:29], v[192:195], v[232:235], v[26:29]
	v_mfma_f32_16x16x32_bf16 v[14:17], v[170:173], v[240:243], v[14:17]
	v_mfma_f32_16x16x32_bf16 v[10:13], v[192:195], v[240:243], v[10:13]
	s_setprio 0
	s_setprio 3
	v_mfma_f32_16x16x32_bf16 v[54:57], v[196:199], v[212:215], v[54:57]
	v_mfma_f32_16x16x32_bf16 v[50:53], v[204:207], v[212:215], v[50:53]
	v_mfma_f32_16x16x32_bf16 v[38:41], v[196:199], v[220:223], v[38:41]
	v_mfma_f32_16x16x32_bf16 v[34:37], v[204:207], v[220:223], v[34:37]
	v_mfma_f32_16x16x32_bf16 v[22:25], v[196:199], v[228:231], v[22:25]
	v_mfma_f32_16x16x32_bf16 v[18:21], v[204:207], v[228:231], v[18:21]
	v_mfma_f32_16x16x32_bf16 v[6:9], v[196:199], v[236:239], v[6:9]
	v_mfma_f32_16x16x32_bf16 v[2:5], v[204:207], v[236:239], v[2:5]
	v_mfma_f32_16x16x32_bf16 v[54:57], v[200:203], v[216:219], v[54:57]
	v_mfma_f32_16x16x32_bf16 v[50:53], v[208:211], v[216:219], v[50:53]
	v_mfma_f32_16x16x32_bf16 v[38:41], v[200:203], v[224:227], v[38:41]
	v_mfma_f32_16x16x32_bf16 v[34:37], v[208:211], v[224:227], v[34:37]
	v_mfma_f32_16x16x32_bf16 v[22:25], v[200:203], v[232:235], v[22:25]
	v_mfma_f32_16x16x32_bf16 v[18:21], v[208:211], v[232:235], v[18:21]
	v_mfma_f32_16x16x32_bf16 v[6:9], v[200:203], v[240:243], v[6:9]
	v_mfma_f32_16x16x32_bf16 v[2:5], v[208:211], v[240:243], v[2:5]
	s_setprio 0
	s_barrier
	s_add_i32 s75, 0, 0x18000
	v_add_u32_e32 v165, s75, v146
	s_add_i32 s86, 0, 0x1c000
	ds_read_b128 v[166:169], v165
	ds_read_b128 v[170:173], v165 offset:1024
	ds_read_b128 v[174:177], v165 offset:2048
	ds_read_b128 v[192:195], v165 offset:3072
	v_add_u32_e32 v165, s86, v146
	ds_read_b128 v[196:199], v165
	ds_read_b128 v[200:203], v165 offset:1024
	ds_read_b128 v[204:207], v165 offset:2048
	ds_read_b128 v[208:211], v165 offset:3072
	s_add_u32 s80, s80, 0x40000
	s_addc_u32 s81, s81, 0
	s_mov_b32 m0, s68
	v_lshl_add_u64 v[250:251], s[80:81], 0, v[136:137]
	ds_read_b128 v[212:215], v164 offset:32768
	ds_read_b128 v[216:219], v164 offset:33792
	ds_read_b128 v[220:223], v164 offset:34816
	ds_read_b128 v[224:227], v164 offset:35840
	ds_read_b128 v[228:231], v164 offset:36864
	ds_read_b128 v[232:235], v164 offset:37888
	ds_read_b128 v[236:239], v164 offset:38912
	ds_read_b128 v[240:243], v164 offset:39936
	global_load_lds_dwordx4 v[250:251], off
	v_lshl_add_u64 v[250:251], s[80:81], 0, v[132:133]
	s_mov_b32 m0, s69
	s_nop 0
	global_load_lds_dwordx4 v[250:251], off
	s_waitcnt vmcnt(8)
	s_waitcnt lgkmcnt(0)
	s_barrier
	s_setprio 3
	s_waitcnt lgkmcnt(0)
	v_mfma_f32_16x16x32_bf16 v[126:129], v[166:169], v[212:215], v[126:129]
	v_mfma_f32_16x16x32_bf16 v[122:125], v[174:177], v[212:215], v[122:125]
	v_mfma_f32_16x16x32_bf16 v[110:113], v[166:169], v[220:223], v[110:113]
	v_mfma_f32_16x16x32_bf16 v[106:109], v[174:177], v[220:223], v[106:109]
	v_mfma_f32_16x16x32_bf16 v[94:97], v[166:169], v[228:231], v[94:97]
	v_mfma_f32_16x16x32_bf16 v[90:93], v[174:177], v[228:231], v[90:93]
	v_mfma_f32_16x16x32_bf16 v[78:81], v[166:169], v[236:239], v[78:81]
	v_mfma_f32_16x16x32_bf16 v[74:77], v[174:177], v[236:239], v[74:77]
	v_mfma_f32_16x16x32_bf16 v[126:129], v[170:173], v[216:219], v[126:129]
	v_mfma_f32_16x16x32_bf16 v[122:125], v[192:195], v[216:219], v[122:125]
	v_mfma_f32_16x16x32_bf16 v[110:113], v[170:173], v[224:227], v[110:113]
	v_mfma_f32_16x16x32_bf16 v[106:109], v[192:195], v[224:227], v[106:109]
	v_mfma_f32_16x16x32_bf16 v[94:97], v[170:173], v[232:235], v[94:97]
	v_mfma_f32_16x16x32_bf16 v[90:93], v[192:195], v[232:235], v[90:93]
	v_mfma_f32_16x16x32_bf16 v[78:81], v[170:173], v[240:243], v[78:81]
	v_mfma_f32_16x16x32_bf16 v[74:77], v[192:195], v[240:243], v[74:77]
	s_setprio 0
	s_setprio 3
	v_mfma_f32_16x16x32_bf16 v[118:121], v[196:199], v[212:215], v[118:121]
	v_mfma_f32_16x16x32_bf16 v[114:117], v[204:207], v[212:215], v[114:117]
	v_mfma_f32_16x16x32_bf16 v[102:105], v[196:199], v[220:223], v[102:105]
	v_mfma_f32_16x16x32_bf16 v[98:101], v[204:207], v[220:223], v[98:101]
	v_mfma_f32_16x16x32_bf16 v[86:89], v[196:199], v[228:231], v[86:89]
	v_mfma_f32_16x16x32_bf16 v[82:85], v[204:207], v[228:231], v[82:85]
	v_mfma_f32_16x16x32_bf16 v[70:73], v[196:199], v[236:239], v[70:73]
	v_mfma_f32_16x16x32_bf16 v[66:69], v[204:207], v[236:239], v[66:69]
	v_mfma_f32_16x16x32_bf16 v[118:121], v[200:203], v[216:219], v[118:121]
	v_mfma_f32_16x16x32_bf16 v[114:117], v[208:211], v[216:219], v[114:117]
	v_mfma_f32_16x16x32_bf16 v[102:105], v[200:203], v[224:227], v[102:105]
	v_mfma_f32_16x16x32_bf16 v[98:101], v[208:211], v[224:227], v[98:101]
	v_mfma_f32_16x16x32_bf16 v[86:89], v[200:203], v[232:235], v[86:89]
	v_mfma_f32_16x16x32_bf16 v[82:85], v[208:211], v[232:235], v[82:85]
	v_mfma_f32_16x16x32_bf16 v[70:73], v[200:203], v[240:243], v[70:73]
	v_mfma_f32_16x16x32_bf16 v[66:69], v[208:211], v[240:243], v[66:69]
	s_setprio 0
	s_barrier
; #define PG8_STAGE(bufoff, gbase, voff) do { _Pragma("unroll") for (int _i = 0; _i < 2; ++_i) \
;         __builtin_amdgcn_global_load_lds((const unsigned*)((const char*)(gbase) + (voff)[_i]), (LAS unsigned*)(lds + (bufoff) + ldsw + _i * 8192), 16, 0, 0); } while (0)
; #define PG8_LDA(dst, b, h) do { _Pragma("unroll") for (int m = 0; m < 4; ++m) _Pragma("unroll") for (int k = 0; k < 2; ++k) dst[m][k] = *(const LAS bf16x8*)(lds + PG8_SA(b, h) + aoff + m * 2048 + k * 1024); } while (0)
; #define PG8_LDB(dst, b, h) do { _Pragma("unroll") for (int n = 0; n < 2; ++n) _Pragma("unroll") for (int k = 0; k < 2; ++k) dst[n][k] = *(const LAS bf16x8*)(lds + PG8_SB(b, h) + boff + n * 2048 + k * 1024); } while (0)
; #define PG8_MMA(ai, bj, At, Bt) do { __builtin_amdgcn_s_setprio(3); _Pragma("unroll") for (int m = 0; m < 4; ++m) _Pragma("unroll") for (int n = 0; n < 2; ++n) _Pragma("unroll") for (int k = 0; k < 2; ++k) \
;         acc[ai][bj][m][n] = __builtin_amdgcn_mfma_f32_16x16x32_bf16(Bt[n][k], At[m][k], acc[ai][bj][m][n], 0, 0, 0); __builtin_amdgcn_s_setprio(0); } while (0)
; #define PG8_WAIT_V(n) asm volatile("s_waitcnt vmcnt(" #n ")" ::: "memory")
; #define PG8_WAIT_L(n) asm volatile("s_waitcnt lgkmcnt(" #n ")" ::: "memory")
; #define PG8_BAR __builtin_amdgcn_s_barrier()
; #define PG8_SCHED __builtin_amdgcn_sched_barrier(0)
; __device__ __forceinline__ float row_rs4(const float* ssq, int row, int fq) {
;     const f32x4 a = *(const f32x4*)(ssq + (size_t)row * 16 + fq * 4);
;     float s = (a[0] + a[1]) + (a[2] + a[3]);
;     s += __shfl_xor(s, 16); s += __shfl_xor(s, 32);
;     ...
;             PG8_LDB(B0, 1, 0); PG8_LDB(B1, 1, 1); PG8_SCHED; PG8_LDA(At, 1, 0); PG8_STAGE(PG8_SA(0, 1), a2 + hstepA, voffA);
;             PG8_WAIT_V(8); PG8_WAIT_L(0); PG8_BAR; PG8_MMA(0, 0, At, B0); PG8_MMA(0, 1, At, B1); PG8_BAR; PG8_SCHED;
;             PG8_LDA(At, 1, 1); PG8_STAGE(PG8_SB(1, 0), b3, voffB); PG8_STAGE(PG8_SB(1, 1), b3 + hstepB, voffB); PG8_STAGE(PG8_SA(1, 0), a3, voffA);
;             PG8_WAIT_V(8); PG8_WAIT_L(0); PG8_BAR; PG8_MMA(1, 0, At, B0); PG8_MMA(1, 1, At, B1); PG8_BAR; PG8_SCHED;
	s_add_i32 s75, s75, s17
	v_lshl_add_u64 v[144:145], v[144:145], 0, s[46:47]
	s_mov_b32 m0, s75
	ds_read_b128 v[212:215], v164 offset:49152
	ds_read_b128 v[216:219], v164 offset:50176
	ds_read_b128 v[220:223], v164 offset:51200
	ds_read_b128 v[224:227], v164 offset:52224
	ds_read_b128 v[228:231], v164 offset:53248
	ds_read_b128 v[232:235], v164 offset:54272
	ds_read_b128 v[236:239], v164 offset:55296
	ds_read_b128 v[240:243], v164 offset:56320
	global_load_lds_dwordx4 v[144:145], off
	s_add_i32 m0, s75, 0x2000
	s_add_u32 s78, s78, 0x10080
	v_lshl_add_u64 v[144:145], v[244:245], 0, s[46:47]
	s_addc_u32 s79, s79, 0
	s_add_i32 s75, s86, s17
	global_load_lds_dwordx4 v[144:145], off
	v_lshl_add_u64 v[144:145], s[78:79], 0, v[134:135]
	s_mov_b32 m0, s75
	s_nop 0
	global_load_lds_dwordx4 v[144:145], off
	v_lshl_add_u64 v[144:145], s[78:79], 0, v[130:131]
	s_add_i32 m0, s75, 0x2000
	s_nop 0
	global_load_lds_dwordx4 v[144:145], off
	v_lshl_add_u64 v[144:145], v[246:247], 0, s[46:47]
	s_mov_b32 m0, s82
	s_nop 0
	global_load_lds_dwordx4 v[144:145], off
	v_lshl_add_u64 v[144:145], v[248:249], 0, s[46:47]
	s_mov_b32 m0, s83
	s_nop 0
	global_load_lds_dwordx4 v[144:145], off
	s_waitcnt vmcnt(8)
	s_waitcnt lgkmcnt(0)
	s_barrier
	s_setprio 3
	s_waitcnt lgkmcnt(0)
	v_mfma_f32_16x16x32_bf16 v[62:65], v[166:169], v[212:215], v[62:65]
	v_mfma_f32_16x16x32_bf16 v[58:61], v[174:177], v[212:215], v[58:61]
	v_mfma_f32_16x16x32_bf16 v[46:49], v[166:169], v[220:223], v[46:49]
	v_mfma_f32_16x16x32_bf16 v[42:45], v[174:177], v[220:223], v[42:45]
	v_mfma_f32_16x16x32_bf16 v[30:33], v[166:169], v[228:231], v[30:33]
	v_mfma_f32_16x16x32_bf16 v[26:29], v[174:177], v[228:231], v[26:29]
	v_mfma_f32_16x16x32_bf16 v[14:17], v[166:169], v[236:239], v[14:17]
	v_mfma_f32_16x16x32_bf16 v[10:13], v[174:177], v[236:239], v[10:13]
	v_mfma_f32_16x16x32_bf16 v[62:65], v[170:173], v[216:219], v[62:65]
	v_mfma_f32_16x16x32_bf16 v[58:61], v[192:195], v[216:219], v[58:61]
	v_mfma_f32_16x16x32_bf16 v[46:49], v[170:173], v[224:227], v[46:49]
	v_mfma_f32_16x16x32_bf16 v[42:45], v[192:195], v[224:227], v[42:45]
	v_mfma_f32_16x16x32_bf16 v[30:33], v[170:173], v[232:235], v[30:33]
	v_mfma_f32_16x16x32_bf16 v[26:29], v[192:195], v[232:235], v[26:29]
	v_mfma_f32_16x16x32_bf16 v[14:17], v[170:173], v[240:243], v[14:17]
	v_mfma_f32_16x16x32_bf16 v[10:13], v[192:195], v[240:243], v[10:13]
	s_setprio 0
	s_setprio 3
	v_mfma_f32_16x16x32_bf16 v[54:57], v[196:199], v[212:215], v[54:57]
	v_mfma_f32_16x16x32_bf16 v[50:53], v[204:207], v[212:215], v[50:53]
	v_mfma_f32_16x16x32_bf16 v[38:41], v[196:199], v[220:223], v[38:41]
	v_mfma_f32_16x16x32_bf16 v[34:37], v[204:207], v[220:223], v[34:37]
	v_mfma_f32_16x16x32_bf16 v[22:25], v[196:199], v[228:231], v[22:25]
	v_mfma_f32_16x16x32_bf16 v[18:21], v[204:207], v[228:231], v[18:21]
	v_mfma_f32_16x16x32_bf16 v[6:9], v[196:199], v[236:239], v[6:9]
	v_mfma_f32_16x16x32_bf16 v[2:5], v[204:207], v[236:239], v[2:5]
	v_mfma_f32_16x16x32_bf16 v[54:57], v[200:203], v[216:219], v[54:57]
	v_mfma_f32_16x16x32_bf16 v[50:53], v[208:211], v[216:219], v[50:53]
	v_mfma_f32_16x16x32_bf16 v[38:41], v[200:203], v[224:227], v[38:41]
	v_mfma_f32_16x16x32_bf16 v[34:37], v[208:211], v[224:227], v[34:37]
	v_mfma_f32_16x16x32_bf16 v[22:25], v[200:203], v[232:235], v[22:25]
	v_mfma_f32_16x16x32_bf16 v[18:21], v[208:211], v[232:235], v[18:21]
	v_mfma_f32_16x16x32_bf16 v[6:9], v[200:203], v[240:243], v[6:9]
	v_mfma_f32_16x16x32_bf16 v[2:5], v[208:211], v[240:243], v[2:5]
	s_setprio 0
	s_barrier
	s_add_i32 s61, s61, 2
	s_add_u32 s42, s42, 0x100
	s_addc_u32 s60, s60, 0
	s_add_u32 s76, s76, 0x100
	s_addc_u32 s77, s77, 0
	s_cmp_gt_u32 s61, 13
	s_cbranch_scc0 .LBB0_58
	v_lshl_add_u32 v232, s74, 8, v1
	v_ashrrev_i32_e32 v233, 31, v232
	v_lshlrev_b64 v[234:235], 6, v[232:233]
	v_lshl_add_u64 v[234:235], v[138:139], 0, v[234:235]
	global_load_dwordx4 v[192:195], v[234:235], off
	global_load_dwordx4 v[196:199], v[234:235], off offset:1024
	global_load_dwordx4 v[200:203], v[234:235], off offset:2048
	global_load_dwordx4 v[204:207], v[234:235], off offset:3072
	v_add_u32_e32 v232, 0x80, v232
	v_ashrrev_i32_e32 v233, 31, v232
	v_lshlrev_b64 v[234:235], 6, v[232:233]
	v_lshl_add_u64 v[234:235], v[138:139], 0, v[234:235]
	global_load_dwordx4 v[208:211], v[234:235], off
	global_load_dwordx4 v[212:215], v[234:235], off offset:1024
	global_load_dwordx4 v[216:219], v[234:235], off offset:2048
	global_load_dwordx4 v[220:223], v[234:235], off offset:3072
	v_xor_b32_e32 v176, 16, v182
	v_xor_b32_e32 v177, 32, v182
	v_lshlrev_b32_e32 v176, 2, v176
	v_lshlrev_b32_e32 v177, 2, v177
	s_and_b64 vcc, exec, s[6:7]
	s_cbranch_vccz .LBB0_61
	s_barrier
; __device__ __forceinline__ unsigned cvt_pk_bf16(float lo, float hi) { unsigned r; asm volatile("v_cvt_pk_bf16_f32 %0, %1, %2" : "=v"(r) : "v"(lo), "v"(hi)); return r; }
; __device__ __forceinline__ float row_rs4(const float* ssq, int row, int fq) {
;     const f32x4 a = *(const f32x4*)(ssq + (size_t)row * 16 + fq * 4);
;     float s = (a[0] + a[1]) + (a[2] + a[3]);
;     s += __shfl_xor(s, 16); s += __shfl_xor(s, 32);
;     return __builtin_amdgcn_rsqf(s * (1.0f / 1024.0f) + 1e-6f);
; }
;     __device__ __forceinline__ void operator()(const f32x4 (&acc)[2][2][4][2], const Unit& u, int wr, int wc, int fr, int fq) const {
;     ...
; #pragma unroll
;         for (int ai = 0; ai < 2; ++ai)
; #pragma unroll
;             for (int m = 0; m < 4; ++m) {
;                 const int row = row0 + ai * HALF + m * 16; const float rs = row_rs4(ssq, row, fq);
; #pragma unroll
;                 for (int bj = 0; bj < 2; ++bj) {
;                     const f32x4 v0 = acc[ai][bj][m][0] * rs, v1 = acc[ai][bj][m][1] * rs;
;                     u32x4 w; w.x = cvt_pk_bf16(v0[0], v0[1]); w.y = cvt_pk_bf16(v0[2], v0[3]); w.z = cvt_pk_bf16(v1[0], v1[1]); w.w = cvt_pk_bf16(v1[2], v1[3]);
;                     *(u32x4*)(proj + (size_t)row * pitch + col0 + bj * 32) = w;
;                 }
;             }
.LBB0_61:
	s_waitcnt vmcnt(0)
	v_add_f32_e32 v192, v192, v193
	v_add_f32_e32 v194, v194, v195
	v_add_f32_e32 v196, v196, v197
	v_add_f32_e32 v198, v198, v199
	v_add_f32_e32 v200, v200, v201
	v_add_f32_e32 v202, v202, v203
	v_add_f32_e32 v204, v204, v205
	v_add_f32_e32 v206, v206, v207
	v_add_f32_e32 v208, v208, v209
	v_add_f32_e32 v210, v210, v211
	v_add_f32_e32 v212, v212, v213
	v_add_f32_e32 v214, v214, v215
	v_add_f32_e32 v216, v216, v217
	v_add_f32_e32 v218, v218, v219
	v_add_f32_e32 v220, v220, v221
	v_add_f32_e32 v222, v222, v223
	v_add_f32_e32 v192, v192, v194
	v_add_f32_e32 v196, v196, v198
	v_add_f32_e32 v200, v200, v202
	v_add_f32_e32 v204, v204, v206
	v_add_f32_e32 v208, v208, v210
	v_add_f32_e32 v212, v212, v214
	v_add_f32_e32 v216, v216, v218
	v_add_f32_e32 v220, v220, v222
	ds_bpermute_b32 v224, v176, v192
	ds_bpermute_b32 v225, v176, v196
	ds_bpermute_b32 v226, v176, v200
	ds_bpermute_b32 v227, v176, v204
	ds_bpermute_b32 v228, v176, v208
	ds_bpermute_b32 v229, v176, v212
	ds_bpermute_b32 v230, v176, v216
	ds_bpermute_b32 v231, v176, v220
	s_waitcnt lgkmcnt(7)
	v_add_f32_e32 v192, v192, v224
	s_waitcnt lgkmcnt(6)
	v_add_f32_e32 v196, v196, v225
	s_waitcnt lgkmcnt(5)
	v_add_f32_e32 v200, v200, v226
	s_waitcnt lgkmcnt(4)
	v_add_f32_e32 v204, v204, v227
	s_waitcnt lgkmcnt(3)
	v_add_f32_e32 v208, v208, v228
	s_waitcnt lgkmcnt(2)
	v_add_f32_e32 v212, v212, v229
	s_waitcnt lgkmcnt(1)
	v_add_f32_e32 v216, v216, v230
	s_waitcnt lgkmcnt(0)
	v_add_f32_e32 v220, v220, v231
	ds_bpermute_b32 v224, v177, v192
	ds_bpermute_b32 v225, v177, v196
	ds_bpermute_b32 v226, v177, v200
	ds_bpermute_b32 v227, v177, v204
	ds_bpermute_b32 v228, v177, v208
	ds_bpermute_b32 v229, v177, v212
	ds_bpermute_b32 v230, v177, v216
	ds_bpermute_b32 v231, v177, v220
	s_waitcnt lgkmcnt(7)
	v_add_f32_e32 v192, v192, v224
	s_waitcnt lgkmcnt(6)
	v_add_f32_e32 v196, v196, v225
	s_waitcnt lgkmcnt(5)
	v_add_f32_e32 v200, v200, v226
	s_waitcnt lgkmcnt(4)
	v_add_f32_e32 v204, v204, v227
	s_waitcnt lgkmcnt(3)
	v_add_f32_e32 v208, v208, v228
	s_waitcnt lgkmcnt(2)
	v_add_f32_e32 v212, v212, v229
	s_waitcnt lgkmcnt(1)
	v_add_f32_e32 v216, v216, v230
	s_waitcnt lgkmcnt(0)
	v_add_f32_e32 v220, v220, v231
	v_fmamk_f32 v192, v192, 0x3a800000, v179
	v_fmamk_f32 v196, v196, 0x3a800000, v179
	v_fmamk_f32 v200, v200, 0x3a800000, v179
	v_fmamk_f32 v204, v204, 0x3a800000, v179
	v_fmamk_f32 v208, v208, 0x3a800000, v179
	v_fmamk_f32 v212, v212, 0x3a800000, v179
	v_fmamk_f32 v216, v216, 0x3a800000, v179
	v_fmamk_f32 v220, v220, 0x3a800000, v179
	v_rsq_f32_e32 v192, v192
	v_rsq_f32_e32 v196, v196
	v_rsq_f32_e32 v200, v200
	v_rsq_f32_e32 v204, v204
	v_rsq_f32_e32 v208, v208
	v_rsq_f32_e32 v212, v212
	v_rsq_f32_e32 v216, v216
	v_rsq_f32_e32 v220, v220
	s_nop 0
	v_and_b32_e32 v165, 64, v182
	v_xor_b32_e32 v145, 16, v182
	v_add_u32_e32 v166, 64, v165
	v_cmp_lt_i32_e32 vcc, v145, v166
	v_lshl_add_u32 v144, s74, 8, v1
	v_lshl_or_b32 v172, s19, 8, v147
	v_cndmask_b32_e32 v145, v182, v145, vcc
	v_lshlrev_b32_e32 v165, 2, v145
	v_xor_b32_e32 v145, 32, v182
	v_cmp_lt_i32_e32 vcc, v145, v166
	v_ashrrev_i32_e32 v173, 31, v172
	s_mov_b64 s[74:75], -1
	v_cndmask_b32_e32 v145, v182, v145, vcc
	v_lshlrev_b32_e32 v166, 2, v145
	v_ashrrev_i32_e32 v145, 31, v144
	v_lshlrev_b64 v[168:169], 6, v[144:145]
	v_lshl_add_u64 v[168:169], v[138:139], 0, v[168:169]
	s_andn2_b64 vcc, exec, s[2:3]
	s_mov_b32 s42, 0x11808
	v_readlane_b32 s87, v254, 19
	s_nop 0
	v_mov_b32_e32 v168, v192
	s_nop 0
	v_pk_mul_f32 v[126:127], v[126:127], v[168:169] op_sel_hi:[1,0]
	v_pk_mul_f32 v[122:123], v[122:123], v[168:169] op_sel_hi:[1,0]
	v_pk_mul_f32 v[128:129], v[128:129], v[168:169] op_sel_hi:[1,0]
	v_pk_mul_f32 v[170:171], v[124:125], v[168:169] op_sel_hi:[1,0]
	v_cvt_pk_bf16_f32 v124, v126, v127
	v_cvt_pk_bf16_f32 v125, v128, v129
	v_cvt_pk_bf16_f32 v126, v122, v123
	v_lshlrev_b64 v[122:123], 11, v[144:145]
	v_lshl_add_u64 v[128:129], s[22:23], 0, v[122:123]
	v_lshlrev_b64 v[122:123], 1, v[172:173]
	v_lshl_add_u64 v[128:129], v[128:129], 0, v[122:123]
	v_pk_mul_f32 v[118:119], v[118:119], v[168:169] op_sel_hi:[1,0]
	v_cvt_pk_bf16_f32 v127, v170, v171
	global_store_dwordx4 v[128:129], v[124:127], off
	v_pk_mul_f32 v[120:121], v[120:121], v[168:169] op_sel_hi:[1,0]
	s_nop 0
	v_pk_mul_f32 v[124:125], v[116:117], v[168:169] op_sel_hi:[1,0]
	v_pk_mul_f32 v[116:117], v[114:115], v[168:169] op_sel_hi:[1,0]
	v_cvt_pk_bf16_f32 v114, v118, v119
	v_or_b32_e32 v118, 16, v144
	v_cvt_pk_bf16_f32 v115, v120, v121
	v_ashrrev_i32_e32 v119, 31, v118
	v_cvt_pk_bf16_f32 v116, v116, v117
	v_cvt_pk_bf16_f32 v117, v124, v125
	global_store_dwordx4 v[128:129], v[114:117], off offset:64
	s_nop 1
	v_lshlrev_b64 v[114:115], 6, v[118:119]
	v_lshl_add_u64 v[114:115], v[138:139], 0, v[114:115]
	s_nop 0
	v_mov_b32_e32 v114, v196
	s_nop 0
	v_pk_mul_f32 v[110:111], v[110:111], v[114:115] op_sel_hi:[1,0]
	v_pk_mul_f32 v[116:117], v[108:109], v[114:115] op_sel_hi:[1,0]
	v_pk_mul_f32 v[108:109], v[106:107], v[114:115] op_sel_hi:[1,0]
	v_cvt_pk_bf16_f32 v106, v110, v111
	v_lshlrev_b64 v[110:111], 11, v[118:119]
	v_lshl_add_u64 v[110:111], s[22:23], 0, v[110:111]
	v_pk_mul_f32 v[112:113], v[112:113], v[114:115] op_sel_hi:[1,0]
	v_lshl_add_u64 v[110:111], v[110:111], 0, v[122:123]
	v_cvt_pk_bf16_f32 v107, v112, v113
	v_pk_mul_f32 v[102:103], v[102:103], v[114:115] op_sel_hi:[1,0]
	v_cvt_pk_bf16_f32 v108, v108, v109
	v_cvt_pk_bf16_f32 v109, v116, v117
	global_store_dwordx4 v[110:111], v[106:109], off
	v_pk_mul_f32 v[104:105], v[104:105], v[114:115] op_sel_hi:[1,0]
	s_nop 0
	v_pk_mul_f32 v[106:107], v[100:101], v[114:115] op_sel_hi:[1,0]
; __device__ __forceinline__ unsigned cvt_pk_bf16(float lo, float hi) { unsigned r; asm volatile("v_cvt_pk_bf16_f32 %0, %1, %2" : "=v"(r) : "v"(lo), "v"(hi)); return r; }
;     __device__ __forceinline__ void operator()(const f32x4 (&acc)[2][2][4][2], const Unit& u, int wr, int wc, int fr, int fq) const {
;     ...
; #pragma unroll
;         for (int ai = 0; ai < 2; ++ai)
; #pragma unroll
;             for (int m = 0; m < 4; ++m) {
;                 const int row = row0 + ai * HALF + m * 16; const float rs = row_rs4(ssq, row, fq);
; #pragma unroll
;                 for (int bj = 0; bj < 2; ++bj) {
;                     const f32x4 v0 = acc[ai][bj][m][0] * rs, v1 = acc[ai][bj][m][1] * rs;
;                     u32x4 w; w.x = cvt_pk_bf16(v0[0], v0[1]); w.y = cvt_pk_bf16(v0[2], v0[3]); w.z = cvt_pk_bf16(v1[0], v1[1]); w.w = cvt_pk_bf16(v1[2], v1[3]);
;                     *(u32x4*)(proj + (size_t)row * pitch + col0 + bj * 32) = w;
;                 }
;             }
	v_pk_mul_f32 v[100:101], v[98:99], v[114:115] op_sel_hi:[1,0]
	v_cvt_pk_bf16_f32 v98, v102, v103
	v_or_b32_e32 v102, 32, v144
	v_cvt_pk_bf16_f32 v99, v104, v105
	v_ashrrev_i32_e32 v103, 31, v102
	v_cvt_pk_bf16_f32 v100, v100, v101
	v_cvt_pk_bf16_f32 v101, v106, v107
	global_store_dwordx4 v[110:111], v[98:101], off offset:64
	s_nop 1
	v_lshlrev_b64 v[98:99], 6, v[102:103]
	v_lshl_add_u64 v[98:99], v[138:139], 0, v[98:99]
	s_nop 0
	v_mov_b32_e32 v98, v200
	s_nop 0
	v_pk_mul_f32 v[94:95], v[94:95], v[98:99] op_sel_hi:[1,0]
	v_pk_mul_f32 v[100:101], v[92:93], v[98:99] op_sel_hi:[1,0]
	v_pk_mul_f32 v[92:93], v[90:91], v[98:99] op_sel_hi:[1,0]
	v_cvt_pk_bf16_f32 v90, v94, v95
	v_lshlrev_b64 v[94:95], 11, v[102:103]
	v_lshl_add_u64 v[94:95], s[22:23], 0, v[94:95]
	v_pk_mul_f32 v[96:97], v[96:97], v[98:99] op_sel_hi:[1,0]
	v_lshl_add_u64 v[94:95], v[94:95], 0, v[122:123]
	v_cvt_pk_bf16_f32 v91, v96, v97
	v_pk_mul_f32 v[86:87], v[86:87], v[98:99] op_sel_hi:[1,0]
	v_cvt_pk_bf16_f32 v92, v92, v93
	v_cvt_pk_bf16_f32 v93, v100, v101
	global_store_dwordx4 v[94:95], v[90:93], off
	v_pk_mul_f32 v[88:89], v[88:89], v[98:99] op_sel_hi:[1,0]
	s_nop 0
	v_pk_mul_f32 v[90:91], v[84:85], v[98:99] op_sel_hi:[1,0]
	v_pk_mul_f32 v[84:85], v[82:83], v[98:99] op_sel_hi:[1,0]
	v_cvt_pk_bf16_f32 v82, v86, v87
	v_or_b32_e32 v86, 48, v144
	v_cvt_pk_bf16_f32 v83, v88, v89
	v_ashrrev_i32_e32 v87, 31, v86
	v_cvt_pk_bf16_f32 v84, v84, v85
	v_cvt_pk_bf16_f32 v85, v90, v91
	global_store_dwordx4 v[94:95], v[82:85], off offset:64
	s_nop 1
	v_lshlrev_b64 v[82:83], 6, v[86:87]
	v_lshl_add_u64 v[82:83], v[138:139], 0, v[82:83]
	s_nop 0
	v_mov_b32_e32 v82, v204
	s_nop 0
	v_pk_mul_f32 v[78:79], v[78:79], v[82:83] op_sel_hi:[1,0]
	v_pk_mul_f32 v[84:85], v[76:77], v[82:83] op_sel_hi:[1,0]
	v_pk_mul_f32 v[76:77], v[74:75], v[82:83] op_sel_hi:[1,0]
	v_cvt_pk_bf16_f32 v74, v78, v79
	v_lshlrev_b64 v[78:79], 11, v[86:87]
	v_lshl_add_u64 v[78:79], s[22:23], 0, v[78:79]
	v_pk_mul_f32 v[80:81], v[80:81], v[82:83] op_sel_hi:[1,0]
	v_lshl_add_u64 v[78:79], v[78:79], 0, v[122:123]
	v_cvt_pk_bf16_f32 v75, v80, v81
	v_pk_mul_f32 v[70:71], v[70:71], v[82:83] op_sel_hi:[1,0]
	v_cvt_pk_bf16_f32 v76, v76, v77
	v_cvt_pk_bf16_f32 v77, v84, v85
	global_store_dwordx4 v[78:79], v[74:77], off
	v_pk_mul_f32 v[72:73], v[72:73], v[82:83] op_sel_hi:[1,0]
	s_nop 0
	v_pk_mul_f32 v[74:75], v[68:69], v[82:83] op_sel_hi:[1,0]
	v_pk_mul_f32 v[68:69], v[66:67], v[82:83] op_sel_hi:[1,0]
	v_cvt_pk_bf16_f32 v66, v70, v71
	v_add_u32_e32 v70, 0x80, v144
	v_cvt_pk_bf16_f32 v67, v72, v73
	v_ashrrev_i32_e32 v71, 31, v70
	v_cvt_pk_bf16_f32 v68, v68, v69
	v_cvt_pk_bf16_f32 v69, v74, v75
	global_store_dwordx4 v[78:79], v[66:69], off offset:64
	s_nop 1
	v_lshlrev_b64 v[66:67], 6, v[70:71]
	v_lshl_add_u64 v[66:67], v[138:139], 0, v[66:67]
	s_nop 0
	v_mov_b32_e32 v66, v208
	s_nop 0
	v_pk_mul_f32 v[62:63], v[62:63], v[66:67] op_sel_hi:[1,0]
	v_pk_mul_f32 v[68:69], v[60:61], v[66:67] op_sel_hi:[1,0]
	v_pk_mul_f32 v[60:61], v[58:59], v[66:67] op_sel_hi:[1,0]
	v_cvt_pk_bf16_f32 v58, v62, v63
	v_lshlrev_b64 v[62:63], 11, v[70:71]
	v_lshl_add_u64 v[62:63], s[22:23], 0, v[62:63]
	v_pk_mul_f32 v[64:65], v[64:65], v[66:67] op_sel_hi:[1,0]
	v_lshl_add_u64 v[62:63], v[62:63], 0, v[122:123]
	v_cvt_pk_bf16_f32 v59, v64, v65
	v_pk_mul_f32 v[54:55], v[54:55], v[66:67] op_sel_hi:[1,0]
	v_cvt_pk_bf16_f32 v60, v60, v61
	v_cvt_pk_bf16_f32 v61, v68, v69
	global_store_dwordx4 v[62:63], v[58:61], off
	v_pk_mul_f32 v[56:57], v[56:57], v[66:67] op_sel_hi:[1,0]
	s_nop 0
	v_pk_mul_f32 v[58:59], v[52:53], v[66:67] op_sel_hi:[1,0]
	v_pk_mul_f32 v[52:53], v[50:51], v[66:67] op_sel_hi:[1,0]
	v_cvt_pk_bf16_f32 v50, v54, v55
	v_add_u32_e32 v54, 0x90, v144
	v_cvt_pk_bf16_f32 v51, v56, v57
; __device__ __forceinline__ unsigned cvt_pk_bf16(float lo, float hi) { unsigned r; asm volatile("v_cvt_pk_bf16_f32 %0, %1, %2" : "=v"(r) : "v"(lo), "v"(hi)); return r; }
;     __device__ __forceinline__ void operator()(const f32x4 (&acc)[2][2][4][2], const Unit& u, int wr, int wc, int fr, int fq) const {
;     ...
; #pragma unroll
;         for (int ai = 0; ai < 2; ++ai)
; #pragma unroll
;             for (int m = 0; m < 4; ++m) {
;                 const int row = row0 + ai * HALF + m * 16; const float rs = row_rs4(ssq, row, fq);
; #pragma unroll
;                 for (int bj = 0; bj < 2; ++bj) {
;                     const f32x4 v0 = acc[ai][bj][m][0] * rs, v1 = acc[ai][bj][m][1] * rs;
;                     u32x4 w; w.x = cvt_pk_bf16(v0[0], v0[1]); w.y = cvt_pk_bf16(v0[2], v0[3]); w.z = cvt_pk_bf16(v1[0], v1[1]); w.w = cvt_pk_bf16(v1[2], v1[3]);
;                     *(u32x4*)(proj + (size_t)row * pitch + col0 + bj * 32) = w;
;                 }
;             }
	v_ashrrev_i32_e32 v55, 31, v54
	v_cvt_pk_bf16_f32 v52, v52, v53
	v_cvt_pk_bf16_f32 v53, v58, v59
	global_store_dwordx4 v[62:63], v[50:53], off offset:64
	s_nop 1
	v_lshlrev_b64 v[50:51], 6, v[54:55]
	v_lshl_add_u64 v[50:51], v[138:139], 0, v[50:51]
	s_nop 0
	v_mov_b32_e32 v50, v212
	s_nop 0
	v_pk_mul_f32 v[46:47], v[46:47], v[50:51] op_sel_hi:[1,0]
	v_pk_mul_f32 v[52:53], v[44:45], v[50:51] op_sel_hi:[1,0]
	v_pk_mul_f32 v[44:45], v[42:43], v[50:51] op_sel_hi:[1,0]
	v_cvt_pk_bf16_f32 v42, v46, v47
	v_lshlrev_b64 v[46:47], 11, v[54:55]
	v_lshl_add_u64 v[46:47], s[22:23], 0, v[46:47]
	v_pk_mul_f32 v[48:49], v[48:49], v[50:51] op_sel_hi:[1,0]
	v_lshl_add_u64 v[46:47], v[46:47], 0, v[122:123]
	v_cvt_pk_bf16_f32 v43, v48, v49
	v_pk_mul_f32 v[38:39], v[38:39], v[50:51] op_sel_hi:[1,0]
	v_cvt_pk_bf16_f32 v44, v44, v45
	v_cvt_pk_bf16_f32 v45, v52, v53
	global_store_dwordx4 v[46:47], v[42:45], off
	v_pk_mul_f32 v[40:41], v[40:41], v[50:51] op_sel_hi:[1,0]
	s_nop 0
	v_pk_mul_f32 v[42:43], v[36:37], v[50:51] op_sel_hi:[1,0]
	v_pk_mul_f32 v[36:37], v[34:35], v[50:51] op_sel_hi:[1,0]
	v_cvt_pk_bf16_f32 v34, v38, v39
	v_add_u32_e32 v38, 0xa0, v144
	v_cvt_pk_bf16_f32 v35, v40, v41
	v_ashrrev_i32_e32 v39, 31, v38
	v_cvt_pk_bf16_f32 v36, v36, v37
	v_cvt_pk_bf16_f32 v37, v42, v43
	global_store_dwordx4 v[46:47], v[34:37], off offset:64
	s_nop 1
	v_lshlrev_b64 v[34:35], 6, v[38:39]
	v_lshl_add_u64 v[34:35], v[138:139], 0, v[34:35]
	s_nop 0
	v_mov_b32_e32 v34, v216
	s_nop 0
	v_pk_mul_f32 v[30:31], v[30:31], v[34:35] op_sel_hi:[1,0]
	v_pk_mul_f32 v[36:37], v[28:29], v[34:35] op_sel_hi:[1,0]
	v_pk_mul_f32 v[28:29], v[26:27], v[34:35] op_sel_hi:[1,0]
	v_cvt_pk_bf16_f32 v26, v30, v31
	v_lshlrev_b64 v[30:31], 11, v[38:39]
	v_lshl_add_u64 v[30:31], s[22:23], 0, v[30:31]
	v_pk_mul_f32 v[32:33], v[32:33], v[34:35] op_sel_hi:[1,0]
	v_lshl_add_u64 v[30:31], v[30:31], 0, v[122:123]
	v_cvt_pk_bf16_f32 v27, v32, v33
	v_pk_mul_f32 v[22:23], v[22:23], v[34:35] op_sel_hi:[1,0]
	v_cvt_pk_bf16_f32 v28, v28, v29
	v_cvt_pk_bf16_f32 v29, v36, v37
	global_store_dwordx4 v[30:31], v[26:29], off
	v_pk_mul_f32 v[24:25], v[24:25], v[34:35] op_sel_hi:[1,0]
	s_nop 0
	v_pk_mul_f32 v[26:27], v[20:21], v[34:35] op_sel_hi:[1,0]
	v_pk_mul_f32 v[20:21], v[18:19], v[34:35] op_sel_hi:[1,0]
	v_cvt_pk_bf16_f32 v18, v22, v23
	v_add_u32_e32 v22, 0xb0, v144
	v_cvt_pk_bf16_f32 v19, v24, v25
	v_ashrrev_i32_e32 v23, 31, v22
	v_cvt_pk_bf16_f32 v20, v20, v21
	v_cvt_pk_bf16_f32 v21, v26, v27
	global_store_dwordx4 v[30:31], v[18:21], off offset:64
	s_nop 1
	v_lshlrev_b64 v[18:19], 6, v[22:23]
	v_lshl_add_u64 v[18:19], v[138:139], 0, v[18:19]
	s_nop 0
	v_mov_b32_e32 v18, v220
	s_nop 0
	v_pk_mul_f32 v[14:15], v[14:15], v[18:19] op_sel_hi:[1,0]
	v_pk_mul_f32 v[20:21], v[12:13], v[18:19] op_sel_hi:[1,0]
	v_pk_mul_f32 v[12:13], v[10:11], v[18:19] op_sel_hi:[1,0]
	v_cvt_pk_bf16_f32 v10, v14, v15
	v_lshlrev_b64 v[14:15], 11, v[22:23]
	v_lshl_add_u64 v[14:15], s[22:23], 0, v[14:15]
	v_pk_mul_f32 v[16:17], v[16:17], v[18:19] op_sel_hi:[1,0]
	v_lshl_add_u64 v[14:15], v[14:15], 0, v[122:123]
	v_cvt_pk_bf16_f32 v11, v16, v17
	v_cvt_pk_bf16_f32 v12, v12, v13
	v_cvt_pk_bf16_f32 v13, v20, v21
	global_store_dwordx4 v[14:15], v[10:13], off
	v_pk_mul_f32 v[8:9], v[8:9], v[18:19] op_sel_hi:[1,0]
	v_pk_mul_f32 v[6:7], v[6:7], v[18:19] op_sel_hi:[1,0]
	v_pk_mul_f32 v[10:11], v[4:5], v[18:19] op_sel_hi:[1,0]
	v_pk_mul_f32 v[4:5], v[2:3], v[18:19] op_sel_hi:[1,0]
	v_cvt_pk_bf16_f32 v2, v6, v7
	v_cvt_pk_bf16_f32 v3, v8, v9
	s_nop 0
	v_cvt_pk_bf16_f32 v4, v4, v5
	v_cvt_pk_bf16_f32 v5, v10, v11
	global_store_dwordx4 v[14:15], v[2:5], off offset:64
	s_cbranch_vccnz .LBB0_54
	s_andn2_b64 vcc, exec, s[4:5]
	s_cbranch_vccnz .LBB0_53
	s_barrier
	s_branch .LBB0_53

; __device__ __forceinline__ unsigned cvt_pk_bf16(float lo, float hi) { unsigned r; asm volatile("v_cvt_pk_bf16_f32 %0, %1, %2" : "=v"(r) : "v"(lo), "v"(hi)); return r; }
; __device__ __forceinline__ void attn_unit(LAS unsigned char* lds, bf16_t* proj, const float* biasG, const float* sink, int s, int qb, int kh, int hp, bf16_t* dummy = nullptr) {
;     ...
; #pragma unroll
;     for (int qt = 0; qt < 2; ++qt) {
;         float lt = lsum[qt]; lt += __shfl_xor(lt, 16); lt += __shfl_xor(lt, 32);
;         const float inv = 1.0f / lt;
;         bf16_t* orow = dummy ? dummy + (rowbase + qt * 16 + l16) * D + h * 128 + kg * 4 : proj + (rowbase + qt * 16 + l16) * PW + C_Q + h * 128 + kg * 4;
; #pragma unroll
;         for (int dt = 0; dt < 8; ++dt) { const f32x4 v = o[dt][qt] * inv; u32x2 w; w.x = cvt_pk_bf16(v[0], v[1]); w.y = cvt_pk_bf16(v[2], v[3]); *(u32x2*)(orow + dt * 16) = w; }
;     }
.LBB0_121:
	v_and_b32_e32 v2, 64, v182
	v_xor_b32_e32 v1, 16, v182
	v_add_u32_e32 v2, 64, v2
	v_cmp_lt_i32_e32 vcc, v1, v2
	v_xor_b32_e32 v4, 32, v182
	s_nop 0
	v_cndmask_b32_e32 v1, v182, v1, vcc
	v_lshlrev_b32_e32 v1, 2, v1
	ds_bpermute_b32 v3, v1, v223
	v_cmp_lt_i32_e32 vcc, v4, v2
	ds_bpermute_b32 v1, v1, v221
	s_waitcnt lgkmcnt(0)
	v_add_f32_e32 v1, v221, v1
	v_cndmask_b32_e32 v2, v182, v4, vcc
	v_lshlrev_b32_e32 v5, 2, v2
	v_add_f32_e32 v2, v223, v3
	ds_bpermute_b32 v3, v5, v2
	ds_bpermute_b32 v12, v5, v1
	s_waitcnt lgkmcnt(0)
	v_add_f32_e32 v3, v2, v3
	v_div_scale_f32 v4, s[2:3], v3, v3, 1.0
	v_rcp_f32_e32 v6, v4
	v_div_scale_f32 v7, vcc, 1.0, v3, 1.0
	v_lshlrev_b32_e32 v2, 1, v194
	v_fma_f32 v8, -v4, v6, 1.0
	v_fmac_f32_e32 v6, v8, v6
	v_mul_f32_e32 v8, v7, v6
	v_fma_f32 v9, -v4, v8, v7
	v_fmac_f32_e32 v8, v9, v6
	v_fma_f32 v4, -v4, v8, v7
	v_div_fmas_f32 v4, v4, v6, v8
	v_div_fixup_f32 v4, v4, v3, 1.0
	v_mov_b32_e32 v3, v0
	v_lshl_add_u64 v[6:7], v[166:167], 0, v[2:3]
	v_add_f32_e32 v1, v1, v12
	v_lshl_add_u64 v[2:3], v[164:165], 0, v[2:3]
	v_div_scale_f32 v10, s[2:3], v1, v1, 1.0
	v_rcp_f32_e32 v11, v10
	s_mov_b64 s[2:3], 0
	v_and_b32_e32 v252, 16, v182
	v_lshrrev_b32_e32 v252, 4, v252
	v_mul_u32_u24_e32 v252, 24, v252
	v_mov_b32_e32 v253, 0
	v_lshl_add_u64 v[252:253], v[6:7], 0, v[252:253]
	v_pk_mul_f32 v[244:245], v[96:97], v[4:5] op_sel_hi:[1,0]
	v_pk_mul_f32 v[246:247], v[98:99], v[4:5] op_sel_hi:[1,0]
	v_cvt_pk_bf16_f32 v236, v244, v245
	v_cvt_pk_bf16_f32 v237, v246, v247
	v_pk_mul_f32 v[248:249], v[104:105], v[4:5] op_sel_hi:[1,0]
	v_pk_mul_f32 v[250:251], v[106:107], v[4:5] op_sel_hi:[1,0]
	v_cvt_pk_bf16_f32 v238, v248, v249
	v_cvt_pk_bf16_f32 v239, v250, v251
	s_nop 1
	v_permlane16_swap_b32_e32 v236, v238
	v_permlane16_swap_b32_e32 v237, v239
	flat_store_dwordx4 v[252:253], v[236:239] offset:2048
	v_pk_mul_f32 v[244:245], v[108:109], v[4:5] op_sel_hi:[1,0]
	v_pk_mul_f32 v[246:247], v[110:111], v[4:5] op_sel_hi:[1,0]
	v_cvt_pk_bf16_f32 v240, v244, v245
	v_cvt_pk_bf16_f32 v241, v246, v247
	v_pk_mul_f32 v[248:249], v[112:113], v[4:5] op_sel_hi:[1,0]
	v_pk_mul_f32 v[250:251], v[114:115], v[4:5] op_sel_hi:[1,0]
	v_cvt_pk_bf16_f32 v242, v248, v249
	v_cvt_pk_bf16_f32 v243, v250, v251
	s_nop 1
	v_permlane16_swap_b32_e32 v240, v242
	v_permlane16_swap_b32_e32 v241, v243
	flat_store_dwordx4 v[252:253], v[240:243] offset:2112
	v_pk_mul_f32 v[244:245], v[116:117], v[4:5] op_sel_hi:[1,0]
	v_pk_mul_f32 v[246:247], v[118:119], v[4:5] op_sel_hi:[1,0]
	v_cvt_pk_bf16_f32 v236, v244, v245
	v_cvt_pk_bf16_f32 v237, v246, v247
	v_pk_mul_f32 v[248:249], v[120:121], v[4:5] op_sel_hi:[1,0]
	v_pk_mul_f32 v[250:251], v[122:123], v[4:5] op_sel_hi:[1,0]
	v_cvt_pk_bf16_f32 v238, v248, v249
	v_cvt_pk_bf16_f32 v239, v250, v251
	s_nop 1
	v_permlane16_swap_b32_e32 v236, v238
	v_permlane16_swap_b32_e32 v237, v239
	flat_store_dwordx4 v[252:253], v[236:239] offset:2176
	v_pk_mul_f32 v[244:245], v[124:125], v[4:5] op_sel_hi:[1,0]
	v_pk_mul_f32 v[246:247], v[126:127], v[4:5] op_sel_hi:[1,0]
	v_cvt_pk_bf16_f32 v240, v244, v245
	v_cvt_pk_bf16_f32 v241, v246, v247
	v_pk_mul_f32 v[248:249], v[128:129], v[4:5] op_sel_hi:[1,0]
	v_pk_mul_f32 v[250:251], v[130:131], v[4:5] op_sel_hi:[1,0]
	v_cvt_pk_bf16_f32 v242, v248, v249
	v_cvt_pk_bf16_f32 v243, v250, v251
	s_nop 1
	v_permlane16_swap_b32_e32 v240, v242
	v_permlane16_swap_b32_e32 v241, v243
	flat_store_dwordx4 v[252:253], v[240:243] offset:2240
	v_fma_f32 v4, -v10, v11, 1.0
	v_fmac_f32_e32 v11, v4, v11
	v_div_scale_f32 v4, vcc, 1.0, v1, 1.0
	v_mul_f32_e32 v5, v4, v11
	v_fma_f32 v6, -v10, v5, v4
	v_fmac_f32_e32 v5, v6, v11
	v_fma_f32 v4, -v10, v5, v4
	v_div_fmas_f32 v4, v4, v11, v5
	v_div_fixup_f32 v4, v4, v1, 1.0
	v_and_b32_e32 v252, 16, v182
	v_lshrrev_b32_e32 v252, 4, v252
	v_mul_u32_u24_e32 v252, 24, v252
	v_mov_b32_e32 v253, 0
	v_lshl_add_u64 v[252:253], v[2:3], 0, v[252:253]
	v_pk_mul_f32 v[244:245], v[68:69], v[4:5] op_sel_hi:[1,0]
	v_pk_mul_f32 v[246:247], v[70:71], v[4:5] op_sel_hi:[1,0]
	v_cvt_pk_bf16_f32 v236, v244, v245
	v_cvt_pk_bf16_f32 v237, v246, v247
	v_pk_mul_f32 v[248:249], v[72:73], v[4:5] op_sel_hi:[1,0]
	v_pk_mul_f32 v[250:251], v[74:75], v[4:5] op_sel_hi:[1,0]
	v_cvt_pk_bf16_f32 v238, v248, v249
	v_cvt_pk_bf16_f32 v239, v250, v251
	s_nop 1
	v_permlane16_swap_b32_e32 v236, v238
	v_permlane16_swap_b32_e32 v237, v239
	flat_store_dwordx4 v[252:253], v[236:239] offset:2048
	v_pk_mul_f32 v[244:245], v[76:77], v[4:5] op_sel_hi:[1,0]
	v_pk_mul_f32 v[246:247], v[78:79], v[4:5] op_sel_hi:[1,0]
	v_cvt_pk_bf16_f32 v240, v244, v245
	v_cvt_pk_bf16_f32 v241, v246, v247
	v_pk_mul_f32 v[248:249], v[80:81], v[4:5] op_sel_hi:[1,0]
	v_pk_mul_f32 v[250:251], v[82:83], v[4:5] op_sel_hi:[1,0]
	v_cvt_pk_bf16_f32 v242, v248, v249
	v_cvt_pk_bf16_f32 v243, v250, v251
	s_nop 1
	v_permlane16_swap_b32_e32 v240, v242
	v_permlane16_swap_b32_e32 v241, v243
	flat_store_dwordx4 v[252:253], v[240:243] offset:2112
	v_pk_mul_f32 v[244:245], v[84:85], v[4:5] op_sel_hi:[1,0]
	v_pk_mul_f32 v[246:247], v[86:87], v[4:5] op_sel_hi:[1,0]
	v_cvt_pk_bf16_f32 v236, v244, v245
	v_cvt_pk_bf16_f32 v237, v246, v247
	v_pk_mul_f32 v[248:249], v[88:89], v[4:5] op_sel_hi:[1,0]
	v_pk_mul_f32 v[250:251], v[90:91], v[4:5] op_sel_hi:[1,0]
	v_cvt_pk_bf16_f32 v238, v248, v249
	v_cvt_pk_bf16_f32 v239, v250, v251
	s_nop 1
	v_permlane16_swap_b32_e32 v236, v238
	v_permlane16_swap_b32_e32 v237, v239
	flat_store_dwordx4 v[252:253], v[236:239] offset:2176
	v_pk_mul_f32 v[244:245], v[92:93], v[4:5] op_sel_hi:[1,0]
	v_pk_mul_f32 v[246:247], v[94:95], v[4:5] op_sel_hi:[1,0]
	v_cvt_pk_bf16_f32 v240, v244, v245
	v_cvt_pk_bf16_f32 v241, v246, v247
	v_pk_mul_f32 v[248:249], v[100:101], v[4:5] op_sel_hi:[1,0]
	v_pk_mul_f32 v[250:251], v[102:103], v[4:5] op_sel_hi:[1,0]
	v_cvt_pk_bf16_f32 v242, v248, v249
	v_cvt_pk_bf16_f32 v243, v250, v251
	s_nop 1
	v_permlane16_swap_b32_e32 v240, v242
	v_permlane16_swap_b32_e32 v241, v243
	flat_store_dwordx4 v[252:253], v[240:243] offset:2240

; __device__ __forceinline__ const float* PIN(int i) { return (const float*)KARG(i); }
; __device__ __forceinline__ int TID() { int t = threadIdx.x; asm volatile("" : "+v"(t)); return t; }
; __device__ __forceinline__ void phase_attn(LAS unsigned char* lds, bf16_t* proj, int layer, int nseq, unsigned* ctr) {
;     ...
;     for (;;) {
;         __syncthreads();
;         if (TID() == 0) *slot = (int)atomicAdd(ctr, 1u);
;         __syncthreads();
;         const int idx = *slot;
;         if (idx >= total) break;
;         attn_unit(lds, proj, biasG, PIN(14) + layer * 8, idx >> 8, (idx >> 2) & 63, (idx >> 1) & 1, idx & 1);
.LBB0_123:
	v_mov_b32_e32 v1, v178
	global_load_dwordx2 v[252:253], v[148:149], off offset:112 sc0 sc1
	s_waitcnt lgkmcnt(0)
	s_barrier
	s_nop 0
	v_cmp_eq_u32_e32 vcc, 0, v1
	s_and_saveexec_b64 s[2:3], vcc
	s_cbranch_execz .LBB0_125
	v_mov_b64_e32 v[2:3], s[72:73]
	flat_atomic_add v1, v[2:3], v180 sc0
	v_readlane_b32 s4, v254, 3
	s_nop 1
	v_mov_b32_e32 v2, s4
	s_waitcnt vmcnt(0) lgkmcnt(0)
	ds_write_b32 v2, v1
.LBB0_125:
	s_or_b64 exec, exec, s[2:3]
	v_readlane_b32 s2, v254, 3
	s_waitcnt lgkmcnt(0)
	s_barrier
	v_mov_b32_e32 v1, s2
	ds_read_b32 v1, v1
	s_movk_i32 s2, 0x9ff
	s_waitcnt lgkmcnt(0)
	v_cmp_lt_i32_e32 vcc, s2, v1
	v_readfirstlane_b32 s6, v1
	s_mov_b64 s[2:3], -1
	s_cbranch_vccnz .LBB0_122
	s_bfe_u32 s7, s6, 0x10001
	s_lshl_b32 s3, s6, 1
	s_lshl_b32 s2, s7, 2
	s_and_b32 s3, s3, 2
	v_mov_b32_e32 v1, v178
	s_or_b32 s10, s2, s3
	s_movk_i32 s2, 0x202
	s_waitcnt vmcnt(0)
	v_readfirstlane_b32 s8, v253
	v_readfirstlane_b32 s9, v252
	v_cmp_gt_i32_e32 vcc, s2, v1
	s_and_saveexec_b64 s[2:3], vcc
	s_cbranch_execz .LBB0_129
	v_readlane_b32 s4, v254, 4
	v_mov_b32_e32 v3, v1
	s_nop 0
	v_lshl_add_u32 v2, v1, 2, s4
	s_mov_b64 s[4:5], 0

;     ...
; #pragma unroll
;         for (int a = 0; a < 2; ++a)
; #pragma unroll
;             for (int b = 0; b < 2; ++b)
; #pragma unroll
;                 for (int m = 0; m < 4; ++m)
; #pragma unroll
;                     for (int n = 0; n < 2; ++n) acc[a][b][m][n] = (f32x4){0.f, 0.f, 0.f, 0.f};
;         cur = nxt; cA = nA; cB = nB; ++ui;
.LBB0_284:
	s_ashr_i32 s11, s10, 31
	s_lshl_b64 s[12:13], s[10:11], 19
	s_add_u32 s12, s24, s12
	s_addc_u32 s13, s25, s13
	s_and_b64 s[16:17], s[2:3], exec
	s_cselect_b32 s11, s13, s79
	s_cselect_b32 s34, s12, s78
	s_ashr_i32 s9, s8, 31
	s_lshl_b64 s[16:17], s[8:9], 19
	s_add_u32 s16, s84, s16
	s_addc_u32 s17, s85, s17
	s_and_b64 s[60:61], s[2:3], exec
	s_cselect_b32 s9, s17, s77
	s_cselect_b32 s35, s16, s76
	s_add_u32 s42, s76, 0x100
	s_addc_u32 s60, s77, 0
	s_add_u32 s76, s78, 0x40080
	v_mov_b32_e32 v2, 0
	s_addc_u32 s77, s79, 0
	s_mov_b32 s61, -2
	v_mov_b32_e32 v3, v2
	v_mov_b32_e32 v4, v2
	v_mov_b32_e32 v5, v2
	v_mov_b32_e32 v6, v2
	v_mov_b32_e32 v7, v2
	v_mov_b32_e32 v8, v2
	v_mov_b32_e32 v9, v2
	v_mov_b32_e32 v18, v2
	v_mov_b32_e32 v19, v2
	v_mov_b32_e32 v20, v2
	v_mov_b32_e32 v21, v2
	v_mov_b32_e32 v22, v2
	v_mov_b32_e32 v23, v2
	v_mov_b32_e32 v24, v2
	v_mov_b32_e32 v25, v2
	v_mov_b32_e32 v34, v2
	v_mov_b32_e32 v35, v2
	v_mov_b32_e32 v36, v2
	v_mov_b32_e32 v37, v2
	v_mov_b32_e32 v38, v2
	v_mov_b32_e32 v39, v2
	v_mov_b32_e32 v40, v2
	v_mov_b32_e32 v41, v2
	v_mov_b32_e32 v50, v2
	v_mov_b32_e32 v51, v2
	v_mov_b32_e32 v52, v2
	v_mov_b32_e32 v53, v2
	v_mov_b32_e32 v54, v2
	v_mov_b32_e32 v55, v2
	v_mov_b32_e32 v56, v2
	v_mov_b32_e32 v57, v2
	v_mov_b32_e32 v10, v2
	v_mov_b32_e32 v11, v2
	v_mov_b32_e32 v12, v2
	v_mov_b32_e32 v13, v2
	v_mov_b32_e32 v14, v2
	v_mov_b32_e32 v15, v2
	v_mov_b32_e32 v16, v2
	v_mov_b32_e32 v17, v2
	v_mov_b32_e32 v26, v2
	v_mov_b32_e32 v27, v2
	v_mov_b32_e32 v28, v2
	v_mov_b32_e32 v29, v2
	v_mov_b32_e32 v30, v2
	v_mov_b32_e32 v31, v2
	v_mov_b32_e32 v32, v2
	v_mov_b32_e32 v33, v2
	v_mov_b32_e32 v42, v2
	v_mov_b32_e32 v43, v2
	v_mov_b32_e32 v44, v2
	v_mov_b32_e32 v45, v2
	v_mov_b32_e32 v46, v2
	v_mov_b32_e32 v47, v2
	v_mov_b32_e32 v48, v2
	v_mov_b32_e32 v49, v2
	v_mov_b32_e32 v58, v2
	v_mov_b32_e32 v59, v2
	v_mov_b32_e32 v60, v2
	v_mov_b32_e32 v61, v2
	v_mov_b32_e32 v62, v2
	v_mov_b32_e32 v63, v2
	v_mov_b32_e32 v64, v2
	v_mov_b32_e32 v65, v2
	v_mov_b32_e32 v66, v2
	v_mov_b32_e32 v67, v2
	v_mov_b32_e32 v68, v2
	v_mov_b32_e32 v69, v2
	v_mov_b32_e32 v70, v2
	v_mov_b32_e32 v71, v2
	v_mov_b32_e32 v72, v2
	v_mov_b32_e32 v73, v2
	v_mov_b32_e32 v82, v2
	v_mov_b32_e32 v83, v2
	v_mov_b32_e32 v84, v2
	v_mov_b32_e32 v85, v2
	v_mov_b32_e32 v86, v2
	v_mov_b32_e32 v87, v2
	v_mov_b32_e32 v88, v2
	v_mov_b32_e32 v89, v2
	v_mov_b32_e32 v98, v2
	v_mov_b32_e32 v99, v2
	v_mov_b32_e32 v100, v2
	v_mov_b32_e32 v101, v2
	v_mov_b32_e32 v102, v2
	v_mov_b32_e32 v103, v2
	v_mov_b32_e32 v104, v2
	v_mov_b32_e32 v105, v2
	v_mov_b32_e32 v114, v2
	v_mov_b32_e32 v115, v2
	v_mov_b32_e32 v116, v2
	v_mov_b32_e32 v117, v2
	v_mov_b32_e32 v118, v2
	v_mov_b32_e32 v119, v2
	v_mov_b32_e32 v120, v2
	v_mov_b32_e32 v121, v2
	v_mov_b32_e32 v74, v2
	v_mov_b32_e32 v75, v2
	v_mov_b32_e32 v76, v2
	v_mov_b32_e32 v77, v2
	v_mov_b32_e32 v78, v2
	v_mov_b32_e32 v79, v2
	v_mov_b32_e32 v80, v2
	v_mov_b32_e32 v81, v2
	v_mov_b32_e32 v90, v2
	v_mov_b32_e32 v91, v2
	v_mov_b32_e32 v92, v2
	v_mov_b32_e32 v93, v2
	v_mov_b32_e32 v94, v2
	v_mov_b32_e32 v95, v2
	v_mov_b32_e32 v96, v2
	v_mov_b32_e32 v97, v2
	v_mov_b32_e32 v106, v2
	v_mov_b32_e32 v107, v2
	v_mov_b32_e32 v108, v2
	v_mov_b32_e32 v109, v2
	v_mov_b32_e32 v110, v2
	v_mov_b32_e32 v111, v2
	v_mov_b32_e32 v112, v2
	v_mov_b32_e32 v113, v2
	v_mov_b32_e32 v122, v2
	v_mov_b32_e32 v123, v2
	v_mov_b32_e32 v124, v2
	v_mov_b32_e32 v125, v2
	v_mov_b32_e32 v126, v2
	v_mov_b32_e32 v127, v2
	v_mov_b32_e32 v128, v2
	v_mov_b32_e32 v129, v2
	s_waitcnt vmcnt(0)

;     ...
; #pragma unroll
;         for (int a = 0; a < 2; ++a)
; #pragma unroll
;             for (int b = 0; b < 2; ++b)
; #pragma unroll
;                 for (int m = 0; m < 4; ++m)
; #pragma unroll
;                     for (int n = 0; n < 2; ++n) acc[a][b][m][n] = (f32x4){0.f, 0.f, 0.f, 0.f};
;         cur = nxt; cA = nA; cB = nB; ++ui;
.LBB0_450:
	s_ashr_i32 s11, s10, 31
	s_lshl_b64 s[12:13], s[10:11], 19
	s_add_u32 s12, s24, s12
	s_addc_u32 s13, s25, s13
	s_and_b64 s[16:17], s[2:3], exec
	s_cselect_b32 s11, s13, s81
	s_cselect_b32 s34, s12, s80
	s_ashr_i32 s9, s8, 31
	s_lshl_b64 s[16:17], s[8:9], 19
	s_add_u32 s16, s84, s16
	s_addc_u32 s17, s85, s17
	s_and_b64 s[60:61], s[2:3], exec
	s_cselect_b32 s9, s17, s79
	s_cselect_b32 s35, s16, s78
	s_add_u32 s42, s78, 0x100
	s_addc_u32 s60, s79, 0
	s_add_u32 s78, s80, 0x40080
	v_mov_b32_e32 v2, 0
	s_addc_u32 s79, s81, 0
	s_mov_b32 s61, -2
	v_mov_b32_e32 v3, v2
	v_mov_b32_e32 v4, v2
	v_mov_b32_e32 v5, v2
	v_mov_b32_e32 v6, v2
	v_mov_b32_e32 v7, v2
	v_mov_b32_e32 v8, v2
	v_mov_b32_e32 v9, v2
	v_mov_b32_e32 v18, v2
	v_mov_b32_e32 v19, v2
	v_mov_b32_e32 v20, v2
	v_mov_b32_e32 v21, v2
	v_mov_b32_e32 v22, v2
	v_mov_b32_e32 v23, v2
	v_mov_b32_e32 v24, v2
	v_mov_b32_e32 v25, v2
	v_mov_b32_e32 v34, v2
	v_mov_b32_e32 v35, v2
	v_mov_b32_e32 v36, v2
	v_mov_b32_e32 v37, v2
	v_mov_b32_e32 v38, v2
	v_mov_b32_e32 v39, v2
	v_mov_b32_e32 v40, v2
	v_mov_b32_e32 v41, v2
	v_mov_b32_e32 v50, v2
	v_mov_b32_e32 v51, v2
	v_mov_b32_e32 v52, v2
	v_mov_b32_e32 v53, v2
	v_mov_b32_e32 v54, v2
	v_mov_b32_e32 v55, v2
	v_mov_b32_e32 v56, v2
	v_mov_b32_e32 v57, v2
	v_mov_b32_e32 v10, v2
	v_mov_b32_e32 v11, v2
	v_mov_b32_e32 v12, v2
	v_mov_b32_e32 v13, v2
	v_mov_b32_e32 v14, v2
	v_mov_b32_e32 v15, v2
	v_mov_b32_e32 v16, v2
	v_mov_b32_e32 v17, v2
	v_mov_b32_e32 v26, v2
	v_mov_b32_e32 v27, v2
	v_mov_b32_e32 v28, v2
	v_mov_b32_e32 v29, v2
	v_mov_b32_e32 v30, v2
	v_mov_b32_e32 v31, v2
	v_mov_b32_e32 v32, v2
	v_mov_b32_e32 v33, v2
	v_mov_b32_e32 v42, v2
	v_mov_b32_e32 v43, v2
	v_mov_b32_e32 v44, v2
	v_mov_b32_e32 v45, v2
	v_mov_b32_e32 v46, v2
	v_mov_b32_e32 v47, v2
	v_mov_b32_e32 v48, v2
	v_mov_b32_e32 v49, v2
	v_mov_b32_e32 v58, v2
	v_mov_b32_e32 v59, v2
	v_mov_b32_e32 v60, v2
	v_mov_b32_e32 v61, v2
	v_mov_b32_e32 v62, v2
	v_mov_b32_e32 v63, v2
	v_mov_b32_e32 v64, v2
	v_mov_b32_e32 v65, v2
	v_mov_b32_e32 v66, v2
	v_mov_b32_e32 v67, v2
	v_mov_b32_e32 v68, v2
	v_mov_b32_e32 v69, v2
	v_mov_b32_e32 v70, v2
	v_mov_b32_e32 v71, v2
	v_mov_b32_e32 v72, v2
	v_mov_b32_e32 v73, v2
	v_mov_b32_e32 v82, v2
	v_mov_b32_e32 v83, v2
	v_mov_b32_e32 v84, v2
	v_mov_b32_e32 v85, v2
	v_mov_b32_e32 v86, v2
	v_mov_b32_e32 v87, v2
	v_mov_b32_e32 v88, v2
	v_mov_b32_e32 v89, v2
	v_mov_b32_e32 v98, v2
	v_mov_b32_e32 v99, v2
	v_mov_b32_e32 v100, v2
	v_mov_b32_e32 v101, v2
	v_mov_b32_e32 v102, v2
	v_mov_b32_e32 v103, v2
	v_mov_b32_e32 v104, v2
	v_mov_b32_e32 v105, v2
	v_mov_b32_e32 v114, v2
	v_mov_b32_e32 v115, v2
	v_mov_b32_e32 v116, v2
	v_mov_b32_e32 v117, v2
	v_mov_b32_e32 v118, v2
	v_mov_b32_e32 v119, v2
	v_mov_b32_e32 v120, v2
	v_mov_b32_e32 v121, v2
	v_mov_b32_e32 v74, v2
	v_mov_b32_e32 v75, v2
	v_mov_b32_e32 v76, v2
	v_mov_b32_e32 v77, v2
	v_mov_b32_e32 v78, v2
	v_mov_b32_e32 v79, v2
	v_mov_b32_e32 v80, v2
	v_mov_b32_e32 v81, v2
	v_mov_b32_e32 v90, v2
	v_mov_b32_e32 v91, v2
	v_mov_b32_e32 v92, v2
	v_mov_b32_e32 v93, v2
	v_mov_b32_e32 v94, v2
	v_mov_b32_e32 v95, v2
	v_mov_b32_e32 v96, v2
	v_mov_b32_e32 v97, v2
	v_mov_b32_e32 v106, v2
	v_mov_b32_e32 v107, v2
	v_mov_b32_e32 v108, v2
	v_mov_b32_e32 v109, v2
	v_mov_b32_e32 v110, v2
	v_mov_b32_e32 v111, v2
	v_mov_b32_e32 v112, v2
	v_mov_b32_e32 v113, v2
	v_mov_b32_e32 v122, v2
	v_mov_b32_e32 v123, v2
	v_mov_b32_e32 v124, v2
	v_mov_b32_e32 v125, v2
	v_mov_b32_e32 v126, v2
	v_mov_b32_e32 v127, v2
	v_mov_b32_e32 v128, v2
	v_mov_b32_e32 v129, v2
	s_waitcnt vmcnt(0)

; #define LAS __attribute__((address_space(3)))
; template <int DIR>
; __device__ __forceinline__ void rnn_item(LAS unsigned char* lds, const bf16_t* proj, bf16_t* hout, int hpitch, int layer, int s, int n) {
;     ...
; #pragma unroll
;         for (int ks = 0; ks < 4; ++ks)
; #pragma unroll
;             for (int mt = 0; mt < 4; ++mt) {
;                 const bf16x8 af = *(const LAS bf16x8*)(At + buf * 17408 + (mt * 16 + l16) * 272 + ks * 64 + kg * 16);
;                 aA[mt] = __builtin_amdgcn_mfma_f32_16x16x32_bf16(af, bfr[0][ks], aA[mt], 0, 0, 0);
;                 aX[mt] = __builtin_amdgcn_mfma_f32_16x16x32_bf16(af, bfr[1][ks], aX[mt], 0, 0, 0);
;             }
.LBB0_537:
	s_or_b64 exec, exec, s[16:17]
	s_xor_b32 s16, s34, 1
	s_mul_i32 s17, s16, 0x4300
	v_add_u32_e32 v1, s17, v107
	ds_read_b128 v[64:67], v1
	ds_read_b128 v[68:71], v1 offset:256
	ds_read_b128 v[84:87], v1 offset:512
	ds_read_b128 v[92:95], v1 offset:768
	ds_read_b128 v[60:63], v1 offset:1024
	ds_read_b128 v[96:99], v120
	ds_read_b128 v[100:103], v120 offset:16
	ds_read_b128 v[142:145], v120 offset:512
	ds_read_b128 v[164:167], v120 offset:528
	ds_read_b128 v[168:171], v120 offset:1024
	ds_read_b128 v[204:207], v120 offset:1040
	ds_read_b128 v[172:175], v120 offset:1536
	ds_read_b128 v[192:195], v120 offset:1552
	ds_read_b128 v[196:199], v120 offset:2048
	ds_read_b128 v[200:203], v120 offset:2064
	s_mulk_i32 s16, 0x4400
	v_add_u32_e32 v2, s16, v112
	s_mul_i32 s16, s34, 0x4400
	v_cndmask_b32_e64 v131, v131, v135, s[6:7]
	s_add_i32 s69, s69, 1
	s_add_i32 s19, s19, 0xfff90000
	s_sub_i32 s68, s68, 64
	s_waitcnt lgkmcnt(0)
	v_lshlrev_b32_e32 v208, 16, v64
	v_and_b32_e32 v209, 0xffff0000, v64
	v_lshlrev_b32_e32 v210, 16, v68
	v_and_b32_e32 v211, 0xffff0000, v68
	v_lshlrev_b32_e32 v212, 16, v84
	v_and_b32_e32 v213, 0xffff0000, v84
	v_lshlrev_b32_e32 v214, 16, v92
	v_and_b32_e32 v215, 0xffff0000, v92
	v_lshlrev_b32_e32 v216, 16, v60
	v_and_b32_e32 v217, 0xffff0000, v60
	v_fma_f32 v218, v96, v208, v196
	v_fmac_f32_e32 v218, v142, v210
	v_fmac_f32_e32 v218, v168, v212
	v_fmac_f32_e32 v218, v172, v214
	v_fma_f32 v226, v96, v210, v196
	v_fmac_f32_e32 v226, v142, v212
	v_fmac_f32_e32 v226, v168, v214
	v_fmac_f32_e32 v226, v172, v216
	v_fma_f32 v219, v97, v209, v197
	v_fmac_f32_e32 v219, v143, v211
	v_fmac_f32_e32 v219, v169, v213
	v_fmac_f32_e32 v219, v173, v215
	v_fma_f32 v227, v97, v211, v197
	v_fmac_f32_e32 v227, v143, v213
	v_fmac_f32_e32 v227, v169, v215
	v_fmac_f32_e32 v227, v173, v217
	v_lshlrev_b32_e32 v208, 16, v65
	v_and_b32_e32 v209, 0xffff0000, v65
	v_lshlrev_b32_e32 v210, 16, v69
	v_and_b32_e32 v211, 0xffff0000, v69
	v_lshlrev_b32_e32 v212, 16, v85
	v_and_b32_e32 v213, 0xffff0000, v85
	v_lshlrev_b32_e32 v214, 16, v93
	v_and_b32_e32 v215, 0xffff0000, v93
	v_lshlrev_b32_e32 v216, 16, v61
	v_and_b32_e32 v217, 0xffff0000, v61
	v_fma_f32 v220, v98, v208, v198
	v_fmac_f32_e32 v220, v144, v210
	v_fmac_f32_e32 v220, v170, v212
	v_fmac_f32_e32 v220, v174, v214
	v_fma_f32 v228, v98, v210, v198
	v_fmac_f32_e32 v228, v144, v212
	v_fmac_f32_e32 v228, v170, v214
	v_fmac_f32_e32 v228, v174, v216
	v_fma_f32 v221, v99, v209, v199
	v_fmac_f32_e32 v221, v145, v211
	v_fmac_f32_e32 v221, v171, v213
	v_fmac_f32_e32 v221, v175, v215
	v_fma_f32 v229, v99, v211, v199
	v_fmac_f32_e32 v229, v145, v213
	v_fmac_f32_e32 v229, v171, v215
	v_fmac_f32_e32 v229, v175, v217
	v_lshlrev_b32_e32 v208, 16, v66
	v_and_b32_e32 v209, 0xffff0000, v66
	v_lshlrev_b32_e32 v210, 16, v70
	v_and_b32_e32 v211, 0xffff0000, v70
	v_lshlrev_b32_e32 v212, 16, v86
	v_and_b32_e32 v213, 0xffff0000, v86
	v_lshlrev_b32_e32 v214, 16, v94
	v_and_b32_e32 v215, 0xffff0000, v94
	v_lshlrev_b32_e32 v216, 16, v62
	v_and_b32_e32 v217, 0xffff0000, v62
	v_fma_f32 v222, v100, v208, v200
	v_fmac_f32_e32 v222, v164, v210
	v_fmac_f32_e32 v222, v204, v212
	v_fmac_f32_e32 v222, v192, v214
	v_fma_f32 v230, v100, v210, v200
	v_fmac_f32_e32 v230, v164, v212
	v_fmac_f32_e32 v230, v204, v214
	v_fmac_f32_e32 v230, v192, v216
	v_fma_f32 v223, v101, v209, v201
	v_fmac_f32_e32 v223, v165, v211
	v_fmac_f32_e32 v223, v205, v213
	v_fmac_f32_e32 v223, v193, v215
	v_fma_f32 v231, v101, v211, v201
	v_fmac_f32_e32 v231, v165, v213
	v_fmac_f32_e32 v231, v205, v215
	v_fmac_f32_e32 v231, v193, v217
	v_lshlrev_b32_e32 v208, 16, v67
	v_and_b32_e32 v209, 0xffff0000, v67
	v_lshlrev_b32_e32 v210, 16, v71
	v_and_b32_e32 v211, 0xffff0000, v71
	v_lshlrev_b32_e32 v212, 16, v87
	v_and_b32_e32 v213, 0xffff0000, v87
	v_lshlrev_b32_e32 v214, 16, v95
	v_and_b32_e32 v215, 0xffff0000, v95
	v_lshlrev_b32_e32 v216, 16, v63
	v_and_b32_e32 v217, 0xffff0000, v63
	v_fma_f32 v224, v102, v208, v202
	v_fmac_f32_e32 v224, v166, v210
	v_fmac_f32_e32 v224, v206, v212
	v_fmac_f32_e32 v224, v194, v214
	v_fma_f32 v232, v102, v210, v202
	v_fmac_f32_e32 v232, v166, v212
	v_fmac_f32_e32 v232, v206, v214
	v_fmac_f32_e32 v232, v194, v216
	v_fma_f32 v225, v103, v209, v203
	v_fmac_f32_e32 v225, v167, v211
	v_fmac_f32_e32 v225, v207, v213
	v_fmac_f32_e32 v225, v195, v215
	v_fma_f32 v233, v103, v211, v203
	v_fmac_f32_e32 v233, v167, v213
	v_fmac_f32_e32 v233, v207, v215
	v_fmac_f32_e32 v233, v195, v217
	v_cvt_pk_bf16_f32 v234, v218, v219
	v_cvt_pk_bf16_f32 v235, v220, v221
	v_cvt_pk_bf16_f32 v236, v222, v223
	v_cvt_pk_bf16_f32 v237, v224, v225
	v_cvt_pk_bf16_f32 v238, v226, v227
	v_cvt_pk_bf16_f32 v239, v228, v229
	v_cvt_pk_bf16_f32 v240, v230, v231
	v_cvt_pk_bf16_f32 v241, v232, v233
	ds_write_b128 v2, v[234:237] offset:34304
	ds_write_b128 v2, v[238:241] offset:34576
	v_add_u32_e32 v1, s16, v127
	ds_read_b128 v[60:63], v1 offset:34304
	ds_read_b128 v[64:67], v1 offset:34368
	ds_read_b128 v[84:87], v1 offset:38656
	ds_read_b128 v[92:95], v1 offset:38720
	ds_read_b128 v[100:103], v1 offset:43008
	ds_read_b128 v[142:145], v1 offset:43072
	ds_read_b128 v[168:171], v1 offset:47360
	ds_read_b128 v[172:175], v1 offset:47424
	ds_read_b128 v[204:207], v1 offset:34432
	ds_read_b128 v[208:211], v1 offset:34496
	ds_read_b128 v[212:215], v1 offset:38784
	ds_read_b128 v[216:219], v1 offset:38848
	ds_read_b128 v[220:223], v1 offset:43136
	ds_read_b128 v[224:227], v1 offset:43200
	ds_read_b128 v[228:231], v1 offset:47488
	ds_read_b128 v[232:235], v1 offset:47552
	s_waitcnt lgkmcnt(8)
; #define LAS __attribute__((address_space(3)))
; __device__ __forceinline__ float bf_1(bf16_t h) { return __uint_as_float(((unsigned)h) << 16); }
; template <int DIR>
; __device__ __forceinline__ void rnn_item(LAS unsigned char* lds, const bf16_t* proj, bf16_t* hout, int hpitch, int layer, int s, int n) {
;     ...
; #pragma unroll
;         for (int ks = 0; ks < 4; ++ks)
; #pragma unroll
;             for (int mt = 0; mt < 4; ++mt) {
;                 const bf16x8 af = *(const LAS bf16x8*)(At + buf * 17408 + (mt * 16 + l16) * 272 + ks * 64 + kg * 16);
;                 aA[mt] = __builtin_amdgcn_mfma_f32_16x16x32_bf16(af, bfr[0][ks], aA[mt], 0, 0, 0);
;                 aX[mt] = __builtin_amdgcn_mfma_f32_16x16x32_bf16(af, bfr[1][ks], aX[mt], 0, 0, 0);
;             }
;         {   typedef float f32x2 __attribute__((ext_vector_type(2)));
; #pragma unroll
;             for (int mt = 0; mt < 4; ++mt)
; #pragma unroll
;                 for (int rp = 0; rp < 2; ++rp) {
;                     const LAS unsigned char* xp = At + buf * 17408 + (mt * 16 + kg * 4 + 2 * rp) * 272 + (w * 16 + l16) * 2;
;                     const f32x2 xc = {bf_1(*(const LAS bf16_t*)xp), bf_1(*(const LAS bf16_t*)(xp + 272))};
;                     const f32x2 xa = {aA[mt][2 * rp], aA[mt][2 * rp + 1]}, xx = {aX[mt][2 * rp], aX[mt][2 * rp + 1]};
;                     f32x2 ta = xa * (-LOG2E) + nba, tx = xx * (-LOG2E) + nbx;
;                     ta.x = fminf(ta.x, 60.f); ta.y = fminf(ta.y, 60.f); tx.x = fminf(tx.x, 60.f); tx.y = fminf(tx.y, 60.f);
;                     f32x2 ea, ex; ea.x = __builtin_amdgcn_exp2f(ta.x); ea.y = __builtin_amdgcn_exp2f(ta.y); ex.x = __builtin_amdgcn_exp2f(tx.x); ex.y = __builtin_amdgcn_exp2f(tx.y);
;                     const f32x2 da = ea + 1.0f, dx = ex + 1.0f, dd = da * dx;
;                     f32x2 inv; inv.x = __builtin_amdgcn_rcpf(dd.x); inv.y = __builtin_amdgcn_rcpf(dd.y);
;                     const f32x2 rr = dx * inv, ii = da * inv, tt = rr * clam2;
	v_mfma_f32_16x16x32_bf16 v[68:71], v[60:63], v[4:7], 0
	v_mfma_f32_16x16x32_bf16 v[60:63], v[60:63], v[20:23], 0
	v_mfma_f32_16x16x32_bf16 v[96:99], v[84:87], v[4:7], 0
	v_mfma_f32_16x16x32_bf16 v[84:87], v[84:87], v[20:23], 0
	v_mfma_f32_16x16x32_bf16 v[164:167], v[100:103], v[4:7], 0
	v_mfma_f32_16x16x32_bf16 v[100:103], v[100:103], v[20:23], 0
	v_mfma_f32_16x16x32_bf16 v[192:195], v[168:171], v[4:7], 0
	v_mfma_f32_16x16x32_bf16 v[168:171], v[168:171], v[20:23], 0
	v_mfma_f32_16x16x32_bf16 v[68:71], v[64:67], v[8:11], v[68:71]
	v_mfma_f32_16x16x32_bf16 v[60:63], v[64:67], v[24:27], v[60:63]
	v_mfma_f32_16x16x32_bf16 v[64:67], v[92:95], v[8:11], v[96:99]
	v_mfma_f32_16x16x32_bf16 v[84:87], v[92:95], v[24:27], v[84:87]
	v_mfma_f32_16x16x32_bf16 v[92:95], v[142:145], v[8:11], v[164:167]
	v_mfma_f32_16x16x32_bf16 v[96:99], v[142:145], v[24:27], v[100:103]
	v_mfma_f32_16x16x32_bf16 v[142:145], v[172:175], v[24:27], v[168:171]
	s_nop 0
	s_nop 0
	v_mfma_f32_16x16x32_bf16 v[100:103], v[172:175], v[8:11], v[192:195]
	s_waitcnt lgkmcnt(0)
	v_mfma_f32_16x16x32_bf16 v[68:71], v[204:207], v[12:15], v[68:71]
	v_mfma_f32_16x16x32_bf16 v[60:63], v[204:207], v[28:31], v[60:63]
	s_waitcnt lgkmcnt(0)
	v_mfma_f32_16x16x32_bf16 v[64:67], v[212:215], v[12:15], v[64:67]
	v_mfma_f32_16x16x32_bf16 v[84:87], v[212:215], v[28:31], v[84:87]
	s_waitcnt lgkmcnt(0)
	v_mfma_f32_16x16x32_bf16 v[92:95], v[220:223], v[12:15], v[92:95]
	v_mfma_f32_16x16x32_bf16 v[96:99], v[220:223], v[28:31], v[96:99]
	s_waitcnt lgkmcnt(0)
	v_mfma_f32_16x16x32_bf16 v[100:103], v[228:231], v[12:15], v[100:103]
	v_mfma_f32_16x16x32_bf16 v[142:145], v[228:231], v[28:31], v[142:145]
	v_mfma_f32_16x16x32_bf16 v[164:167], v[208:211], v[16:19], v[68:71]
	v_mfma_f32_16x16x32_bf16 v[168:171], v[208:211], v[32:35], v[60:63]
	v_mfma_f32_16x16x32_bf16 v[200:203], v[216:219], v[16:19], v[64:67]
	s_nop 5
	v_fma_f32 v2, -v164, s50, v114
	v_fma_f32 v3, -v165, s50, v115
	v_pk_fma_f32 v[60:61], v[168:169], s[50:51], v[116:117] op_sel_hi:[1,0,1] neg_lo:[1,0,0] neg_hi:[1,0,0]
	v_min_f32_e32 v1, 0x42700000, v2
	v_min_f32_e32 v3, 0x42700000, v3
	v_min_f32_e32 v60, 0x42700000, v60
	v_min_f32_e32 v61, 0x42700000, v61
	v_exp_f32_e32 v2, v1
	v_exp_f32_e32 v3, v3
	v_exp_f32_e32 v64, v60
	v_exp_f32_e32 v65, v61
	v_mfma_f32_16x16x32_bf16 v[68:71], v[224:227], v[16:19], v[92:95]
	v_add_f32_e64 v2, v2, 1.0
	v_add_f32_e64 v3, v3, 1.0
	v_add_u32_e32 v1, s16, v126
	s_lshl_b32 s16, s34, 14
	v_pk_add_f32 v[92:93], v[64:65], 1.0 op_sel_hi:[1,0]
	v_mfma_f32_16x16x32_bf16 v[172:175], v[216:219], v[32:35], v[84:87]
	v_mul_f32_e64 v64, v92, v2
	v_mul_f32_e64 v65, v93, v3
	v_pk_fma_f32 v[68:69], v[68:69], s[50:51], v[114:115] op_sel_hi:[1,0,1] neg_lo:[1,0,0] neg_hi:[1,0,0]
	v_rcp_f32_e32 v94, v64
	v_rcp_f32_e32 v95, v65
	v_mfma_f32_16x16x32_bf16 v[84:87], v[224:227], v[32:35], v[96:99]
	v_min_f32_e32 v68, 0x42700000, v68
	v_min_f32_e32 v69, 0x42700000, v69
	v_pk_mul_f32 v[92:93], v[92:93], v[94:95]
	v_mfma_f32_16x16x32_bf16 v[60:63], v[232:235], v[16:19], v[100:103]
	v_mul_f32_e64 v92, v118, v92
	v_mul_f32_e64 v93, v119, v93
	v_pk_fma_f32 v[98:99], v[166:167], s[50:51], v[114:115] op_sel_hi:[1,0,1] neg_lo:[1,0,0] neg_hi:[1,0,0]
	v_exp_f32_e32 v92, v92
	v_pk_fma_f32 v[100:101], v[170:171], s[50:51], v[116:117] op_sel_hi:[1,0,1] neg_lo:[1,0,0] neg_hi:[1,0,0]
	v_exp_f32_e32 v93, v93
	v_min_f32_e32 v98, 0x42700000, v98
	v_min_f32_e32 v99, 0x42700000, v99
	v_min_f32_e32 v100, 0x42700000, v100
	v_min_f32_e32 v101, 0x42700000, v101
	v_exp_f32_e32 v98, v98
	v_exp_f32_e32 v99, v99
	v_exp_f32_e32 v100, v100
	v_exp_f32_e32 v101, v101
	v_pk_mul_f32 v[2:3], v[2:3], v[94:95]
	v_pk_fma_f32 v[94:95], v[92:93], v[92:93], 1.0 op_sel_hi:[1,1,0] neg_lo:[1,0,0] neg_hi:[1,0,0]
	v_pk_add_f32 v[98:99], v[98:99], 1.0 op_sel_hi:[1,0]
	v_max_f32_e32 v102, 0, v94
	v_max_f32_e32 v103, 0, v95
	v_pk_add_f32 v[94:95], v[100:101], 1.0 op_sel_hi:[1,0]
	v_mfma_f32_16x16x32_bf16 v[64:67], v[232:235], v[32:35], v[142:145]
	v_mul_f32_e64 v100, v94, v98
	v_mul_f32_e64 v101, v95, v99
	ds_read_u16 v96, v1 offset:34304
	ds_read_u16 v97, v1 offset:34576
	ds_read_u16 v141, v1 offset:34848
	ds_read_u16 v142, v1 offset:35120
	ds_read_u16 v164, v1 offset:38656
	ds_read_u16 v165, v1 offset:38928
	ds_read_u16 v168, v1 offset:39200
	ds_read_u16 v169, v1 offset:39472
	v_rcp_f32_e32 v100, v100
	v_rcp_f32_e32 v101, v101
	s_waitcnt lgkmcnt(0)
; #define LAS __attribute__((address_space(3)))
; __device__ __forceinline__ float bf_1(bf16_t h) { return __uint_as_float(((unsigned)h) << 16); }
; template <int DIR>
; __device__ __forceinline__ void rnn_item(LAS unsigned char* lds, const bf16_t* proj, bf16_t* hout, int hpitch, int layer, int s, int n) {
;     ...
;                     const LAS unsigned char* xp = At + buf * 17408 + (mt * 16 + kg * 4 + 2 * rp) * 272 + (w * 16 + l16) * 2;
;                     const f32x2 xc = {bf_1(*(const LAS bf16_t*)xp), bf_1(*(const LAS bf16_t*)(xp + 272))};
;                     const f32x2 xa = {aA[mt][2 * rp], aA[mt][2 * rp + 1]}, xx = {aX[mt][2 * rp], aX[mt][2 * rp + 1]};
;                     f32x2 ta = xa * (-LOG2E) + nba, tx = xx * (-LOG2E) + nbx;
;                     ta.x = fminf(ta.x, 60.f); ta.y = fminf(ta.y, 60.f); tx.x = fminf(tx.x, 60.f); tx.y = fminf(tx.y, 60.f);
;                     f32x2 ea, ex; ea.x = __builtin_amdgcn_exp2f(ta.x); ea.y = __builtin_amdgcn_exp2f(ta.y); ex.x = __builtin_amdgcn_exp2f(tx.x); ex.y = __builtin_amdgcn_exp2f(tx.y);
;                     const f32x2 da = ea + 1.0f, dx = ex + 1.0f, dd = da * dx;
;                     f32x2 inv; inv.x = __builtin_amdgcn_rcpf(dd.x); inv.y = __builtin_amdgcn_rcpf(dd.y);
;                     const f32x2 rr = dx * inv, ii = da * inv, tt = rr * clam2;
;                     f32x2 av; av.x = __builtin_amdgcn_exp2f(tt.x); av.y = __builtin_amdgcn_exp2f(tt.y);
;                     f32x2 om = 1.0f - av * av; om.x = fmaxf(om.x, 0.f); om.y = fmaxf(om.y, 0.f);
;                     f32x2 sq; sq.x = __builtin_amdgcn_sqrtf(om.x); sq.y = __builtin_amdgcn_sqrtf(om.y);
;                     const f32x2 bv = sq * (ii * xc);
;                     aA[mt][2 * rp] = av.x; aA[mt][2 * rp + 1] = av.y; aX[mt][2 * rp] = bv.x; aX[mt][2 * rp + 1] = bv.y;
;                 }
	v_lshlrev_b32_e32 v96, 16, v96
	v_lshlrev_b32_e32 v97, 16, v97
	v_pk_mul_f32 v[96:97], v[2:3], v[96:97]
	v_pk_mul_f32 v[2:3], v[94:95], v[100:101]
	v_sqrt_f32_e32 v102, v102
	v_pk_mul_f32 v[2:3], v[118:119], v[2:3]
	v_sqrt_f32_e32 v103, v103
	v_exp_f32_e32 v2, v2
	v_exp_f32_e32 v3, v3
	v_pk_mul_f32 v[98:99], v[98:99], v[100:101]
	v_pk_mul_f32 v[94:95], v[96:97], v[102:103]
	v_lshlrev_b32_e32 v96, 16, v141
	v_pk_fma_f32 v[102:103], v[2:3], v[2:3], 1.0 op_sel_hi:[1,1,0] neg_lo:[1,0,0] neg_hi:[1,0,0]
	v_lshlrev_b32_e32 v97, 16, v142
	v_max_f32_e32 v141, 0, v102
	v_max_f32_e32 v145, 0, v103
	v_pk_fma_f32 v[102:103], v[200:201], s[50:51], v[114:115] op_sel_hi:[1,0,1] neg_lo:[1,0,0] neg_hi:[1,0,0]
	v_pk_fma_f32 v[142:143], v[172:173], s[50:51], v[116:117] op_sel_hi:[1,0,1] neg_lo:[1,0,0] neg_hi:[1,0,0]
	v_min_f32_e32 v102, 0x42700000, v102
	v_min_f32_e32 v103, 0x42700000, v103
	v_min_f32_e32 v142, 0x42700000, v142
	v_min_f32_e32 v143, 0x42700000, v143
	v_exp_f32_e32 v102, v102
	v_exp_f32_e32 v103, v103
	v_exp_f32_e32 v142, v142
	v_exp_f32_e32 v143, v143
	v_sqrt_f32_e32 v144, v141
	v_pk_add_f32 v[146:147], v[102:103], 1.0 op_sel_hi:[1,0]
	v_sqrt_f32_e32 v145, v145
	v_pk_add_f32 v[102:103], v[142:143], 1.0 op_sel_hi:[1,0]
	v_pk_mul_f32 v[96:97], v[98:99], v[96:97]
	v_pk_mul_f32 v[142:143], v[102:103], v[146:147]
	v_pk_mul_f32 v[96:97], v[96:97], v[144:145]
	v_rcp_f32_e32 v142, v142
	v_rcp_f32_e32 v143, v143
	v_pk_fma_f32 v[144:145], v[202:203], s[50:51], v[114:115] op_sel_hi:[1,0,1] neg_lo:[1,0,0] neg_hi:[1,0,0]
	v_pk_fma_f32 v[84:85], v[84:85], s[50:51], v[116:117] op_sel_hi:[1,0,1] neg_lo:[1,0,0] neg_hi:[1,0,0]
	v_min_f32_e32 v141, 0x42700000, v144
	v_pk_mul_f32 v[98:99], v[102:103], v[142:143]
	v_pk_mul_f32 v[100:101], v[146:147], v[142:143]
	v_pk_mul_f32 v[98:99], v[118:119], v[98:99]
	v_pk_fma_f32 v[146:147], v[174:175], s[50:51], v[116:117] op_sel_hi:[1,0,1] neg_lo:[1,0,0] neg_hi:[1,0,0]
	v_exp_f32_e32 v102, v98
	v_exp_f32_e32 v103, v99
	v_min_f32_e32 v145, 0x42700000, v145
	v_min_f32_e32 v146, 0x42700000, v146
	v_min_f32_e32 v147, 0x42700000, v147
	v_exp_f32_e32 v144, v141
	v_exp_f32_e32 v145, v145
	v_exp_f32_e32 v146, v146
	v_exp_f32_e32 v147, v147
	v_pk_fma_f32 v[142:143], v[102:103], v[102:103], 1.0 op_sel_hi:[1,1,0] neg_lo:[1,0,0] neg_hi:[1,0,0]
	v_min_f32_e32 v84, 0x42700000, v84
	v_min_f32_e32 v85, 0x42700000, v85
	v_lshlrev_b32_e32 v99, 16, v165
	v_max_f32_e32 v141, 0, v142
	v_max_f32_e32 v165, 0, v143
	v_pk_add_f32 v[142:143], v[144:145], 1.0 op_sel_hi:[1,0]
	v_pk_add_f32 v[144:145], v[146:147], 1.0 op_sel_hi:[1,0]
	v_exp_f32_e32 v68, v68
	v_exp_f32_e32 v69, v69
	v_exp_f32_e32 v84, v84
	v_exp_f32_e32 v85, v85
	v_pk_mul_f32 v[146:147], v[144:145], v[142:143]
	v_pk_add_f32 v[166:167], v[68:69], 1.0 op_sel_hi:[1,0]
	v_rcp_f32_e32 v146, v146
	v_rcp_f32_e32 v147, v147
	v_pk_add_f32 v[84:85], v[84:85], 1.0 op_sel_hi:[1,0]
	v_lshlrev_b32_e32 v98, 16, v164
	v_pk_mul_f32 v[68:69], v[84:85], v[166:167]
	v_pk_mul_f32 v[100:101], v[100:101], v[98:99]
	v_pk_mul_f32 v[98:99], v[144:145], v[146:147]
	v_lshlrev_b32_e32 v144, 16, v168
	v_lshlrev_b32_e32 v145, 16, v169
	v_rcp_f32_e32 v168, v68
	v_rcp_f32_e32 v169, v69
	v_pk_mul_f32 v[98:99], v[118:119], v[98:99]
	v_sqrt_f32_e32 v164, v141
	v_sqrt_f32_e32 v165, v165
	v_exp_f32_e32 v98, v98
	v_exp_f32_e32 v99, v99
	v_pk_mul_f32 v[84:85], v[84:85], v[168:169]
	v_pk_fma_f32 v[70:71], v[70:71], s[50:51], v[114:115] op_sel_hi:[1,0,1] neg_lo:[1,0,0] neg_hi:[1,0,0]
	v_pk_fma_f32 v[86:87], v[86:87], s[50:51], v[116:117] op_sel_hi:[1,0,1] neg_lo:[1,0,0] neg_hi:[1,0,0]
	v_pk_mul_f32 v[84:85], v[118:119], v[84:85]
	v_min_f32_e32 v70, 0x42700000, v70
	v_min_f32_e32 v71, 0x42700000, v71
	v_min_f32_e32 v86, 0x42700000, v86
	v_min_f32_e32 v87, 0x42700000, v87
	v_pk_mul_f32 v[68:69], v[142:143], v[146:147]
	v_exp_f32_e32 v142, v84
	v_exp_f32_e32 v143, v85
	v_exp_f32_e32 v70, v70
	v_exp_f32_e32 v71, v71
	v_exp_f32_e32 v86, v86
	v_exp_f32_e32 v87, v87
	v_pk_mul_f32 v[100:101], v[100:101], v[164:165]
	v_pk_fma_f32 v[164:165], v[98:99], v[98:99], 1.0 op_sel_hi:[1,1,0] neg_lo:[1,0,0] neg_hi:[1,0,0]
	v_pk_mul_f32 v[68:69], v[68:69], v[144:145]
	v_max_f32_e32 v141, 0, v164
	v_max_f32_e32 v165, 0, v165
	v_sqrt_f32_e32 v164, v141
	v_sqrt_f32_e32 v165, v165
	v_pk_fma_f32 v[144:145], v[142:143], v[142:143], 1.0 op_sel_hi:[1,1,0] neg_lo:[1,0,0] neg_hi:[1,0,0]
	v_pk_add_f32 v[146:147], v[70:71], 1.0 op_sel_hi:[1,0]
	v_pk_add_f32 v[70:71], v[86:87], 1.0 op_sel_hi:[1,0]
	v_pk_fma_f32 v[60:61], v[60:61], s[50:51], v[114:115] op_sel_hi:[1,0,1] neg_lo:[1,0,0] neg_hi:[1,0,0]
	v_pk_fma_f32 v[64:65], v[64:65], s[50:51], v[116:117] op_sel_hi:[1,0,1] neg_lo:[1,0,0] neg_hi:[1,0,0]
	v_max_f32_e32 v144, 0, v144
	v_max_f32_e32 v145, 0, v145
	v_pk_mul_f32 v[86:87], v[70:71], v[146:147]
	v_min_f32_e32 v60, 0x42700000, v60
	v_min_f32_e32 v61, 0x42700000, v61
	v_min_f32_e32 v64, 0x42700000, v64
	v_min_f32_e32 v65, 0x42700000, v65
	v_sqrt_f32_e32 v144, v144
	v_sqrt_f32_e32 v145, v145
	v_rcp_f32_e32 v86, v86
	v_rcp_f32_e32 v87, v87
	v_exp_f32_e32 v60, v60
	v_exp_f32_e32 v61, v61
	v_exp_f32_e32 v64, v64
	v_exp_f32_e32 v65, v65
	ds_read_u16 v84, v1 offset:43008
	ds_read_u16 v85, v1 offset:43280
	ds_read_u16 v141, v1 offset:43552
	ds_read_u16 v170, v1 offset:43824
	ds_read_u16 v171, v1 offset:47360
	ds_read_u16 v172, v1 offset:47632
	ds_read_u16 v173, v1 offset:47904
	ds_read_u16 v1, v1 offset:48176
	v_pk_mul_f32 v[68:69], v[68:69], v[164:165]
	s_waitcnt lgkmcnt(0)
; template <int DIR>
; __device__ __forceinline__ void rnn_item(LAS unsigned char* lds, const bf16_t* proj, bf16_t* hout, int hpitch, int layer, int s, int n) {
;     ...
;                     f32x2 ea, ex; ea.x = __builtin_amdgcn_exp2f(ta.x); ea.y = __builtin_amdgcn_exp2f(ta.y); ex.x = __builtin_amdgcn_exp2f(tx.x); ex.y = __builtin_amdgcn_exp2f(tx.y);
;                     const f32x2 da = ea + 1.0f, dx = ex + 1.0f, dd = da * dx;
;                     f32x2 inv; inv.x = __builtin_amdgcn_rcpf(dd.x); inv.y = __builtin_amdgcn_rcpf(dd.y);
;                     const f32x2 rr = dx * inv, ii = da * inv, tt = rr * clam2;
;                     f32x2 av; av.x = __builtin_amdgcn_exp2f(tt.x); av.y = __builtin_amdgcn_exp2f(tt.y);
;                     f32x2 om = 1.0f - av * av; om.x = fmaxf(om.x, 0.f); om.y = fmaxf(om.y, 0.f);
;                     f32x2 sq; sq.x = __builtin_amdgcn_sqrtf(om.x); sq.y = __builtin_amdgcn_sqrtf(om.y);
;                     const f32x2 bv = sq * (ii * xc);
;                     aA[mt][2 * rp] = av.x; aA[mt][2 * rp + 1] = av.y; aX[mt][2 * rp] = bv.x; aX[mt][2 * rp + 1] = bv.y;
;                 }
;         }
; #pragma unroll
;         for (int mt = 0; mt < 4; ++mt) {
;             float pp = 1.f, hh = 0.f;
; #pragma unroll
;             for (int q = 0; q < 4; ++q) { const int r = DIR == 0 ? q : 3 - q; hh = aA[mt][r] * hh + aX[mt][r]; pp *= aA[mt][r]; aA[mt][r] = pp; aX[mt][r] = hh; }
;         }
;         float start[4]; float carry = hcarry;
; #pragma unroll
;         for (int hq = 0; hq < 2; ++hq) {
;             float Ar[8], Br[8];
; #pragma unroll
;             for (int q8 = 0; q8 < 8; ++q8) { const int q = hq * 8 + q8; const int rho = DIR == 0 ? q : 15 - q; const int mt = rho >> 2, kgp = rho & 3; constexpr int re = DIR == 0 ? 3 : 0;
;                 Ar[q8] = __shfl(aA[mt][re], l16 + 16 * kgp); Br[q8] = __shfl(aX[mt][re], l16 + 16 * kgp); }
	v_lshlrev_b32_e32 v84, 16, v84
	v_lshlrev_b32_e32 v85, 16, v85
	v_pk_mul_f32 v[164:165], v[166:167], v[168:169]
	v_pk_fma_f32 v[62:63], v[62:63], s[50:51], v[114:115] op_sel_hi:[1,0,1] neg_lo:[1,0,0] neg_hi:[1,0,0]
	v_pk_mul_f32 v[84:85], v[164:165], v[84:85]
	v_pk_fma_f32 v[66:67], v[66:67], s[50:51], v[116:117] op_sel_hi:[1,0,1] neg_lo:[1,0,0] neg_hi:[1,0,0]
	v_pk_mul_f32 v[84:85], v[84:85], v[144:145]
	v_pk_mul_f32 v[70:71], v[70:71], v[86:87]
	v_lshlrev_b32_e32 v144, 16, v141
	v_lshlrev_b32_e32 v145, 16, v170
	v_pk_mul_f32 v[86:87], v[146:147], v[86:87]
	v_pk_add_f32 v[60:61], v[60:61], 1.0 op_sel_hi:[1,0]
	v_pk_add_f32 v[64:65], v[64:65], 1.0 op_sel_hi:[1,0]
	v_min_f32_e32 v62, 0x42700000, v62
	v_min_f32_e32 v63, 0x42700000, v63
	v_min_f32_e32 v66, 0x42700000, v66
	v_min_f32_e32 v67, 0x42700000, v67
	v_pk_mul_f32 v[86:87], v[86:87], v[144:145]
	v_pk_mul_f32 v[144:145], v[64:65], v[60:61]
	v_exp_f32_e32 v62, v62
	v_exp_f32_e32 v63, v63
	v_exp_f32_e32 v66, v66
	v_exp_f32_e32 v67, v67
	v_rcp_f32_e32 v144, v144
	v_rcp_f32_e32 v145, v145
	v_pk_mul_f32 v[70:71], v[118:119], v[70:71]
	v_pk_add_f32 v[62:63], v[62:63], 1.0 op_sel_hi:[1,0]
	v_pk_add_f32 v[66:67], v[66:67], 1.0 op_sel_hi:[1,0]
	v_exp_f32_e32 v70, v70
	v_exp_f32_e32 v71, v71
	v_pk_mul_f32 v[64:65], v[64:65], v[144:145]
	v_pk_mul_f32 v[164:165], v[66:67], v[62:63]
	v_pk_mul_f32 v[64:65], v[118:119], v[64:65]
	v_rcp_f32_e32 v164, v164
	v_rcp_f32_e32 v165, v165
	v_exp_f32_e32 v64, v64
	v_exp_f32_e32 v65, v65
	v_pk_fma_f32 v[146:147], v[70:71], v[70:71], 1.0 op_sel_hi:[1,1,0] neg_lo:[1,0,0] neg_hi:[1,0,0]
	v_pk_mul_f32 v[66:67], v[66:67], v[164:165]
	v_max_f32_e32 v141, 0, v146
	v_max_f32_e32 v147, 0, v147
	v_sqrt_f32_e32 v146, v141
	v_sqrt_f32_e32 v147, v147
	v_pk_mul_f32 v[60:61], v[60:61], v[144:145]
	v_pk_fma_f32 v[144:145], v[64:65], v[64:65], 1.0 op_sel_hi:[1,1,0] neg_lo:[1,0,0] neg_hi:[1,0,0]
	v_pk_mul_f32 v[66:67], v[118:119], v[66:67]
	v_max_f32_e32 v141, 0, v144
	v_max_f32_e32 v145, 0, v145
	v_exp_f32_e32 v66, v66
	v_exp_f32_e32 v67, v67
	v_sqrt_f32_e32 v144, v141
	v_sqrt_f32_e32 v145, v145
	v_pk_mul_f32 v[86:87], v[86:87], v[146:147]
	v_lshlrev_b32_e32 v146, 16, v171
	v_lshlrev_b32_e32 v147, 16, v172
	v_pk_mul_f32 v[60:61], v[60:61], v[146:147]
	v_pk_fma_f32 v[146:147], v[66:67], v[66:67], 1.0 op_sel_hi:[1,1,0] neg_lo:[1,0,0] neg_hi:[1,0,0]
	v_pk_mul_f32 v[144:145], v[60:61], v[144:145]
	v_max_f32_e32 v61, 0, v146
	v_max_f32_e32 v141, 0, v147
	v_sqrt_f32_e32 v146, v61
	v_sqrt_f32_e32 v147, v141
	v_lshlrev_b32_e32 v60, 16, v173
	v_lshlrev_b32_e32 v61, 16, v1
	v_pk_mul_f32 v[62:63], v[62:63], v[164:165]
	v_fma_f32 v69, 0, v99, v69
	v_fma_f32 v87, 0, v71, v87
	v_pk_mul_f32 v[60:61], v[62:63], v[60:61]
	v_fma_f32 v1, 0, v3, v97
	v_fmac_f32_e32 v68, v98, v69
	v_mul_f32_e32 v97, v99, v98
	v_fmac_f32_e32 v86, v70, v87
	v_mul_f32_e32 v70, v71, v70
	v_pk_mul_f32 v[146:147], v[60:61], v[146:147]
	v_fma_f32 v98, v103, v68, v101
	v_mul_f32_e32 v101, v103, v97
	v_fma_f32 v85, v143, v86, v85
	v_mul_f32_e32 v103, v143, v70
	v_fmac_f32_e32 v84, v142, v85
	v_mul_f32_e32 v141, v142, v103
	v_fma_f32 v142, 0, v67, v147
	v_fmac_f32_e32 v146, v66, v142
	v_mul_f32_e32 v66, v67, v66
	v_fma_f32 v143, v65, v146, v145
	v_mul_f32_e32 v65, v65, v66
	v_fmac_f32_e32 v144, v64, v143
	v_mul_f32_e32 v64, v64, v65
	ds_bpermute_b32 v60, v128, v64
	ds_bpermute_b32 v61, v128, v144
	ds_bpermute_b32 v62, v129, v64
	ds_bpermute_b32 v63, v129, v144
	ds_bpermute_b32 v145, v130, v64
	ds_bpermute_b32 v147, v130, v144
	ds_bpermute_b32 v164, v123, v64
	ds_bpermute_b32 v165, v123, v144
	ds_bpermute_b32 v166, v128, v141
	ds_bpermute_b32 v167, v128, v84
	ds_bpermute_b32 v168, v129, v141
	ds_bpermute_b32 v169, v129, v84
	s_waitcnt lgkmcnt(0)
; #define LAS __attribute__((address_space(3)))
; __device__ __forceinline__ unsigned cvt_pk_bf16(float lo, float hi) { unsigned r; asm volatile("v_cvt_pk_bf16_f32 %0, %1, %2" : "=v"(r) : "v"(lo), "v"(hi)); return r; }
; #define RNN_BAR() do { asm volatile("s_waitcnt lgkmcnt(0)" ::: "memory"); __builtin_amdgcn_s_barrier(); asm volatile("" ::: "memory"); } while (0)
; template <int DIR>
; __device__ __forceinline__ void rnn_item(LAS unsigned char* lds, const bf16_t* proj, bf16_t* hout, int hpitch, int layer, int s, int n) {
;     ...
; #pragma unroll
;             for (int q8 = 0; q8 < 8; ++q8) { const int q = hq * 8 + q8; const int rho = DIR == 0 ? q : 15 - q; const int mt = rho >> 2, kgp = rho & 3;
;                 if (kg == kgp) start[mt] = carry;
;                 carry = Ar[q8] * carry + Br[q8]; }
;         }
;         hcarry = carry;
;         if (it > 0) {
; #pragma unroll
;             for (int i = 0; i < 2; ++i) { const int c = tid + 512 * i; const u32x4 v = *(const LAS u32x4*)(OUTB + (buf ^ 1) * 16384 + c * 16);
;                 *(u32x4*)(hout + (seqbase + (size_t)(sub - stp) * 64 + (c >> 4)) * hpitch + n * 128 + (c & 15) * 8) = v; }
;         }
;         {   LAS unsigned short* ob = (LAS unsigned short*)(OUTB + buf * 16384 + (kg * 4) * 256 + (w * 16 + l16) * 2);
; #pragma unroll
;             for (int mt = 0; mt < 4; ++mt)
; #pragma unroll
;                 for (int rp = 0; rp < 2; ++rp) {
;                     const float h0 = aX[mt][2 * rp] + aA[mt][2 * rp] * start[mt], h1 = aX[mt][2 * rp + 1] + aA[mt][2 * rp + 1] * start[mt];
;                     const unsigned pk = cvt_pk_bf16(h0, h1);
;                     ob[(mt * 16 + 2 * rp) * 128] = (unsigned short)(pk & 0xffffu); ob[(mt * 16 + 2 * rp + 1) * 128] = (unsigned short)(pk >> 16);
;                 }
;         }
;         RNN_BAR();
	v_fmac_f32_e32 v61, v135, v60
	ds_bpermute_b32 v170, v130, v141
	ds_bpermute_b32 v171, v130, v84
	v_fmac_f32_e32 v63, v61, v62
	v_cndmask_b32_e64 v60, v131, v61, s[8:9]
	v_fmac_f32_e32 v147, v63, v145
	v_cndmask_b32_e64 v60, v60, v63, s[10:11]
	v_fmac_f32_e32 v165, v147, v164
	v_cndmask_b32_e64 v131, v60, v147, s[12:13]
	v_cndmask_b32_e64 v60, v132, v165, s[6:7]
	v_fmac_f32_e32 v167, v165, v166
	v_cndmask_b32_e64 v60, v60, v167, s[8:9]
	v_fmac_f32_e32 v169, v167, v168
	v_fmac_f32_e32 v100, v102, v98
	v_mul_f32_e32 v102, v102, v101
	ds_bpermute_b32 v172, v123, v141
	ds_bpermute_b32 v173, v123, v84
	v_cndmask_b32_e64 v60, v60, v169, s[10:11]
	s_waitcnt lgkmcnt(0)
	v_fmac_f32_e32 v171, v169, v170
	v_cndmask_b32_e64 v132, v60, v171, s[12:13]
	ds_bpermute_b32 v60, v128, v102
	ds_bpermute_b32 v61, v128, v100
	ds_bpermute_b32 v62, v129, v102
	ds_bpermute_b32 v63, v129, v100
	ds_bpermute_b32 v145, v130, v102
	ds_bpermute_b32 v147, v130, v100
	v_fmac_f32_e32 v173, v171, v172
	v_cndmask_b32_e64 v133, v133, v173, s[6:7]
	s_waitcnt lgkmcnt(0)
	v_fmac_f32_e32 v61, v173, v60
	s_xor_b32 s17, s16, 0x4000
	v_cndmask_b32_e64 v60, v133, v61, s[8:9]
	v_fmac_f32_e32 v63, v61, v62
	s_add_i32 s17, s17, 0
	v_cndmask_b32_e64 v60, v60, v63, s[10:11]
	v_fmac_f32_e32 v147, v63, v145
	s_add_i32 s17, s17, 0x11800
	v_fmac_f32_e32 v96, v2, v1
	v_mul_f32_e32 v2, v3, v2
	v_cndmask_b32_e64 v133, v60, v147, s[12:13]
	v_add_u32_e32 v60, s17, v113
	v_fma_f32 v95, v93, v96, v95
	v_mul_f32_e32 v93, v93, v2
	ds_read_b128 v[60:63], v60
	v_fmac_f32_e32 v94, v92, v95
	v_mul_f32_e32 v92, v92, v93
	ds_bpermute_b32 v164, v123, v102
	ds_bpermute_b32 v165, v123, v100
	ds_bpermute_b32 v166, v128, v92
	ds_bpermute_b32 v167, v128, v94
	ds_bpermute_b32 v168, v129, v92
	ds_bpermute_b32 v169, v129, v94
	ds_bpermute_b32 v170, v130, v92
	ds_bpermute_b32 v171, v130, v94
	s_waitcnt lgkmcnt(0)
	global_store_dwordx4 v[90:91], v[60:63], off
	v_fmac_f32_e32 v165, v147, v164
	v_cndmask_b32_e64 v134, v134, v165, s[6:7]
	v_add_u32_e32 v60, s17, v121
	ds_read_b128 v[60:63], v60
	v_fmac_f32_e32 v167, v165, v166
	v_cndmask_b32_e64 v134, v134, v167, s[8:9]
	v_fmac_f32_e32 v169, v167, v168
	v_cndmask_b32_e64 v134, v134, v169, s[10:11]
	v_fmac_f32_e32 v171, v169, v170
	v_cndmask_b32_e64 v134, v134, v171, s[12:13]
	ds_bpermute_b32 v135, v123, v94
	s_waitcnt lgkmcnt(0)
	global_store_dwordx4 v[88:89], v[60:63], off
	v_fmac_f32_e32 v94, v92, v134
	v_fmac_f32_e32 v95, v93, v134
	v_add_u32_e32 v60, s16, v124
	v_cvt_pk_bf16_f32 v61, v94, v95
	v_fmac_f32_e32 v1, v3, v134
	ds_write_b16 v60, v61
	ds_write_b16_d16_hi v60, v61 offset:256
	v_fmac_f32_e32 v96, v2, v134
	v_cvt_pk_bf16_f32 v1, v96, v1
	ds_write_b16 v60, v1 offset:512
	ds_write_b16_d16_hi v60, v1 offset:768
	v_fmac_f32_e32 v100, v102, v133
	v_fmac_f32_e32 v98, v101, v133
	v_cvt_pk_bf16_f32 v1, v100, v98
	ds_write_b16 v60, v1 offset:4096
	ds_write_b16_d16_hi v60, v1 offset:4352
	v_fmac_f32_e32 v68, v97, v133
	v_fmac_f32_e32 v69, v99, v133
	v_cvt_pk_bf16_f32 v1, v68, v69
	ds_write_b16 v60, v1 offset:4608
	ds_write_b16_d16_hi v60, v1 offset:4864
	v_fmac_f32_e32 v84, v141, v132
	v_fmac_f32_e32 v85, v103, v132
	v_cvt_pk_bf16_f32 v1, v84, v85
	ds_write_b16 v60, v1 offset:8192
	ds_write_b16_d16_hi v60, v1 offset:8448
	v_fmac_f32_e32 v86, v70, v132
	v_fmac_f32_e32 v87, v71, v132
	v_cvt_pk_bf16_f32 v1, v86, v87
	ds_bpermute_b32 v172, v123, v92
	ds_write_b16 v60, v1 offset:8704
	ds_write_b16_d16_hi v60, v1 offset:8960
	v_fmac_f32_e32 v144, v64, v131
	v_fmac_f32_e32 v143, v65, v131
	v_cvt_pk_bf16_f32 v1, v144, v143
	ds_write_b16 v60, v1 offset:12288
	ds_write_b16_d16_hi v60, v1 offset:12544
	v_fmac_f32_e32 v146, v66, v131
	v_fmac_f32_e32 v142, v67, v131
	v_cvt_pk_bf16_f32 v1, v146, v142
	ds_write_b16 v60, v1 offset:12800
	ds_write_b16_d16_hi v60, v1 offset:13056
	s_waitcnt lgkmcnt(0)
	s_barrier
	s_mov_b32 s16, 0xfffe0000
	s_mov_b32 s17, -1
	s_waitcnt lgkmcnt(0)
	v_fmac_f32_e32 v135, v171, v172
	v_lshl_add_u64 v[88:89], v[88:89], 0, s[16:17]
	v_lshl_add_u64 v[90:91], v[90:91], 0, s[16:17]
	s_cmp_lg_u32 s19, 0xfc870000
	s_cbranch_scc0 .LBB0_554

; #define LAS __attribute__((address_space(3)))
; template <int DIR>
; __device__ __forceinline__ void rnn_item(LAS unsigned char* lds, const bf16_t* proj, bf16_t* hout, int hpitch, int layer, int s, int n) {
;     ...
; #pragma unroll
;         for (int ks = 0; ks < 4; ++ks)
; #pragma unroll
;             for (int mt = 0; mt < 4; ++mt) {
;                 const bf16x8 af = *(const LAS bf16x8*)(At + buf * 17408 + (mt * 16 + l16) * 272 + ks * 64 + kg * 16);
;                 aA[mt] = __builtin_amdgcn_mfma_f32_16x16x32_bf16(af, bfr[0][ks], aA[mt], 0, 0, 0);
;                 aX[mt] = __builtin_amdgcn_mfma_f32_16x16x32_bf16(af, bfr[1][ks], aX[mt], 0, 0, 0);
;             }
.LBB0_609:
	s_or_b64 exec, exec, s[16:17]
	s_xor_b32 s16, s34, 1
	s_mul_i32 s17, s16, 0x4300
	v_add_u32_e32 v1, s17, v107
	ds_read_b128 v[64:67], v1
	ds_read_b128 v[68:71], v1 offset:256
	ds_read_b128 v[84:87], v1 offset:512
	ds_read_b128 v[92:95], v1 offset:768
	ds_read_b128 v[60:63], v1 offset:1024
	ds_read_b128 v[96:99], v120
	ds_read_b128 v[100:103], v120 offset:16
	ds_read_b128 v[142:145], v120 offset:512
	ds_read_b128 v[164:167], v120 offset:528
	ds_read_b128 v[168:171], v120 offset:1024
	ds_read_b128 v[204:207], v120 offset:1040
	ds_read_b128 v[172:175], v120 offset:1536
	ds_read_b128 v[192:195], v120 offset:1552
	ds_read_b128 v[196:199], v120 offset:2048
	ds_read_b128 v[200:203], v120 offset:2064
	s_mulk_i32 s16, 0x4400
	v_add_u32_e32 v2, s16, v112
	s_mul_i32 s16, s34, 0x4400
	v_cndmask_b32_e64 v132, v132, v136, s[6:7]
	s_add_i32 s31, s31, 1
	s_add_i32 s19, s19, 0x38000
	s_add_i32 s30, s30, 64
	s_waitcnt lgkmcnt(0)
	v_lshlrev_b32_e32 v208, 16, v64
	v_and_b32_e32 v209, 0xffff0000, v64
	v_lshlrev_b32_e32 v210, 16, v68
	v_and_b32_e32 v211, 0xffff0000, v68
	v_lshlrev_b32_e32 v212, 16, v84
	v_and_b32_e32 v213, 0xffff0000, v84
	v_lshlrev_b32_e32 v214, 16, v92
	v_and_b32_e32 v215, 0xffff0000, v92
	v_lshlrev_b32_e32 v216, 16, v60
	v_and_b32_e32 v217, 0xffff0000, v60
	v_fma_f32 v218, v96, v208, v196
	v_fmac_f32_e32 v218, v142, v210
	v_fmac_f32_e32 v218, v168, v212
	v_fmac_f32_e32 v218, v172, v214
	v_fma_f32 v226, v96, v210, v196
	v_fmac_f32_e32 v226, v142, v212
	v_fmac_f32_e32 v226, v168, v214
	v_fmac_f32_e32 v226, v172, v216
	v_fma_f32 v219, v97, v209, v197
	v_fmac_f32_e32 v219, v143, v211
	v_fmac_f32_e32 v219, v169, v213
	v_fmac_f32_e32 v219, v173, v215
	v_fma_f32 v227, v97, v211, v197
	v_fmac_f32_e32 v227, v143, v213
	v_fmac_f32_e32 v227, v169, v215
	v_fmac_f32_e32 v227, v173, v217
	v_lshlrev_b32_e32 v208, 16, v65
	v_and_b32_e32 v209, 0xffff0000, v65
	v_lshlrev_b32_e32 v210, 16, v69
	v_and_b32_e32 v211, 0xffff0000, v69
	v_lshlrev_b32_e32 v212, 16, v85
	v_and_b32_e32 v213, 0xffff0000, v85
	v_lshlrev_b32_e32 v214, 16, v93
	v_and_b32_e32 v215, 0xffff0000, v93
	v_lshlrev_b32_e32 v216, 16, v61
	v_and_b32_e32 v217, 0xffff0000, v61
	v_fma_f32 v220, v98, v208, v198
	v_fmac_f32_e32 v220, v144, v210
	v_fmac_f32_e32 v220, v170, v212
	v_fmac_f32_e32 v220, v174, v214
	v_fma_f32 v228, v98, v210, v198
	v_fmac_f32_e32 v228, v144, v212
	v_fmac_f32_e32 v228, v170, v214
	v_fmac_f32_e32 v228, v174, v216
	v_fma_f32 v221, v99, v209, v199
	v_fmac_f32_e32 v221, v145, v211
	v_fmac_f32_e32 v221, v171, v213
	v_fmac_f32_e32 v221, v175, v215
	v_fma_f32 v229, v99, v211, v199
	v_fmac_f32_e32 v229, v145, v213
	v_fmac_f32_e32 v229, v171, v215
	v_fmac_f32_e32 v229, v175, v217
	v_lshlrev_b32_e32 v208, 16, v66
	v_and_b32_e32 v209, 0xffff0000, v66
	v_lshlrev_b32_e32 v210, 16, v70
	v_and_b32_e32 v211, 0xffff0000, v70
	v_lshlrev_b32_e32 v212, 16, v86
	v_and_b32_e32 v213, 0xffff0000, v86
	v_lshlrev_b32_e32 v214, 16, v94
	v_and_b32_e32 v215, 0xffff0000, v94
	v_lshlrev_b32_e32 v216, 16, v62
	v_and_b32_e32 v217, 0xffff0000, v62
	v_fma_f32 v222, v100, v208, v200
	v_fmac_f32_e32 v222, v164, v210
	v_fmac_f32_e32 v222, v204, v212
	v_fmac_f32_e32 v222, v192, v214
	v_fma_f32 v230, v100, v210, v200
	v_fmac_f32_e32 v230, v164, v212
	v_fmac_f32_e32 v230, v204, v214
	v_fmac_f32_e32 v230, v192, v216
	v_fma_f32 v223, v101, v209, v201
	v_fmac_f32_e32 v223, v165, v211
	v_fmac_f32_e32 v223, v205, v213
	v_fmac_f32_e32 v223, v193, v215
	v_fma_f32 v231, v101, v211, v201
	v_fmac_f32_e32 v231, v165, v213
	v_fmac_f32_e32 v231, v205, v215
	v_fmac_f32_e32 v231, v193, v217
	v_lshlrev_b32_e32 v208, 16, v67
	v_and_b32_e32 v209, 0xffff0000, v67
	v_lshlrev_b32_e32 v210, 16, v71
	v_and_b32_e32 v211, 0xffff0000, v71
	v_lshlrev_b32_e32 v212, 16, v87
	v_and_b32_e32 v213, 0xffff0000, v87
	v_lshlrev_b32_e32 v214, 16, v95
	v_and_b32_e32 v215, 0xffff0000, v95
	v_lshlrev_b32_e32 v216, 16, v63
	v_and_b32_e32 v217, 0xffff0000, v63
	v_fma_f32 v224, v102, v208, v202
	v_fmac_f32_e32 v224, v166, v210
	v_fmac_f32_e32 v224, v206, v212
	v_fmac_f32_e32 v224, v194, v214
	v_fma_f32 v232, v102, v210, v202
	v_fmac_f32_e32 v232, v166, v212
	v_fmac_f32_e32 v232, v206, v214
	v_fmac_f32_e32 v232, v194, v216
	v_fma_f32 v225, v103, v209, v203
	v_fmac_f32_e32 v225, v167, v211
	v_fmac_f32_e32 v225, v207, v213
	v_fmac_f32_e32 v225, v195, v215
	v_fma_f32 v233, v103, v211, v203
	v_fmac_f32_e32 v233, v167, v213
	v_fmac_f32_e32 v233, v207, v215
	v_fmac_f32_e32 v233, v195, v217
	v_cvt_pk_bf16_f32 v234, v218, v219
	v_cvt_pk_bf16_f32 v235, v220, v221
	v_cvt_pk_bf16_f32 v236, v222, v223
	v_cvt_pk_bf16_f32 v237, v224, v225
	v_cvt_pk_bf16_f32 v238, v226, v227
	v_cvt_pk_bf16_f32 v239, v228, v229
	v_cvt_pk_bf16_f32 v240, v230, v231
	v_cvt_pk_bf16_f32 v241, v232, v233
	ds_write_b128 v2, v[234:237] offset:34304
	ds_write_b128 v2, v[238:241] offset:34576
	v_add_u32_e32 v1, s16, v127
	ds_read_b128 v[60:63], v1 offset:34304
	ds_read_b128 v[64:67], v1 offset:34368
	ds_read_b128 v[84:87], v1 offset:38656
	ds_read_b128 v[92:95], v1 offset:38720
	ds_read_b128 v[100:103], v1 offset:43008
	ds_read_b128 v[142:145], v1 offset:43072
	ds_read_b128 v[168:171], v1 offset:47360
	ds_read_b128 v[172:175], v1 offset:47424
	ds_read_b128 v[204:207], v1 offset:34432
	ds_read_b128 v[208:211], v1 offset:34496
	ds_read_b128 v[212:215], v1 offset:38784
	ds_read_b128 v[216:219], v1 offset:38848
	ds_read_b128 v[220:223], v1 offset:43136
	ds_read_b128 v[224:227], v1 offset:43200
	ds_read_b128 v[228:231], v1 offset:47488
	ds_read_b128 v[232:235], v1 offset:47552
	s_waitcnt lgkmcnt(8)
; #define LAS __attribute__((address_space(3)))
; __device__ __forceinline__ float bf_1(bf16_t h) { return __uint_as_float(((unsigned)h) << 16); }
; template <int DIR>
; __device__ __forceinline__ void rnn_item(LAS unsigned char* lds, const bf16_t* proj, bf16_t* hout, int hpitch, int layer, int s, int n) {
;     ...
; #pragma unroll
;         for (int ks = 0; ks < 4; ++ks)
; #pragma unroll
;             for (int mt = 0; mt < 4; ++mt) {
;                 const bf16x8 af = *(const LAS bf16x8*)(At + buf * 17408 + (mt * 16 + l16) * 272 + ks * 64 + kg * 16);
;                 aA[mt] = __builtin_amdgcn_mfma_f32_16x16x32_bf16(af, bfr[0][ks], aA[mt], 0, 0, 0);
;                 aX[mt] = __builtin_amdgcn_mfma_f32_16x16x32_bf16(af, bfr[1][ks], aX[mt], 0, 0, 0);
;             }
;         {   typedef float f32x2 __attribute__((ext_vector_type(2)));
; #pragma unroll
;             for (int mt = 0; mt < 4; ++mt)
; #pragma unroll
;                 for (int rp = 0; rp < 2; ++rp) {
;                     const LAS unsigned char* xp = At + buf * 17408 + (mt * 16 + kg * 4 + 2 * rp) * 272 + (w * 16 + l16) * 2;
;                     const f32x2 xc = {bf_1(*(const LAS bf16_t*)xp), bf_1(*(const LAS bf16_t*)(xp + 272))};
;                     const f32x2 xa = {aA[mt][2 * rp], aA[mt][2 * rp + 1]}, xx = {aX[mt][2 * rp], aX[mt][2 * rp + 1]};
;                     f32x2 ta = xa * (-LOG2E) + nba, tx = xx * (-LOG2E) + nbx;
;                     ta.x = fminf(ta.x, 60.f); ta.y = fminf(ta.y, 60.f); tx.x = fminf(tx.x, 60.f); tx.y = fminf(tx.y, 60.f);
;                     f32x2 ea, ex; ea.x = __builtin_amdgcn_exp2f(ta.x); ea.y = __builtin_amdgcn_exp2f(ta.y); ex.x = __builtin_amdgcn_exp2f(tx.x); ex.y = __builtin_amdgcn_exp2f(tx.y);
;                     const f32x2 da = ea + 1.0f, dx = ex + 1.0f, dd = da * dx;
;                     f32x2 inv; inv.x = __builtin_amdgcn_rcpf(dd.x); inv.y = __builtin_amdgcn_rcpf(dd.y);
;                     const f32x2 rr = dx * inv, ii = da * inv, tt = rr * clam2;
	v_mfma_f32_16x16x32_bf16 v[68:71], v[60:63], v[4:7], 0
	v_mfma_f32_16x16x32_bf16 v[60:63], v[60:63], v[20:23], 0
	v_mfma_f32_16x16x32_bf16 v[96:99], v[84:87], v[4:7], 0
	v_mfma_f32_16x16x32_bf16 v[84:87], v[84:87], v[20:23], 0
	v_mfma_f32_16x16x32_bf16 v[164:167], v[100:103], v[4:7], 0
	v_mfma_f32_16x16x32_bf16 v[100:103], v[100:103], v[20:23], 0
	v_mfma_f32_16x16x32_bf16 v[192:195], v[168:171], v[4:7], 0
	v_mfma_f32_16x16x32_bf16 v[168:171], v[168:171], v[20:23], 0
	v_mfma_f32_16x16x32_bf16 v[68:71], v[64:67], v[8:11], v[68:71]
	v_mfma_f32_16x16x32_bf16 v[60:63], v[64:67], v[24:27], v[60:63]
	v_mfma_f32_16x16x32_bf16 v[64:67], v[92:95], v[8:11], v[96:99]
	v_mfma_f32_16x16x32_bf16 v[84:87], v[92:95], v[24:27], v[84:87]
	v_mfma_f32_16x16x32_bf16 v[92:95], v[142:145], v[8:11], v[164:167]
	v_mfma_f32_16x16x32_bf16 v[96:99], v[142:145], v[24:27], v[100:103]
	v_mfma_f32_16x16x32_bf16 v[142:145], v[172:175], v[24:27], v[168:171]
	s_nop 0
	s_nop 0
	v_mfma_f32_16x16x32_bf16 v[100:103], v[172:175], v[8:11], v[192:195]
	s_waitcnt lgkmcnt(0)
	v_mfma_f32_16x16x32_bf16 v[68:71], v[204:207], v[12:15], v[68:71]
	v_mfma_f32_16x16x32_bf16 v[60:63], v[204:207], v[28:31], v[60:63]
	s_waitcnt lgkmcnt(0)
	v_mfma_f32_16x16x32_bf16 v[64:67], v[212:215], v[12:15], v[64:67]
	v_mfma_f32_16x16x32_bf16 v[84:87], v[212:215], v[28:31], v[84:87]
	s_waitcnt lgkmcnt(0)
	v_mfma_f32_16x16x32_bf16 v[92:95], v[220:223], v[12:15], v[92:95]
	v_mfma_f32_16x16x32_bf16 v[96:99], v[220:223], v[28:31], v[96:99]
	s_waitcnt lgkmcnt(0)
	v_mfma_f32_16x16x32_bf16 v[100:103], v[228:231], v[12:15], v[100:103]
	v_mfma_f32_16x16x32_bf16 v[142:145], v[228:231], v[28:31], v[142:145]
	v_mfma_f32_16x16x32_bf16 v[164:167], v[208:211], v[16:19], v[68:71]
	v_mfma_f32_16x16x32_bf16 v[168:171], v[208:211], v[32:35], v[60:63]
	v_mfma_f32_16x16x32_bf16 v[200:203], v[216:219], v[16:19], v[64:67]
	s_nop 5
	v_fma_f32 v2, -v164, s50, v114
	v_fma_f32 v3, -v165, s50, v115
	v_pk_fma_f32 v[60:61], v[168:169], s[50:51], v[116:117] op_sel_hi:[1,0,1] neg_lo:[1,0,0] neg_hi:[1,0,0]
	v_min_f32_e32 v1, 0x42700000, v2
	v_min_f32_e32 v3, 0x42700000, v3
	v_min_f32_e32 v60, 0x42700000, v60
	v_min_f32_e32 v61, 0x42700000, v61
	v_exp_f32_e32 v2, v1
	v_exp_f32_e32 v3, v3
	v_exp_f32_e32 v64, v60
	v_exp_f32_e32 v65, v61
	v_mfma_f32_16x16x32_bf16 v[68:71], v[224:227], v[16:19], v[92:95]
	v_add_u32_e32 v1, s16, v126
	s_lshl_b32 s16, s34, 14
	s_xor_b32 s17, s16, 0x4000
	v_pk_add_f32 v[92:93], v[2:3], 1.0 op_sel_hi:[1,0]
	v_pk_add_f32 v[2:3], v[64:65], 1.0 op_sel_hi:[1,0]
	v_mfma_f32_16x16x32_bf16 v[172:175], v[216:219], v[32:35], v[84:87]
	v_mul_f32_e64 v64, v2, v92
	v_mul_f32_e64 v65, v3, v93
	v_pk_fma_f32 v[68:69], v[68:69], s[50:51], v[114:115] op_sel_hi:[1,0,1] neg_lo:[1,0,0] neg_hi:[1,0,0]
	v_rcp_f32_e32 v94, v64
	v_rcp_f32_e32 v95, v65
	v_mfma_f32_16x16x32_bf16 v[84:87], v[224:227], v[32:35], v[96:99]
	v_min_f32_e32 v68, 0x42700000, v68
	v_min_f32_e32 v69, 0x42700000, v69
	v_pk_mul_f32 v[2:3], v[2:3], v[94:95]
	v_mfma_f32_16x16x32_bf16 v[60:63], v[232:235], v[16:19], v[100:103]
	v_mul_f32_e64 v2, v118, v2
	v_mul_f32_e64 v3, v119, v3
	v_pk_fma_f32 v[98:99], v[166:167], s[50:51], v[114:115] op_sel_hi:[1,0,1] neg_lo:[1,0,0] neg_hi:[1,0,0]
	v_exp_f32_e32 v2, v2
	v_pk_fma_f32 v[100:101], v[170:171], s[50:51], v[116:117] op_sel_hi:[1,0,1] neg_lo:[1,0,0] neg_hi:[1,0,0]
	v_exp_f32_e32 v3, v3
	v_min_f32_e32 v98, 0x42700000, v98
	v_min_f32_e32 v99, 0x42700000, v99
	v_min_f32_e32 v100, 0x42700000, v100
	v_min_f32_e32 v101, 0x42700000, v101
	v_exp_f32_e32 v98, v98
	v_exp_f32_e32 v99, v99
	v_exp_f32_e32 v100, v100
	v_exp_f32_e32 v101, v101
	v_pk_mul_f32 v[92:93], v[92:93], v[94:95]
	v_pk_fma_f32 v[94:95], v[2:3], v[2:3], 1.0 op_sel_hi:[1,1,0] neg_lo:[1,0,0] neg_hi:[1,0,0]
	v_mfma_f32_16x16x32_bf16 v[64:67], v[232:235], v[32:35], v[142:145]
	ds_read_u16 v96, v1 offset:34304
	ds_read_u16 v97, v1 offset:34576
	ds_read_u16 v141, v1 offset:34848
	ds_read_u16 v144, v1 offset:35120
	ds_read_u16 v164, v1 offset:38656
	ds_read_u16 v165, v1 offset:38928
	ds_read_u16 v168, v1 offset:39200
	ds_read_u16 v169, v1 offset:39472
	v_max_f32_e32 v142, 0, v94
	v_max_f32_e32 v143, 0, v95
	v_pk_add_f32 v[94:95], v[98:99], 1.0 op_sel_hi:[1,0]
	v_pk_add_f32 v[98:99], v[100:101], 1.0 op_sel_hi:[1,0]
	s_waitcnt lgkmcnt(0)
; #define LAS __attribute__((address_space(3)))
; __device__ __forceinline__ float bf_1(bf16_t h) { return __uint_as_float(((unsigned)h) << 16); }
; template <int DIR>
; __device__ __forceinline__ void rnn_item(LAS unsigned char* lds, const bf16_t* proj, bf16_t* hout, int hpitch, int layer, int s, int n) {
;     ...
;                     const LAS unsigned char* xp = At + buf * 17408 + (mt * 16 + kg * 4 + 2 * rp) * 272 + (w * 16 + l16) * 2;
;                     const f32x2 xc = {bf_1(*(const LAS bf16_t*)xp), bf_1(*(const LAS bf16_t*)(xp + 272))};
;                     const f32x2 xa = {aA[mt][2 * rp], aA[mt][2 * rp + 1]}, xx = {aX[mt][2 * rp], aX[mt][2 * rp + 1]};
;                     f32x2 ta = xa * (-LOG2E) + nba, tx = xx * (-LOG2E) + nbx;
;                     ta.x = fminf(ta.x, 60.f); ta.y = fminf(ta.y, 60.f); tx.x = fminf(tx.x, 60.f); tx.y = fminf(tx.y, 60.f);
;                     f32x2 ea, ex; ea.x = __builtin_amdgcn_exp2f(ta.x); ea.y = __builtin_amdgcn_exp2f(ta.y); ex.x = __builtin_amdgcn_exp2f(tx.x); ex.y = __builtin_amdgcn_exp2f(tx.y);
;                     const f32x2 da = ea + 1.0f, dx = ex + 1.0f, dd = da * dx;
;                     f32x2 inv; inv.x = __builtin_amdgcn_rcpf(dd.x); inv.y = __builtin_amdgcn_rcpf(dd.y);
;                     const f32x2 rr = dx * inv, ii = da * inv, tt = rr * clam2;
;                     f32x2 av; av.x = __builtin_amdgcn_exp2f(tt.x); av.y = __builtin_amdgcn_exp2f(tt.y);
;                     f32x2 om = 1.0f - av * av; om.x = fmaxf(om.x, 0.f); om.y = fmaxf(om.y, 0.f);
;                     f32x2 sq; sq.x = __builtin_amdgcn_sqrtf(om.x); sq.y = __builtin_amdgcn_sqrtf(om.y);
;                     const f32x2 bv = sq * (ii * xc);
;                     aA[mt][2 * rp] = av.x; aA[mt][2 * rp + 1] = av.y; aX[mt][2 * rp] = bv.x; aX[mt][2 * rp + 1] = bv.y;
;                 }
	v_lshlrev_b32_e32 v96, 16, v96
	v_pk_mul_f32 v[100:101], v[98:99], v[94:95]
	v_lshlrev_b32_e32 v97, 16, v97
	v_rcp_f32_e32 v102, v100
	v_rcp_f32_e32 v103, v101
	v_pk_mul_f32 v[92:93], v[92:93], v[96:97]
	v_sqrt_f32_e32 v142, v142
	v_sqrt_f32_e32 v143, v143
	v_pk_mul_f32 v[96:97], v[98:99], v[102:103]
	v_pk_mul_f32 v[94:95], v[94:95], v[102:103]
	v_pk_mul_f32 v[96:97], v[118:119], v[96:97]
	v_pk_mul_f32 v[92:93], v[92:93], v[142:143]
	v_exp_f32_e32 v100, v96
	v_exp_f32_e32 v101, v97
	v_lshlrev_b32_e32 v96, 16, v141
	v_pk_fma_f32 v[142:143], v[172:173], s[50:51], v[116:117] op_sel_hi:[1,0,1] neg_lo:[1,0,0] neg_hi:[1,0,0]
	v_lshlrev_b32_e32 v97, 16, v144
	v_pk_fma_f32 v[98:99], v[100:101], v[100:101], 1.0 op_sel_hi:[1,1,0] neg_lo:[1,0,0] neg_hi:[1,0,0]
	v_min_f32_e32 v142, 0x42700000, v142
	v_max_f32_e32 v141, 0, v98
	v_max_f32_e32 v145, 0, v99
	v_pk_fma_f32 v[98:99], v[200:201], s[50:51], v[114:115] op_sel_hi:[1,0,1] neg_lo:[1,0,0] neg_hi:[1,0,0]
	v_min_f32_e32 v143, 0x42700000, v143
	v_min_f32_e32 v98, 0x42700000, v98
	v_min_f32_e32 v99, 0x42700000, v99
	v_exp_f32_e32 v98, v98
	v_exp_f32_e32 v99, v99
	v_exp_f32_e32 v142, v142
	v_exp_f32_e32 v143, v143
	v_sqrt_f32_e32 v144, v141
	v_pk_add_f32 v[98:99], v[98:99], 1.0 op_sel_hi:[1,0]
	v_sqrt_f32_e32 v145, v145
	v_pk_add_f32 v[142:143], v[142:143], 1.0 op_sel_hi:[1,0]
	v_pk_mul_f32 v[94:95], v[94:95], v[96:97]
	v_pk_mul_f32 v[146:147], v[142:143], v[98:99]
	v_pk_mul_f32 v[96:97], v[94:95], v[144:145]
	v_rcp_f32_e32 v146, v146
	v_rcp_f32_e32 v147, v147
	v_pk_fma_f32 v[144:145], v[202:203], s[50:51], v[114:115] op_sel_hi:[1,0,1] neg_lo:[1,0,0] neg_hi:[1,0,0]
	v_pk_fma_f32 v[84:85], v[84:85], s[50:51], v[116:117] op_sel_hi:[1,0,1] neg_lo:[1,0,0] neg_hi:[1,0,0]
	v_min_f32_e32 v141, 0x42700000, v144
	v_pk_mul_f32 v[94:95], v[142:143], v[146:147]
	v_pk_mul_f32 v[98:99], v[98:99], v[146:147]
	v_pk_mul_f32 v[94:95], v[118:119], v[94:95]
	v_pk_fma_f32 v[146:147], v[174:175], s[50:51], v[116:117] op_sel_hi:[1,0,1] neg_lo:[1,0,0] neg_hi:[1,0,0]
	v_exp_f32_e32 v94, v94
	v_exp_f32_e32 v95, v95
	v_min_f32_e32 v145, 0x42700000, v145
	v_min_f32_e32 v146, 0x42700000, v146
	v_min_f32_e32 v147, 0x42700000, v147
	v_exp_f32_e32 v144, v141
	v_exp_f32_e32 v145, v145
	v_exp_f32_e32 v146, v146
	v_exp_f32_e32 v147, v147
	v_pk_fma_f32 v[142:143], v[94:95], v[94:95], 1.0 op_sel_hi:[1,1,0] neg_lo:[1,0,0] neg_hi:[1,0,0]
	v_min_f32_e32 v84, 0x42700000, v84
	v_min_f32_e32 v85, 0x42700000, v85
	v_lshlrev_b32_e32 v103, 16, v165
	v_max_f32_e32 v141, 0, v142
	v_max_f32_e32 v165, 0, v143
	v_pk_add_f32 v[142:143], v[144:145], 1.0 op_sel_hi:[1,0]
	v_pk_add_f32 v[144:145], v[146:147], 1.0 op_sel_hi:[1,0]
	v_exp_f32_e32 v68, v68
	v_exp_f32_e32 v69, v69
	v_exp_f32_e32 v84, v84
	v_exp_f32_e32 v85, v85
	v_pk_mul_f32 v[146:147], v[144:145], v[142:143]
	v_pk_add_f32 v[166:167], v[68:69], 1.0 op_sel_hi:[1,0]
	v_rcp_f32_e32 v146, v146
	v_rcp_f32_e32 v147, v147
	v_pk_add_f32 v[84:85], v[84:85], 1.0 op_sel_hi:[1,0]
	v_lshlrev_b32_e32 v102, 16, v164
	v_pk_mul_f32 v[68:69], v[84:85], v[166:167]
	v_pk_mul_f32 v[98:99], v[98:99], v[102:103]
	v_pk_mul_f32 v[102:103], v[144:145], v[146:147]
	v_lshlrev_b32_e32 v144, 16, v168
	v_lshlrev_b32_e32 v145, 16, v169
	v_rcp_f32_e32 v168, v68
	v_rcp_f32_e32 v169, v69
	v_pk_mul_f32 v[102:103], v[118:119], v[102:103]
	v_sqrt_f32_e32 v164, v141
	v_sqrt_f32_e32 v165, v165
	v_exp_f32_e32 v102, v102
	v_exp_f32_e32 v103, v103
	v_pk_mul_f32 v[84:85], v[84:85], v[168:169]
	v_pk_fma_f32 v[70:71], v[70:71], s[50:51], v[114:115] op_sel_hi:[1,0,1] neg_lo:[1,0,0] neg_hi:[1,0,0]
	v_pk_fma_f32 v[86:87], v[86:87], s[50:51], v[116:117] op_sel_hi:[1,0,1] neg_lo:[1,0,0] neg_hi:[1,0,0]
	v_pk_mul_f32 v[84:85], v[118:119], v[84:85]
	v_min_f32_e32 v70, 0x42700000, v70
	v_min_f32_e32 v71, 0x42700000, v71
	v_min_f32_e32 v86, 0x42700000, v86
	v_min_f32_e32 v87, 0x42700000, v87
	v_pk_mul_f32 v[98:99], v[98:99], v[164:165]
	v_pk_fma_f32 v[164:165], v[102:103], v[102:103], 1.0 op_sel_hi:[1,1,0] neg_lo:[1,0,0] neg_hi:[1,0,0]
	v_exp_f32_e32 v84, v84
	v_exp_f32_e32 v85, v85
	v_exp_f32_e32 v70, v70
	v_exp_f32_e32 v71, v71
	v_exp_f32_e32 v86, v86
	v_exp_f32_e32 v87, v87
	v_max_f32_e32 v141, 0, v164
	v_max_f32_e32 v165, 0, v165
	v_sqrt_f32_e32 v164, v141
	v_sqrt_f32_e32 v165, v165
	v_pk_mul_f32 v[68:69], v[142:143], v[146:147]
	ds_read_u16 v141, v1 offset:43008
	ds_read_u16 v143, v1 offset:43280
	ds_read_u16 v170, v1 offset:43552
	ds_read_u16 v171, v1 offset:43824
	ds_read_u16 v172, v1 offset:47360
	ds_read_u16 v173, v1 offset:47632
	ds_read_u16 v174, v1 offset:47904
	ds_read_u16 v1, v1 offset:48176
	v_pk_mul_f32 v[68:69], v[68:69], v[144:145]
	v_pk_fma_f32 v[144:145], v[84:85], v[84:85], 1.0 op_sel_hi:[1,1,0] neg_lo:[1,0,0] neg_hi:[1,0,0]
	v_pk_add_f32 v[146:147], v[70:71], 1.0 op_sel_hi:[1,0]
	v_pk_add_f32 v[86:87], v[86:87], 1.0 op_sel_hi:[1,0]
	v_pk_fma_f32 v[60:61], v[60:61], s[50:51], v[114:115] op_sel_hi:[1,0,1] neg_lo:[1,0,0] neg_hi:[1,0,0]
	v_pk_fma_f32 v[64:65], v[64:65], s[50:51], v[116:117] op_sel_hi:[1,0,1] neg_lo:[1,0,0] neg_hi:[1,0,0]
	s_waitcnt lgkmcnt(0)
; #define LAS __attribute__((address_space(3)))
; template <int DIR>
; __device__ __forceinline__ void rnn_item(LAS unsigned char* lds, const bf16_t* proj, bf16_t* hout, int hpitch, int layer, int s, int n) {
;     ...
;                     const LAS unsigned char* xp = At + buf * 17408 + (mt * 16 + kg * 4 + 2 * rp) * 272 + (w * 16 + l16) * 2;
;                     const f32x2 xc = {bf_1(*(const LAS bf16_t*)xp), bf_1(*(const LAS bf16_t*)(xp + 272))};
;                     const f32x2 xa = {aA[mt][2 * rp], aA[mt][2 * rp + 1]}, xx = {aX[mt][2 * rp], aX[mt][2 * rp + 1]};
;                     f32x2 ta = xa * (-LOG2E) + nba, tx = xx * (-LOG2E) + nbx;
;                     ta.x = fminf(ta.x, 60.f); ta.y = fminf(ta.y, 60.f); tx.x = fminf(tx.x, 60.f); tx.y = fminf(tx.y, 60.f);
;                     f32x2 ea, ex; ea.x = __builtin_amdgcn_exp2f(ta.x); ea.y = __builtin_amdgcn_exp2f(ta.y); ex.x = __builtin_amdgcn_exp2f(tx.x); ex.y = __builtin_amdgcn_exp2f(tx.y);
;                     const f32x2 da = ea + 1.0f, dx = ex + 1.0f, dd = da * dx;
;                     f32x2 inv; inv.x = __builtin_amdgcn_rcpf(dd.x); inv.y = __builtin_amdgcn_rcpf(dd.y);
;                     const f32x2 rr = dx * inv, ii = da * inv, tt = rr * clam2;
;                     f32x2 av; av.x = __builtin_amdgcn_exp2f(tt.x); av.y = __builtin_amdgcn_exp2f(tt.y);
;                     f32x2 om = 1.0f - av * av; om.x = fmaxf(om.x, 0.f); om.y = fmaxf(om.y, 0.f);
;                     f32x2 sq; sq.x = __builtin_amdgcn_sqrtf(om.x); sq.y = __builtin_amdgcn_sqrtf(om.y);
;                     const f32x2 bv = sq * (ii * xc);
;                     aA[mt][2 * rp] = av.x; aA[mt][2 * rp + 1] = av.y; aX[mt][2 * rp] = bv.x; aX[mt][2 * rp + 1] = bv.y;
;                 }
;         }
; #pragma unroll
;         for (int mt = 0; mt < 4; ++mt) {
;             float pp = 1.f, hh = 0.f;
; #pragma unroll
;             for (int q = 0; q < 4; ++q) { const int r = DIR == 0 ? q : 3 - q; hh = aA[mt][r] * hh + aX[mt][r]; pp *= aA[mt][r]; aA[mt][r] = pp; aX[mt][r] = hh; }
;         }
;         float start[4]; float carry = hcarry;
; #pragma unroll
;         for (int hq = 0; hq < 2; ++hq) {
;             float Ar[8], Br[8];
; #pragma unroll
;             for (int q8 = 0; q8 < 8; ++q8) { const int q = hq * 8 + q8; const int rho = DIR == 0 ? q : 15 - q; const int mt = rho >> 2, kgp = rho & 3; constexpr int re = DIR == 0 ? 3 : 0;
	v_lshlrev_b32_e32 v142, 16, v141
	v_max_f32_e32 v141, 0, v144
	v_max_f32_e32 v145, 0, v145
	v_pk_mul_f32 v[70:71], v[86:87], v[146:147]
	v_min_f32_e32 v60, 0x42700000, v60
	v_min_f32_e32 v61, 0x42700000, v61
	v_min_f32_e32 v64, 0x42700000, v64
	v_min_f32_e32 v65, 0x42700000, v65
	v_pk_mul_f32 v[68:69], v[68:69], v[164:165]
	v_sqrt_f32_e32 v144, v141
	v_sqrt_f32_e32 v145, v145
	v_rcp_f32_e32 v164, v70
	v_rcp_f32_e32 v165, v71
	v_exp_f32_e32 v60, v60
	v_exp_f32_e32 v61, v61
	v_exp_f32_e32 v64, v64
	v_exp_f32_e32 v65, v65
	v_lshlrev_b32_e32 v143, 16, v143
	v_pk_mul_f32 v[70:71], v[166:167], v[168:169]
	v_pk_fma_f32 v[62:63], v[62:63], s[50:51], v[114:115] op_sel_hi:[1,0,1] neg_lo:[1,0,0] neg_hi:[1,0,0]
	v_pk_mul_f32 v[70:71], v[70:71], v[142:143]
	v_pk_fma_f32 v[66:67], v[66:67], s[50:51], v[116:117] op_sel_hi:[1,0,1] neg_lo:[1,0,0] neg_hi:[1,0,0]
	v_pk_mul_f32 v[70:71], v[70:71], v[144:145]
	v_lshlrev_b32_e32 v142, 16, v170
	v_lshlrev_b32_e32 v143, 16, v171
	v_pk_mul_f32 v[144:145], v[146:147], v[164:165]
	v_pk_add_f32 v[60:61], v[60:61], 1.0 op_sel_hi:[1,0]
	v_pk_add_f32 v[64:65], v[64:65], 1.0 op_sel_hi:[1,0]
	v_min_f32_e32 v62, 0x42700000, v62
	v_min_f32_e32 v63, 0x42700000, v63
	v_min_f32_e32 v66, 0x42700000, v66
	v_min_f32_e32 v67, 0x42700000, v67
	v_pk_mul_f32 v[142:143], v[144:145], v[142:143]
	v_pk_mul_f32 v[144:145], v[64:65], v[60:61]
	v_exp_f32_e32 v62, v62
	v_exp_f32_e32 v63, v63
	v_exp_f32_e32 v66, v66
	v_exp_f32_e32 v67, v67
	v_rcp_f32_e32 v144, v144
	v_rcp_f32_e32 v145, v145
	v_pk_mul_f32 v[86:87], v[86:87], v[164:165]
	v_pk_add_f32 v[62:63], v[62:63], 1.0 op_sel_hi:[1,0]
	v_pk_mul_f32 v[86:87], v[118:119], v[86:87]
	v_pk_add_f32 v[66:67], v[66:67], 1.0 op_sel_hi:[1,0]
	v_exp_f32_e32 v86, v86
	v_exp_f32_e32 v87, v87
	v_pk_mul_f32 v[64:65], v[64:65], v[144:145]
	v_pk_mul_f32 v[164:165], v[66:67], v[62:63]
	v_pk_mul_f32 v[64:65], v[118:119], v[64:65]
	v_rcp_f32_e32 v164, v164
	v_rcp_f32_e32 v165, v165
	v_exp_f32_e32 v64, v64
	v_exp_f32_e32 v65, v65
	v_pk_fma_f32 v[146:147], v[86:87], v[86:87], 1.0 op_sel_hi:[1,1,0] neg_lo:[1,0,0] neg_hi:[1,0,0]
	v_pk_mul_f32 v[66:67], v[66:67], v[164:165]
	v_max_f32_e32 v141, 0, v146
	v_max_f32_e32 v147, 0, v147
	v_sqrt_f32_e32 v146, v141
	v_sqrt_f32_e32 v147, v147
	v_pk_mul_f32 v[60:61], v[60:61], v[144:145]
	v_pk_fma_f32 v[144:145], v[64:65], v[64:65], 1.0 op_sel_hi:[1,1,0] neg_lo:[1,0,0] neg_hi:[1,0,0]
	v_pk_mul_f32 v[66:67], v[118:119], v[66:67]
	v_max_f32_e32 v141, 0, v144
	v_max_f32_e32 v145, 0, v145
	v_exp_f32_e32 v66, v66
	v_exp_f32_e32 v67, v67
	v_sqrt_f32_e32 v144, v141
	v_sqrt_f32_e32 v145, v145
	v_pk_mul_f32 v[142:143], v[142:143], v[146:147]
	v_lshlrev_b32_e32 v146, 16, v172
	v_lshlrev_b32_e32 v147, 16, v173
	v_pk_mul_f32 v[60:61], v[60:61], v[146:147]
	v_pk_fma_f32 v[146:147], v[66:67], v[66:67], 1.0 op_sel_hi:[1,1,0] neg_lo:[1,0,0] neg_hi:[1,0,0]
	v_pk_mul_f32 v[144:145], v[60:61], v[144:145]
	v_max_f32_e32 v61, 0, v146
	v_max_f32_e32 v141, 0, v147
	v_sqrt_f32_e32 v146, v61
	v_sqrt_f32_e32 v147, v141
	v_lshlrev_b32_e32 v61, 16, v1
	v_fma_f32 v1, 0, v2, v92
	v_fmac_f32_e32 v93, v3, v1
	v_mul_f32_e32 v3, v2, v3
	v_lshlrev_b32_e32 v60, 16, v174
	v_pk_mul_f32 v[62:63], v[62:63], v[164:165]
	v_fma_f32 v92, v100, v93, v96
	v_mul_f32_e32 v96, v100, v3
	v_pk_mul_f32 v[60:61], v[62:63], v[60:61]
	v_fmac_f32_e32 v97, v101, v92
	v_mul_f32_e32 v100, v101, v96
	v_fma_f32 v98, 0, v94, v98
	v_pk_mul_f32 v[146:147], v[60:61], v[146:147]
	v_fmac_f32_e32 v99, v95, v98
	v_mul_f32_e32 v95, v94, v95
	v_fma_f32 v70, 0, v84, v70
	v_fma_f32 v141, 0, v64, v144
	ds_bpermute_b32 v60, v128, v100
	ds_bpermute_b32 v61, v128, v97
	v_fma_f32 v68, v102, v99, v68
	v_mul_f32_e32 v101, v102, v95
	v_fmac_f32_e32 v71, v85, v70
	v_fmac_f32_e32 v145, v65, v141
	ds_bpermute_b32 v62, v129, v100
	ds_bpermute_b32 v63, v129, v97
	v_fmac_f32_e32 v69, v103, v68
	v_mul_f32_e32 v102, v103, v101
	v_fma_f32 v103, v86, v71, v142
	v_fma_f32 v142, v66, v145, v146
	ds_bpermute_b32 v144, v130, v100
	ds_bpermute_b32 v146, v130, v97
	ds_bpermute_b32 v164, v131, v100
	ds_bpermute_b32 v165, v131, v97
	ds_bpermute_b32 v166, v128, v102
	ds_bpermute_b32 v167, v128, v69
	ds_bpermute_b32 v168, v129, v102
	ds_bpermute_b32 v169, v129, v69
	s_waitcnt lgkmcnt(0)
; #define LAS __attribute__((address_space(3)))
; __device__ __forceinline__ unsigned cvt_pk_bf16(float lo, float hi) { unsigned r; asm volatile("v_cvt_pk_bf16_f32 %0, %1, %2" : "=v"(r) : "v"(lo), "v"(hi)); return r; }
; #define RNN_BAR() do { asm volatile("s_waitcnt lgkmcnt(0)" ::: "memory"); __builtin_amdgcn_s_barrier(); asm volatile("" ::: "memory"); } while (0)
; template <int DIR>
; __device__ __forceinline__ void rnn_item(LAS unsigned char* lds, const bf16_t* proj, bf16_t* hout, int hpitch, int layer, int s, int n) {
;     ...
;             for (int q8 = 0; q8 < 8; ++q8) { const int q = hq * 8 + q8; const int rho = DIR == 0 ? q : 15 - q; const int mt = rho >> 2, kgp = rho & 3; constexpr int re = DIR == 0 ? 3 : 0;
;                 Ar[q8] = __shfl(aA[mt][re], l16 + 16 * kgp); Br[q8] = __shfl(aX[mt][re], l16 + 16 * kgp); }
; #pragma unroll
;             for (int q8 = 0; q8 < 8; ++q8) { const int q = hq * 8 + q8; const int rho = DIR == 0 ? q : 15 - q; const int mt = rho >> 2, kgp = rho & 3;
;                 if (kg == kgp) start[mt] = carry;
;                 carry = Ar[q8] * carry + Br[q8]; }
;         }
;         hcarry = carry;
;         if (it > 0) {
; #pragma unroll
;             for (int i = 0; i < 2; ++i) { const int c = tid + 512 * i; const u32x4 v = *(const LAS u32x4*)(OUTB + (buf ^ 1) * 16384 + c * 16);
;                 *(u32x4*)(hout + (seqbase + (size_t)(sub - stp) * 64 + (c >> 4)) * hpitch + n * 128 + (c & 15) * 8) = v; }
;         }
;         {   LAS unsigned short* ob = (LAS unsigned short*)(OUTB + buf * 16384 + (kg * 4) * 256 + (w * 16 + l16) * 2);
; #pragma unroll
;             for (int mt = 0; mt < 4; ++mt)
; #pragma unroll
;                 for (int rp = 0; rp < 2; ++rp) {
;                     const float h0 = aX[mt][2 * rp] + aA[mt][2 * rp] * start[mt], h1 = aX[mt][2 * rp + 1] + aA[mt][2 * rp + 1] * start[mt];
;                     const unsigned pk = cvt_pk_bf16(h0, h1);
;                     ob[(mt * 16 + 2 * rp) * 128] = (unsigned short)(pk & 0xffffu); ob[(mt * 16 + 2 * rp + 1) * 128] = (unsigned short)(pk >> 16);
;                 }
;         }
;         RNN_BAR();
	v_fmac_f32_e32 v61, v136, v60
	ds_bpermute_b32 v170, v130, v102
	ds_bpermute_b32 v171, v130, v69
	v_fmac_f32_e32 v63, v61, v62
	v_cndmask_b32_e64 v60, v132, v61, s[8:9]
	v_fmac_f32_e32 v146, v63, v144
	v_cndmask_b32_e64 v60, v60, v63, s[10:11]
	v_fmac_f32_e32 v165, v146, v164
	v_mul_f32_e32 v85, v84, v85
	v_cndmask_b32_e64 v132, v60, v146, s[12:13]
	v_cndmask_b32_e64 v60, v133, v165, s[6:7]
	v_fmac_f32_e32 v167, v165, v166
	v_mul_f32_e32 v86, v86, v85
	v_cndmask_b32_e64 v60, v60, v167, s[8:9]
	v_fmac_f32_e32 v169, v167, v168
	v_fmac_f32_e32 v143, v87, v103
	v_mul_f32_e32 v87, v87, v86
	ds_bpermute_b32 v172, v131, v102
	ds_bpermute_b32 v173, v131, v69
	v_cndmask_b32_e64 v60, v60, v169, s[10:11]
	s_waitcnt lgkmcnt(0)
	v_fmac_f32_e32 v171, v169, v170
	v_cndmask_b32_e64 v133, v60, v171, s[12:13]
	ds_bpermute_b32 v60, v128, v87
	ds_bpermute_b32 v61, v128, v143
	ds_bpermute_b32 v62, v129, v87
	ds_bpermute_b32 v63, v129, v143
	ds_bpermute_b32 v144, v130, v87
	ds_bpermute_b32 v146, v130, v143
	v_fmac_f32_e32 v173, v171, v172
	v_cndmask_b32_e64 v134, v134, v173, s[6:7]
	s_waitcnt lgkmcnt(0)
	v_fmac_f32_e32 v61, v173, v60
	v_cndmask_b32_e64 v60, v134, v61, s[8:9]
	v_fmac_f32_e32 v63, v61, v62
	s_add_i32 s17, s17, 0
	v_cndmask_b32_e64 v60, v60, v63, s[10:11]
	v_fmac_f32_e32 v146, v63, v144
	s_add_i32 s17, s17, 0x11800
	v_cndmask_b32_e64 v134, v60, v146, s[12:13]
	v_add_u32_e32 v60, s17, v113
	ds_read_b128 v[60:63], v60
	v_mul_f32_e32 v65, v64, v65
	v_mul_f32_e32 v66, v66, v65
	v_fmac_f32_e32 v147, v67, v142
	v_mul_f32_e32 v67, v67, v66
	s_waitcnt lgkmcnt(0)
	global_store_dwordx4 v[90:91], v[60:63], off
	ds_bpermute_b32 v164, v131, v87
	ds_bpermute_b32 v165, v131, v143
	v_add_u32_e32 v60, s17, v121
	ds_read_b128 v[60:63], v60
	ds_bpermute_b32 v166, v128, v67
	ds_bpermute_b32 v167, v128, v147
	ds_bpermute_b32 v168, v129, v67
	ds_bpermute_b32 v169, v129, v147
	ds_bpermute_b32 v170, v130, v67
	ds_bpermute_b32 v171, v130, v147
	v_fmac_f32_e32 v1, v2, v132
	s_waitcnt lgkmcnt(0)
	global_store_dwordx4 v[88:89], v[60:63], off
	v_fmac_f32_e32 v93, v3, v132
	v_cvt_pk_bf16_f32 v1, v1, v93
	v_fmac_f32_e32 v165, v146, v164
	v_add_u32_e32 v60, s16, v124
	ds_write_b16 v60, v1
	ds_write_b16_d16_hi v60, v1 offset:256
	v_fmac_f32_e32 v92, v96, v132
	v_fmac_f32_e32 v97, v100, v132
	v_cvt_pk_bf16_f32 v1, v92, v97
	v_cndmask_b32_e64 v135, v135, v165, s[6:7]
	v_fmac_f32_e32 v167, v165, v166
	ds_write_b16 v60, v1 offset:512
	ds_write_b16_d16_hi v60, v1 offset:768
	v_fmac_f32_e32 v98, v94, v133
	v_fmac_f32_e32 v99, v95, v133
	v_cvt_pk_bf16_f32 v1, v98, v99
	v_cndmask_b32_e64 v135, v135, v167, s[8:9]
	v_fmac_f32_e32 v169, v167, v168
	ds_write_b16 v60, v1 offset:4096
	ds_write_b16_d16_hi v60, v1 offset:4352
	v_fmac_f32_e32 v68, v101, v133
	v_fmac_f32_e32 v69, v102, v133
	v_cvt_pk_bf16_f32 v1, v68, v69
	v_cndmask_b32_e64 v135, v135, v169, s[10:11]
	v_fmac_f32_e32 v171, v169, v170
	ds_write_b16 v60, v1 offset:4608
	ds_write_b16_d16_hi v60, v1 offset:4864
	v_fmac_f32_e32 v70, v84, v134
	v_fmac_f32_e32 v71, v85, v134
	v_cvt_pk_bf16_f32 v1, v70, v71
	v_cndmask_b32_e64 v135, v135, v171, s[12:13]
	ds_write_b16 v60, v1 offset:8192
	ds_write_b16_d16_hi v60, v1 offset:8448
	v_fmac_f32_e32 v103, v86, v134
	v_fmac_f32_e32 v143, v87, v134
	v_cvt_pk_bf16_f32 v1, v103, v143
	ds_bpermute_b32 v172, v131, v67
	ds_bpermute_b32 v136, v131, v147
	ds_write_b16 v60, v1 offset:8704
	ds_write_b16_d16_hi v60, v1 offset:8960
	v_fmac_f32_e32 v141, v64, v135
	v_fmac_f32_e32 v145, v65, v135
	v_cvt_pk_bf16_f32 v1, v141, v145
	ds_write_b16 v60, v1 offset:12288
	ds_write_b16_d16_hi v60, v1 offset:12544
	v_fmac_f32_e32 v142, v66, v135
	v_fmac_f32_e32 v147, v67, v135
	v_cvt_pk_bf16_f32 v1, v142, v147
	ds_write_b16 v60, v1 offset:12800
	ds_write_b16_d16_hi v60, v1 offset:13056
	s_waitcnt lgkmcnt(0)
	s_barrier
	s_mov_b64 s[16:17], 0x70000
	s_waitcnt lgkmcnt(0)
	v_fmac_f32_e32 v136, v171, v172
	v_lshl_add_u64 v[88:89], v[88:89], 0, s[16:17]
	v_lshl_add_u64 v[90:91], v[90:91], 0, s[16:17]
	s_cmp_lg_u32 s19, 0x1bc8000
	s_cbranch_scc0 .LBB0_626

; #define LAS __attribute__((address_space(3)))
; __device__ __forceinline__ const float* PIN(int i) { return (const float*)KARG(i); }
; __device__ __forceinline__ unsigned char* PWS() { return (unsigned char*)KARG(24); }
; __device__ __forceinline__ int TID() { int t = threadIdx.x; asm volatile("" : "+v"(t)); return t; }
; __device__ __forceinline__ void phase_attn(LAS unsigned char* lds, bf16_t* proj, int layer, int nseq, unsigned* ctr) {
;     LAS int* slot = (LAS int*)(lds + LDS_BYTES - 16);
;     const int total = nseq * 256;
;     const float* biasG = (const float*)(PWS() + OFF_BIAS);
;     for (;;) {
;         __syncthreads();
;         if (TID() == 0) *slot = (int)atomicAdd(ctr, 1u);
;         __syncthreads();
;         const int idx = *slot;
;         if (idx >= total) break;
;         attn_unit(lds, proj, biasG, PIN(14) + layer * 8, idx >> 8, (idx >> 2) & 63, (idx >> 1) & 1, idx & 1);
.LBB0_651:
	s_waitcnt lgkmcnt(0)
	global_load_dwordx2 v[2:3], v[148:149], off offset:192 sc0 sc1
	s_waitcnt vmcnt(0)
	v_readfirstlane_b32 s3, v2
	v_readfirstlane_b32 s2, v3
	s_add_u32 s12, s3, 0x1000
	s_addc_u32 s13, s2, 0
	v_readlane_b32 s2, v254, 11
	v_readlane_b32 s3, v254, 12
	s_lshl_b32 s2, s2, 3
	s_ashr_i32 s3, s2, 31
	s_lshl_b64 s[16:17], s[2:3], 2
	v_readfirstlane_b32 s2, v178
	s_lshr_b32 s2, s2, 6
	s_cmp_ge_u32 s2, 4
	s_cbranch_scc0 .Lmy_prio_skip
	s_setprio 1

; __device__ __forceinline__ const float* PIN(int i) { return (const float*)KARG(i); }
; __device__ __forceinline__ int TID() { int t = threadIdx.x; asm volatile("" : "+v"(t)); return t; }
; __device__ __forceinline__ void phase_attn(LAS unsigned char* lds, bf16_t* proj, int layer, int nseq, unsigned* ctr) {
;     ...
;     for (;;) {
;         __syncthreads();
;         if (TID() == 0) *slot = (int)atomicAdd(ctr, 1u);
;         __syncthreads();
;         const int idx = *slot;
;         if (idx >= total) break;
;         attn_unit(lds, proj, biasG, PIN(14) + layer * 8, idx >> 8, (idx >> 2) & 63, (idx >> 1) & 1, idx & 1);
.LBB0_654:
	v_mov_b32_e32 v1, v178
	global_load_dwordx2 v[252:253], v[148:149], off offset:112 sc0 sc1
	s_barrier
	s_nop 0
	v_cmp_eq_u32_e32 vcc, 0, v1
	s_and_saveexec_b64 s[2:3], vcc
	s_cbranch_execz .LBB0_656
	v_mov_b64_e32 v[2:3], s[72:73]
	flat_atomic_add v1, v[2:3], v180 sc0
	v_readlane_b32 s4, v254, 3
	s_nop 1
	v_mov_b32_e32 v2, s4
	s_waitcnt vmcnt(0) lgkmcnt(0)
	ds_write_b32 v2, v1
.LBB0_656:
	s_or_b64 exec, exec, s[2:3]
	v_readlane_b32 s2, v254, 3
	s_waitcnt lgkmcnt(0)
	s_barrier
	v_mov_b32_e32 v1, s2
	ds_read_b32 v1, v1
	s_movk_i32 s2, 0x9ff
	s_waitcnt lgkmcnt(0)
	v_cmp_lt_i32_e32 vcc, s2, v1
	v_readfirstlane_b32 s6, v1
	s_mov_b64 s[2:3], -1
	s_cbranch_vccnz .LBB0_653
	s_bfe_u32 s7, s6, 0x10001
	s_lshl_b32 s3, s6, 1
	s_lshl_b32 s2, s7, 2
	s_and_b32 s3, s3, 2
	v_mov_b32_e32 v1, v178
	s_or_b32 s10, s2, s3
	s_movk_i32 s2, 0x202
	s_mov_b32 s61, 0x11848
	s_mov_b32 s60, 0x11844
	s_waitcnt vmcnt(0)
	v_readfirstlane_b32 s8, v253
	v_readfirstlane_b32 s9, v252
	v_cmp_gt_i32_e32 vcc, s2, v1
	s_and_saveexec_b64 s[2:3], vcc
	s_mov_b32 s31, 0x11800
	s_mov_b32 s40, 0x11804
	s_cbranch_execz .LBB0_660
	v_readlane_b32 s4, v254, 4
	v_mov_b32_e32 v3, v1
	s_nop 0
	v_lshl_add_u32 v2, v1, 2, s4
	s_mov_b64 s[4:5], 0

; __device__ __forceinline__ const float* PIN(int i) { return (const float*)KARG(i); }
; __device__ __forceinline__ int TID() { int t = threadIdx.x; asm volatile("" : "+v"(t)); return t; }
; __device__ __forceinline__ void phase_attn(LAS unsigned char* lds, bf16_t* proj, int layer, int nseq, unsigned* ctr) {
;     ...
;     for (;;) {
;         __syncthreads();
;         if (TID() == 0) *slot = (int)atomicAdd(ctr, 1u);
;         __syncthreads();
;         const int idx = *slot;
;         if (idx >= total) break;
;         attn_unit(lds, proj, biasG, PIN(14) + layer * 8, idx >> 8, (idx >> 2) & 63, (idx >> 1) & 1, idx & 1);
;     }
; }
.LBB0_800:
	s_setprio 0
	s_mov_b64 s[2:3], 0

; #define PG8_STAGE(bufoff, gbase, voff) do { _Pragma("unroll") for (int _i = 0; _i < 2; ++_i) \
;         __builtin_amdgcn_global_load_lds((const unsigned*)((const char*)(gbase) + (voff)[_i]), (LAS unsigned*)(lds + (bufoff) + ldsw + _i * 8192), 16, 0, 0); } while (0)
; #define PG8_LDA(dst, b, h) do { _Pragma("unroll") for (int m = 0; m < 4; ++m) _Pragma("unroll") for (int k = 0; k < 2; ++k) dst[m][k] = *(const LAS bf16x8*)(lds + PG8_SA(b, h) + aoff + m * 2048 + k * 1024); } while (0)
; #define PG8_LDB(dst, b, h) do { _Pragma("unroll") for (int n = 0; n < 2; ++n) _Pragma("unroll") for (int k = 0; k < 2; ++k) dst[n][k] = *(const LAS bf16x8*)(lds + PG8_SB(b, h) + boff + n * 2048 + k * 1024); } while (0)
; #define PG8_MMA(ai, bj, At, Bt) do { __builtin_amdgcn_s_setprio(3); _Pragma("unroll") for (int m = 0; m < 4; ++m) _Pragma("unroll") for (int n = 0; n < 2; ++n) _Pragma("unroll") for (int k = 0; k < 2; ++k) \
;         acc[ai][bj][m][n] = __builtin_amdgcn_mfma_f32_16x16x32_bf16(Bt[n][k], At[m][k], acc[ai][bj][m][n], 0, 0, 0); __builtin_amdgcn_s_setprio(0); } while (0)
; #define PG8_WAIT_V(n) asm volatile("s_waitcnt vmcnt(" #n ")" ::: "memory")
; #define PG8_WAIT_L(n) asm volatile("s_waitcnt lgkmcnt(" #n ")" ::: "memory")
; #define PG8_BAR __builtin_amdgcn_s_barrier()
; #define PG8_SCHED __builtin_amdgcn_sched_barrier(0)
;     ...
;         for (int t = 0; t < nt; t += 2) {
;             const bool last = (t == nt - 2);
;             const char* a1 = cA + (size_t)(t + 1) * kstep;
;             const char* a2 = last ? nA : cA + (size_t)(t + 2) * kstep; const char* b2 = last ? nB : cB + (size_t)(t + 2) * kstep;
;             const char* a3 = a2 + kstep; const char* b3 = b2 + kstep;
;             if constexpr (SP2) {
;             PG8_LDB(B0, 0, 0); PG8_LDB(B1, 0, 1); PG8_SCHED; PG8_LDA(At, 0, 0); PG8_STAGE(PG8_SA(1, 1), a1 + hstepA, voffA);
;             PG8_WAIT_V(8); PG8_WAIT_L(0); PG8_BAR; PG8_MMA(0, 0, At, B0); PG8_MMA(0, 1, At, B1); PG8_BAR; PG8_SCHED;
;     ...
; #pragma unroll
;         for (int a = 0; a < 2; ++a)
; #pragma unroll
;             for (int b = 0; b < 2; ++b)
; #pragma unroll
;                 for (int m = 0; m < 4; ++m)
; #pragma unroll
;                     for (int n = 0; n < 2; ++n) acc[a][b][m][n] = (f32x4){0.f, 0.f, 0.f, 0.f};
;         cur = nxt; cA = nA; cB = nB; ++ui;
.LBB0_810:
	s_ashr_i32 s11, s10, 31
	s_lshl_b64 s[12:13], s[10:11], 19
	s_add_u32 s12, s24, s12
	s_addc_u32 s13, s25, s13
	s_and_b64 s[16:17], s[2:3], exec
	s_cselect_b32 s11, s13, s77
	s_cselect_b32 s34, s12, s76
	s_ashr_i32 s9, s8, 31
	s_lshl_b64 s[16:17], s[8:9], 19
	s_add_u32 s16, s30, s16
	s_addc_u32 s17, s31, s17
	s_and_b64 s[60:61], s[2:3], exec
	s_cselect_b32 s9, s17, s75
	s_cselect_b32 s35, s16, s74
	s_add_u32 s42, s74, 0x100
	s_addc_u32 s60, s75, 0
	s_add_u32 s74, s76, 0x40080
	v_mov_b32_e32 v2, 0
	s_addc_u32 s75, s77, 0
	s_mov_b32 s61, -2
	v_mov_b32_e32 v3, v2
	v_mov_b32_e32 v4, v2
	v_mov_b32_e32 v5, v2
	v_mov_b32_e32 v6, v2
	v_mov_b32_e32 v7, v2
	v_mov_b32_e32 v8, v2
	v_mov_b32_e32 v9, v2
	v_mov_b32_e32 v18, v2
	v_mov_b32_e32 v19, v2
	v_mov_b32_e32 v20, v2
	v_mov_b32_e32 v21, v2
	v_mov_b32_e32 v22, v2
	v_mov_b32_e32 v23, v2
	v_mov_b32_e32 v24, v2
	v_mov_b32_e32 v25, v2
	v_mov_b32_e32 v34, v2
	v_mov_b32_e32 v35, v2
	v_mov_b32_e32 v36, v2
	v_mov_b32_e32 v37, v2
	v_mov_b32_e32 v38, v2
	v_mov_b32_e32 v39, v2
	v_mov_b32_e32 v40, v2
	v_mov_b32_e32 v41, v2
	v_mov_b32_e32 v50, v2
	v_mov_b32_e32 v51, v2
	v_mov_b32_e32 v52, v2
	v_mov_b32_e32 v53, v2
	v_mov_b32_e32 v54, v2
	v_mov_b32_e32 v55, v2
	v_mov_b32_e32 v56, v2
	v_mov_b32_e32 v57, v2
	v_mov_b32_e32 v10, v2
	v_mov_b32_e32 v11, v2
	v_mov_b32_e32 v12, v2
	v_mov_b32_e32 v13, v2
	v_mov_b32_e32 v14, v2
	v_mov_b32_e32 v15, v2
	v_mov_b32_e32 v16, v2
	v_mov_b32_e32 v17, v2
	v_mov_b32_e32 v26, v2
	v_mov_b32_e32 v27, v2
	v_mov_b32_e32 v28, v2
	v_mov_b32_e32 v29, v2
	v_mov_b32_e32 v30, v2
	v_mov_b32_e32 v31, v2
	v_mov_b32_e32 v32, v2
	v_mov_b32_e32 v33, v2
	v_mov_b32_e32 v42, v2
	v_mov_b32_e32 v43, v2
	v_mov_b32_e32 v44, v2
	v_mov_b32_e32 v45, v2
	v_mov_b32_e32 v46, v2
	v_mov_b32_e32 v47, v2
	v_mov_b32_e32 v48, v2
	v_mov_b32_e32 v49, v2
	v_mov_b32_e32 v58, v2
	v_mov_b32_e32 v59, v2
	v_mov_b32_e32 v60, v2
	v_mov_b32_e32 v61, v2
	v_mov_b32_e32 v62, v2
	v_mov_b32_e32 v63, v2
	v_mov_b32_e32 v64, v2
	v_mov_b32_e32 v65, v2
	v_mov_b32_e32 v66, v2
	v_mov_b32_e32 v67, v2
	v_mov_b32_e32 v68, v2
	v_mov_b32_e32 v69, v2
	v_mov_b32_e32 v70, v2
	v_mov_b32_e32 v71, v2
	v_mov_b32_e32 v72, v2
	v_mov_b32_e32 v73, v2
	v_mov_b32_e32 v82, v2
	v_mov_b32_e32 v83, v2
	v_mov_b32_e32 v84, v2
	v_mov_b32_e32 v85, v2
	v_mov_b32_e32 v86, v2
	v_mov_b32_e32 v87, v2
	v_mov_b32_e32 v88, v2
	v_mov_b32_e32 v89, v2
	v_mov_b32_e32 v98, v2
	v_mov_b32_e32 v99, v2
	v_mov_b32_e32 v100, v2
	v_mov_b32_e32 v101, v2
	v_mov_b32_e32 v102, v2
	v_mov_b32_e32 v103, v2
	v_mov_b32_e32 v104, v2
	v_mov_b32_e32 v105, v2
	v_mov_b32_e32 v114, v2
	v_mov_b32_e32 v115, v2
	v_mov_b32_e32 v116, v2
	v_mov_b32_e32 v117, v2
	v_mov_b32_e32 v118, v2
	v_mov_b32_e32 v119, v2
	v_mov_b32_e32 v120, v2
	v_mov_b32_e32 v121, v2
	v_mov_b32_e32 v74, v2
	v_mov_b32_e32 v75, v2
	v_mov_b32_e32 v76, v2
	v_mov_b32_e32 v77, v2
	v_mov_b32_e32 v78, v2
	v_mov_b32_e32 v79, v2
	v_mov_b32_e32 v80, v2
	v_mov_b32_e32 v81, v2
	v_mov_b32_e32 v90, v2
	v_mov_b32_e32 v91, v2
	v_mov_b32_e32 v92, v2
	v_mov_b32_e32 v93, v2
	v_mov_b32_e32 v94, v2
	v_mov_b32_e32 v95, v2
	v_mov_b32_e32 v96, v2
	v_mov_b32_e32 v97, v2
	v_mov_b32_e32 v106, v2
	v_mov_b32_e32 v107, v2
	v_mov_b32_e32 v108, v2
	v_mov_b32_e32 v109, v2
	v_mov_b32_e32 v110, v2
	v_mov_b32_e32 v111, v2
	v_mov_b32_e32 v112, v2
	v_mov_b32_e32 v113, v2
	v_mov_b32_e32 v122, v2
	v_mov_b32_e32 v123, v2
	v_mov_b32_e32 v124, v2
	v_mov_b32_e32 v125, v2
	v_mov_b32_e32 v126, v2
	v_mov_b32_e32 v127, v2
	v_mov_b32_e32 v128, v2
	v_mov_b32_e32 v129, v2
	s_waitcnt vmcnt(0)
.LBB0_811:
	s_add_u32 s73, s74, 0xfffc0080
	s_addc_u32 s76, s75, -1
	s_add_i32 s86, 0, 0x10000
	s_cmp_eq_u32 s61, 12
	s_cselect_b32 s79, s11, s76
	s_cselect_b32 s78, s34, s73
	v_add_u32_e32 v167, s86, v164
	s_cselect_b32 s77, s9, s60
	s_cselect_b32 s76, s35, s42
	s_add_i32 s73, 0, 0x14000
	ds_read_b128 v[144:147], v167
	ds_read_b128 v[168:171], v167 offset:1024
	ds_read_b128 v[172:175], v167 offset:2048
	ds_read_b128 v[192:195], v167 offset:3072
	v_add_u32_e32 v167, s73, v164
	ds_read_b128 v[196:199], v167
	ds_read_b128 v[200:203], v167 offset:1024
	ds_read_b128 v[204:207], v167 offset:2048
	ds_read_b128 v[208:211], v167 offset:3072
	v_lshl_add_u64 v[176:177], s[74:75], 0, v[142:143]
	s_add_i32 m0, s69, 0xc000
	ds_read_b128 v[212:215], v166
	ds_read_b128 v[216:219], v166 offset:1024
	ds_read_b128 v[220:223], v166 offset:2048
	ds_read_b128 v[224:227], v166 offset:3072
	ds_read_b128 v[228:231], v166 offset:4096
	ds_read_b128 v[232:235], v166 offset:5120
	ds_read_b128 v[236:239], v166 offset:6144
	ds_read_b128 v[240:243], v166 offset:7168
	global_load_lds_dwordx4 v[176:177], off
	v_lshl_add_u64 v[176:177], s[74:75], 0, v[140:141]
	s_add_i32 m0, s69, 0xe000
	s_nop 0
	global_load_lds_dwordx4 v[176:177], off
	s_waitcnt vmcnt(8)
	s_waitcnt lgkmcnt(0)
	s_barrier
; #define PG8_STAGE(bufoff, gbase, voff) do { _Pragma("unroll") for (int _i = 0; _i < 2; ++_i) \
;         __builtin_amdgcn_global_load_lds((const unsigned*)((const char*)(gbase) + (voff)[_i]), (LAS unsigned*)(lds + (bufoff) + ldsw + _i * 8192), 16, 0, 0); } while (0)
; #define PG8_LDA(dst, b, h) do { _Pragma("unroll") for (int m = 0; m < 4; ++m) _Pragma("unroll") for (int k = 0; k < 2; ++k) dst[m][k] = *(const LAS bf16x8*)(lds + PG8_SA(b, h) + aoff + m * 2048 + k * 1024); } while (0)
; #define PG8_LDB(dst, b, h) do { _Pragma("unroll") for (int n = 0; n < 2; ++n) _Pragma("unroll") for (int k = 0; k < 2; ++k) dst[n][k] = *(const LAS bf16x8*)(lds + PG8_SB(b, h) + boff + n * 2048 + k * 1024); } while (0)
; #define PG8_MMA(ai, bj, At, Bt) do { __builtin_amdgcn_s_setprio(3); _Pragma("unroll") for (int m = 0; m < 4; ++m) _Pragma("unroll") for (int n = 0; n < 2; ++n) _Pragma("unroll") for (int k = 0; k < 2; ++k) \
;         acc[ai][bj][m][n] = __builtin_amdgcn_mfma_f32_16x16x32_bf16(Bt[n][k], At[m][k], acc[ai][bj][m][n], 0, 0, 0); __builtin_amdgcn_s_setprio(0); } while (0)
; #define PG8_WAIT_V(n) asm volatile("s_waitcnt vmcnt(" #n ")" ::: "memory")
; #define PG8_WAIT_L(n) asm volatile("s_waitcnt lgkmcnt(" #n ")" ::: "memory")
; #define PG8_BAR __builtin_amdgcn_s_barrier()
; #define PG8_SCHED __builtin_amdgcn_sched_barrier(0)
;     ...
;             PG8_WAIT_V(8); PG8_WAIT_L(0); PG8_BAR; PG8_MMA(0, 0, At, B0); PG8_MMA(0, 1, At, B1); PG8_BAR; PG8_SCHED;
;             PG8_LDA(At, 0, 1); PG8_STAGE(PG8_SB(0, 0), b2, voffB); PG8_STAGE(PG8_SB(0, 1), b2 + hstepB, voffB); PG8_STAGE(PG8_SA(0, 0), a2, voffA);
;             PG8_WAIT_V(8); PG8_WAIT_L(0); PG8_BAR; PG8_MMA(1, 0, At, B0); PG8_MMA(1, 1, At, B1); PG8_BAR; PG8_SCHED;
;             PG8_LDB(B0, 1, 0); PG8_LDB(B1, 1, 1); PG8_SCHED; PG8_LDA(At, 1, 0); PG8_STAGE(PG8_SA(0, 1), a2 + hstepA, voffA);
	s_setprio 3
	s_waitcnt lgkmcnt(0)
	v_mfma_f32_16x16x32_bf16 v[126:129], v[144:147], v[212:215], v[126:129]
	v_mfma_f32_16x16x32_bf16 v[122:125], v[172:175], v[212:215], v[122:125]
	v_mfma_f32_16x16x32_bf16 v[110:113], v[144:147], v[220:223], v[110:113]
	v_mfma_f32_16x16x32_bf16 v[106:109], v[172:175], v[220:223], v[106:109]
	v_mfma_f32_16x16x32_bf16 v[94:97], v[144:147], v[228:231], v[94:97]
	v_mfma_f32_16x16x32_bf16 v[90:93], v[172:175], v[228:231], v[90:93]
	v_mfma_f32_16x16x32_bf16 v[78:81], v[144:147], v[236:239], v[78:81]
	v_mfma_f32_16x16x32_bf16 v[74:77], v[172:175], v[236:239], v[74:77]
	v_mfma_f32_16x16x32_bf16 v[126:129], v[168:171], v[216:219], v[126:129]
	v_mfma_f32_16x16x32_bf16 v[122:125], v[192:195], v[216:219], v[122:125]
	v_mfma_f32_16x16x32_bf16 v[110:113], v[168:171], v[224:227], v[110:113]
	v_mfma_f32_16x16x32_bf16 v[106:109], v[192:195], v[224:227], v[106:109]
	v_mfma_f32_16x16x32_bf16 v[94:97], v[168:171], v[232:235], v[94:97]
	v_mfma_f32_16x16x32_bf16 v[90:93], v[192:195], v[232:235], v[90:93]
	v_mfma_f32_16x16x32_bf16 v[78:81], v[168:171], v[240:243], v[78:81]
	v_mfma_f32_16x16x32_bf16 v[74:77], v[192:195], v[240:243], v[74:77]
	s_setprio 0
	s_setprio 3
	v_mfma_f32_16x16x32_bf16 v[118:121], v[196:199], v[212:215], v[118:121]
	v_mfma_f32_16x16x32_bf16 v[114:117], v[204:207], v[212:215], v[114:117]
	v_mfma_f32_16x16x32_bf16 v[102:105], v[196:199], v[220:223], v[102:105]
	v_mfma_f32_16x16x32_bf16 v[98:101], v[204:207], v[220:223], v[98:101]
	v_mfma_f32_16x16x32_bf16 v[86:89], v[196:199], v[228:231], v[86:89]
	v_mfma_f32_16x16x32_bf16 v[82:85], v[204:207], v[228:231], v[82:85]
	v_mfma_f32_16x16x32_bf16 v[70:73], v[196:199], v[236:239], v[70:73]
	v_mfma_f32_16x16x32_bf16 v[66:69], v[204:207], v[236:239], v[66:69]
	v_mfma_f32_16x16x32_bf16 v[118:121], v[200:203], v[216:219], v[118:121]
	v_mfma_f32_16x16x32_bf16 v[114:117], v[208:211], v[216:219], v[114:117]
	v_mfma_f32_16x16x32_bf16 v[102:105], v[200:203], v[224:227], v[102:105]
	v_mfma_f32_16x16x32_bf16 v[98:101], v[208:211], v[224:227], v[98:101]
	v_mfma_f32_16x16x32_bf16 v[86:89], v[200:203], v[232:235], v[86:89]
	v_mfma_f32_16x16x32_bf16 v[82:85], v[208:211], v[232:235], v[82:85]
	v_mfma_f32_16x16x32_bf16 v[70:73], v[200:203], v[240:243], v[70:73]
	v_mfma_f32_16x16x32_bf16 v[66:69], v[208:211], v[240:243], v[66:69]
	s_setprio 0
	s_barrier
	s_add_i32 s86, s86, s40
	v_lshl_add_u64 v[176:177], s[76:77], 0, v[134:135]
	s_mov_b32 m0, s86
	ds_read_b128 v[212:215], v166 offset:16384
	ds_read_b128 v[216:219], v166 offset:17408
	ds_read_b128 v[220:223], v166 offset:18432
	ds_read_b128 v[224:227], v166 offset:19456
	ds_read_b128 v[228:231], v166 offset:20480
	ds_read_b128 v[232:235], v166 offset:21504
	ds_read_b128 v[236:239], v166 offset:22528
	ds_read_b128 v[240:243], v166 offset:23552
	global_load_lds_dwordx4 v[176:177], off
	s_add_i32 m0, s86, 0x2000
	s_add_u32 s86, s76, 0x10000
	v_lshl_add_u64 v[244:245], s[76:77], 0, v[130:131]
	s_addc_u32 s87, s77, 0
	s_add_i32 s73, s73, s40
	global_load_lds_dwordx4 v[244:245], off
	v_lshl_add_u64 v[246:247], s[86:87], 0, v[134:135]
	s_mov_b32 m0, s73
	v_lshl_add_u64 v[248:249], s[78:79], 0, v[132:133]
	global_load_lds_dwordx4 v[246:247], off
	v_lshl_add_u64 v[246:247], s[86:87], 0, v[130:131]
	s_add_i32 m0, s73, 0x2000
	s_nop 0
	global_load_lds_dwordx4 v[246:247], off
	v_lshl_add_u64 v[246:247], s[78:79], 0, v[136:137]
	s_mov_b32 m0, s69
	s_nop 0
	global_load_lds_dwordx4 v[246:247], off
	s_mov_b32 m0, s70
	s_nop 0
	global_load_lds_dwordx4 v[248:249], off
	s_waitcnt vmcnt(8)
	s_waitcnt lgkmcnt(0)
	s_barrier
	s_setprio 3
	s_waitcnt lgkmcnt(0)
	v_mfma_f32_16x16x32_bf16 v[62:65], v[144:147], v[212:215], v[62:65]
	v_mfma_f32_16x16x32_bf16 v[58:61], v[172:175], v[212:215], v[58:61]
	v_mfma_f32_16x16x32_bf16 v[46:49], v[144:147], v[220:223], v[46:49]
	v_mfma_f32_16x16x32_bf16 v[42:45], v[172:175], v[220:223], v[42:45]
	v_mfma_f32_16x16x32_bf16 v[30:33], v[144:147], v[228:231], v[30:33]
	v_mfma_f32_16x16x32_bf16 v[26:29], v[172:175], v[228:231], v[26:29]
	v_mfma_f32_16x16x32_bf16 v[14:17], v[144:147], v[236:239], v[14:17]
	v_mfma_f32_16x16x32_bf16 v[10:13], v[172:175], v[236:239], v[10:13]
	v_mfma_f32_16x16x32_bf16 v[62:65], v[168:171], v[216:219], v[62:65]
	v_mfma_f32_16x16x32_bf16 v[58:61], v[192:195], v[216:219], v[58:61]
	v_mfma_f32_16x16x32_bf16 v[46:49], v[168:171], v[224:227], v[46:49]
	v_mfma_f32_16x16x32_bf16 v[42:45], v[192:195], v[224:227], v[42:45]
	v_mfma_f32_16x16x32_bf16 v[30:33], v[168:171], v[232:235], v[30:33]
	v_mfma_f32_16x16x32_bf16 v[26:29], v[192:195], v[232:235], v[26:29]
	v_mfma_f32_16x16x32_bf16 v[14:17], v[168:171], v[240:243], v[14:17]
	v_mfma_f32_16x16x32_bf16 v[10:13], v[192:195], v[240:243], v[10:13]
	s_setprio 0
	s_setprio 3
	v_mfma_f32_16x16x32_bf16 v[54:57], v[196:199], v[212:215], v[54:57]
	v_mfma_f32_16x16x32_bf16 v[50:53], v[204:207], v[212:215], v[50:53]
	v_mfma_f32_16x16x32_bf16 v[38:41], v[196:199], v[220:223], v[38:41]
	v_mfma_f32_16x16x32_bf16 v[34:37], v[204:207], v[220:223], v[34:37]
	v_mfma_f32_16x16x32_bf16 v[22:25], v[196:199], v[228:231], v[22:25]
	v_mfma_f32_16x16x32_bf16 v[18:21], v[204:207], v[228:231], v[18:21]
	v_mfma_f32_16x16x32_bf16 v[6:9], v[196:199], v[236:239], v[6:9]
	v_mfma_f32_16x16x32_bf16 v[2:5], v[204:207], v[236:239], v[2:5]
	v_mfma_f32_16x16x32_bf16 v[54:57], v[200:203], v[216:219], v[54:57]
	v_mfma_f32_16x16x32_bf16 v[50:53], v[208:211], v[216:219], v[50:53]
	v_mfma_f32_16x16x32_bf16 v[38:41], v[200:203], v[224:227], v[38:41]
	v_mfma_f32_16x16x32_bf16 v[34:37], v[208:211], v[224:227], v[34:37]
	v_mfma_f32_16x16x32_bf16 v[22:25], v[200:203], v[232:235], v[22:25]
	v_mfma_f32_16x16x32_bf16 v[18:21], v[208:211], v[232:235], v[18:21]
	v_mfma_f32_16x16x32_bf16 v[6:9], v[200:203], v[240:243], v[6:9]
	v_mfma_f32_16x16x32_bf16 v[2:5], v[208:211], v[240:243], v[2:5]
	s_setprio 0
	s_barrier
; #define PG8_STAGE(bufoff, gbase, voff) do { _Pragma("unroll") for (int _i = 0; _i < 2; ++_i) \
;         __builtin_amdgcn_global_load_lds((const unsigned*)((const char*)(gbase) + (voff)[_i]), (LAS unsigned*)(lds + (bufoff) + ldsw + _i * 8192), 16, 0, 0); } while (0)
; #define PG8_LDA(dst, b, h) do { _Pragma("unroll") for (int m = 0; m < 4; ++m) _Pragma("unroll") for (int k = 0; k < 2; ++k) dst[m][k] = *(const LAS bf16x8*)(lds + PG8_SA(b, h) + aoff + m * 2048 + k * 1024); } while (0)
; #define PG8_LDB(dst, b, h) do { _Pragma("unroll") for (int n = 0; n < 2; ++n) _Pragma("unroll") for (int k = 0; k < 2; ++k) dst[n][k] = *(const LAS bf16x8*)(lds + PG8_SB(b, h) + boff + n * 2048 + k * 1024); } while (0)
; #define PG8_MMA(ai, bj, At, Bt) do { __builtin_amdgcn_s_setprio(3); _Pragma("unroll") for (int m = 0; m < 4; ++m) _Pragma("unroll") for (int n = 0; n < 2; ++n) _Pragma("unroll") for (int k = 0; k < 2; ++k) \
;         acc[ai][bj][m][n] = __builtin_amdgcn_mfma_f32_16x16x32_bf16(Bt[n][k], At[m][k], acc[ai][bj][m][n], 0, 0, 0); __builtin_amdgcn_s_setprio(0); } while (0)
; #define PG8_WAIT_V(n) asm volatile("s_waitcnt vmcnt(" #n ")" ::: "memory")
; #define PG8_WAIT_L(n) asm volatile("s_waitcnt lgkmcnt(" #n ")" ::: "memory")
; #define PG8_BAR __builtin_amdgcn_s_barrier()
; #define PG8_SCHED __builtin_amdgcn_sched_barrier(0)
;     ...
;             PG8_LDB(B0, 1, 0); PG8_LDB(B1, 1, 1); PG8_SCHED; PG8_LDA(At, 1, 0); PG8_STAGE(PG8_SA(0, 1), a2 + hstepA, voffA);
;             PG8_WAIT_V(8); PG8_WAIT_L(0); PG8_BAR; PG8_MMA(0, 0, At, B0); PG8_MMA(0, 1, At, B1); PG8_BAR; PG8_SCHED;
;             PG8_LDA(At, 1, 1); PG8_STAGE(PG8_SB(1, 0), b3, voffB); PG8_STAGE(PG8_SB(1, 1), b3 + hstepB, voffB); PG8_STAGE(PG8_SA(1, 0), a3, voffA);
;             PG8_WAIT_V(8); PG8_WAIT_L(0); PG8_BAR; PG8_MMA(1, 0, At, B0); PG8_MMA(1, 1, At, B1); PG8_BAR; PG8_SCHED;
	s_add_i32 s73, 0, 0x18000
	v_add_u32_e32 v167, s73, v164
	s_add_i32 s86, 0, 0x1c000
	ds_read_b128 v[144:147], v167
	ds_read_b128 v[168:171], v167 offset:1024
	ds_read_b128 v[172:175], v167 offset:2048
	ds_read_b128 v[192:195], v167 offset:3072
	v_add_u32_e32 v167, s86, v164
	ds_read_b128 v[196:199], v167
	ds_read_b128 v[200:203], v167 offset:1024
	ds_read_b128 v[204:207], v167 offset:2048
	ds_read_b128 v[208:211], v167 offset:3072
	s_add_u32 s78, s78, 0x40000
	s_addc_u32 s79, s79, 0
	s_mov_b32 m0, s71
	v_lshl_add_u64 v[250:251], s[78:79], 0, v[136:137]
	ds_read_b128 v[212:215], v166 offset:32768
	ds_read_b128 v[216:219], v166 offset:33792
	ds_read_b128 v[220:223], v166 offset:34816
	ds_read_b128 v[224:227], v166 offset:35840
	ds_read_b128 v[228:231], v166 offset:36864
	ds_read_b128 v[232:235], v166 offset:37888
	ds_read_b128 v[236:239], v166 offset:38912
	ds_read_b128 v[240:243], v166 offset:39936
	global_load_lds_dwordx4 v[250:251], off
	v_lshl_add_u64 v[250:251], s[78:79], 0, v[132:133]
	s_mov_b32 m0, s80
	s_nop 0
	global_load_lds_dwordx4 v[250:251], off
	s_waitcnt vmcnt(8)
	s_waitcnt lgkmcnt(0)
	s_barrier
	s_setprio 3
	s_waitcnt lgkmcnt(0)
	v_mfma_f32_16x16x32_bf16 v[126:129], v[144:147], v[212:215], v[126:129]
	v_mfma_f32_16x16x32_bf16 v[122:125], v[172:175], v[212:215], v[122:125]
	v_mfma_f32_16x16x32_bf16 v[110:113], v[144:147], v[220:223], v[110:113]
	v_mfma_f32_16x16x32_bf16 v[106:109], v[172:175], v[220:223], v[106:109]
	v_mfma_f32_16x16x32_bf16 v[94:97], v[144:147], v[228:231], v[94:97]
	v_mfma_f32_16x16x32_bf16 v[90:93], v[172:175], v[228:231], v[90:93]
	v_mfma_f32_16x16x32_bf16 v[78:81], v[144:147], v[236:239], v[78:81]
	v_mfma_f32_16x16x32_bf16 v[74:77], v[172:175], v[236:239], v[74:77]
	v_mfma_f32_16x16x32_bf16 v[126:129], v[168:171], v[216:219], v[126:129]
	v_mfma_f32_16x16x32_bf16 v[122:125], v[192:195], v[216:219], v[122:125]
	v_mfma_f32_16x16x32_bf16 v[110:113], v[168:171], v[224:227], v[110:113]
	v_mfma_f32_16x16x32_bf16 v[106:109], v[192:195], v[224:227], v[106:109]
	v_mfma_f32_16x16x32_bf16 v[94:97], v[168:171], v[232:235], v[94:97]
	v_mfma_f32_16x16x32_bf16 v[90:93], v[192:195], v[232:235], v[90:93]
	v_mfma_f32_16x16x32_bf16 v[78:81], v[168:171], v[240:243], v[78:81]
	v_mfma_f32_16x16x32_bf16 v[74:77], v[192:195], v[240:243], v[74:77]
	s_setprio 0
	s_setprio 3
	v_mfma_f32_16x16x32_bf16 v[118:121], v[196:199], v[212:215], v[118:121]
	v_mfma_f32_16x16x32_bf16 v[114:117], v[204:207], v[212:215], v[114:117]
	v_mfma_f32_16x16x32_bf16 v[102:105], v[196:199], v[220:223], v[102:105]
	v_mfma_f32_16x16x32_bf16 v[98:101], v[204:207], v[220:223], v[98:101]
	v_mfma_f32_16x16x32_bf16 v[86:89], v[196:199], v[228:231], v[86:89]
	v_mfma_f32_16x16x32_bf16 v[82:85], v[204:207], v[228:231], v[82:85]
	v_mfma_f32_16x16x32_bf16 v[70:73], v[196:199], v[236:239], v[70:73]
	v_mfma_f32_16x16x32_bf16 v[66:69], v[204:207], v[236:239], v[66:69]
	v_mfma_f32_16x16x32_bf16 v[118:121], v[200:203], v[216:219], v[118:121]
	v_mfma_f32_16x16x32_bf16 v[114:117], v[208:211], v[216:219], v[114:117]
	v_mfma_f32_16x16x32_bf16 v[102:105], v[200:203], v[224:227], v[102:105]
	v_mfma_f32_16x16x32_bf16 v[98:101], v[208:211], v[224:227], v[98:101]
	v_mfma_f32_16x16x32_bf16 v[86:89], v[200:203], v[232:235], v[86:89]
	v_mfma_f32_16x16x32_bf16 v[82:85], v[208:211], v[232:235], v[82:85]
	v_mfma_f32_16x16x32_bf16 v[70:73], v[200:203], v[240:243], v[70:73]
	v_mfma_f32_16x16x32_bf16 v[66:69], v[208:211], v[240:243], v[66:69]
	s_setprio 0
	s_barrier
	s_add_i32 s73, s73, s40
	v_lshl_add_u64 v[176:177], v[176:177], 0, s[46:47]
	s_mov_b32 m0, s73
	ds_read_b128 v[212:215], v166 offset:49152
	ds_read_b128 v[216:219], v166 offset:50176
	ds_read_b128 v[220:223], v166 offset:51200
	ds_read_b128 v[224:227], v166 offset:52224
	ds_read_b128 v[228:231], v166 offset:53248
	ds_read_b128 v[232:235], v166 offset:54272
	ds_read_b128 v[236:239], v166 offset:55296
	ds_read_b128 v[240:243], v166 offset:56320
	global_load_lds_dwordx4 v[176:177], off
	s_add_i32 m0, s73, 0x2000
	s_add_u32 s76, s76, 0x10080
	v_lshl_add_u64 v[176:177], v[244:245], 0, s[46:47]
	s_addc_u32 s77, s77, 0
	s_add_i32 s73, s86, s40
	global_load_lds_dwordx4 v[176:177], off
	v_lshl_add_u64 v[176:177], s[76:77], 0, v[134:135]
	s_mov_b32 m0, s73
	s_nop 0
	global_load_lds_dwordx4 v[176:177], off
	v_lshl_add_u64 v[176:177], s[76:77], 0, v[130:131]
	s_add_i32 m0, s73, 0x2000
	s_nop 0
	global_load_lds_dwordx4 v[176:177], off
	v_lshl_add_u64 v[176:177], v[246:247], 0, s[46:47]
	s_mov_b32 m0, s82
	s_nop 0
	global_load_lds_dwordx4 v[176:177], off
	v_lshl_add_u64 v[176:177], v[248:249], 0, s[46:47]
	s_mov_b32 m0, s83
	s_nop 0
	global_load_lds_dwordx4 v[176:177], off
	s_waitcnt vmcnt(8)
	s_waitcnt lgkmcnt(0)
	s_barrier
; #define PG8_STAGE(bufoff, gbase, voff) do { _Pragma("unroll") for (int _i = 0; _i < 2; ++_i) \
;         __builtin_amdgcn_global_load_lds((const unsigned*)((const char*)(gbase) + (voff)[_i]), (LAS unsigned*)(lds + (bufoff) + ldsw + _i * 8192), 16, 0, 0); } while (0)
; #define PG8_BAR __builtin_amdgcn_s_barrier()
; __device__ __forceinline__ float row_rs4(const float* ssq, int row, int fq) {
;     const f32x4 a = *(const f32x4*)(ssq + (size_t)row * 16 + fq * 4);
;     float s = (a[0] + a[1]) + (a[2] + a[3]);
;     s += __shfl_xor(s, 16); s += __shfl_xor(s, 32);
;     return __builtin_amdgcn_rsqf(s * (1.0f / 1024.0f) + 1e-6f);
;     ...
;             PG8_WAIT_V(8); PG8_WAIT_L(0); PG8_BAR; PG8_MMA(0, 0, At, B0); PG8_MMA(0, 1, At, B1); PG8_BAR; PG8_SCHED;
;             PG8_LDA(At, 1, 1); PG8_STAGE(PG8_SB(1, 0), b3, voffB); PG8_STAGE(PG8_SB(1, 1), b3 + hstepB, voffB); PG8_STAGE(PG8_SA(1, 0), a3, voffA);
;             PG8_WAIT_V(8); PG8_WAIT_L(0); PG8_BAR; PG8_MMA(1, 0, At, B0); PG8_MMA(1, 1, At, B1); PG8_BAR; PG8_SCHED;
;             } else {
;             PG8_LDB(B0, 0, 0); PG8_SCHED; PG8_LDA(At, 0, 0); PG8_STAGE(PG8_SA(1, 1), a1 + hstepA, voffA);
;             PG8_WAIT_L(8); PG8_BAR; PG8_WAIT_L(0); PG8_MMA(0, 0, At, B0); PG8_BAR; PG8_SCHED;
;             PG8_LDB(B1, 0, 1); PG8_STAGE(PG8_SB(0, 0), b2, voffB);
;             PG8_BAR; PG8_WAIT_L(0); PG8_MMA(0, 1, At, B1); PG8_BAR;
;             PG8_LDA(At, 0, 1); PG8_STAGE(PG8_SA(0, 0), a2, voffA);
;             PG8_BAR; PG8_WAIT_L(0); PG8_MMA(1, 0, At, B0); PG8_BAR; PG8_SCHED;
;             PG8_STAGE(PG8_SB(0, 1), b2 + hstepB, voffB);
;             PG8_WAIT_V(6); PG8_BAR; PG8_MMA(1, 1, At, B1); PG8_BAR;
;             PG8_LDB(B0, 1, 0); PG8_SCHED; PG8_LDA(At, 1, 0); PG8_STAGE(PG8_SA(0, 1), a2 + hstepA, voffA);
;             PG8_WAIT_L(8); PG8_BAR; PG8_WAIT_L(0); PG8_MMA(0, 0, At, B0); PG8_BAR; PG8_SCHED;
;             PG8_LDB(B1, 1, 1); PG8_STAGE(PG8_SB(1, 0), b3, voffB);
;             PG8_BAR; PG8_WAIT_L(0); PG8_MMA(0, 1, At, B1); PG8_BAR;
;             PG8_LDA(At, 1, 1); PG8_STAGE(PG8_SA(1, 0), a3, voffA);
;             PG8_BAR; PG8_WAIT_L(0); PG8_MMA(1, 0, At, B0); PG8_BAR; PG8_SCHED;
;             PG8_STAGE(PG8_SB(1, 1), b3 + hstepB, voffB);
;             PG8_WAIT_V(6); PG8_BAR; PG8_MMA(1, 1, At, B1); PG8_BAR;
;             }
;         }
;         if constexpr (ALIGN_EPI) { if (wr == 0) PG8_BAR; }
	s_setprio 3
	s_waitcnt lgkmcnt(0)
	v_mfma_f32_16x16x32_bf16 v[62:65], v[144:147], v[212:215], v[62:65]
	v_mfma_f32_16x16x32_bf16 v[58:61], v[172:175], v[212:215], v[58:61]
	v_mfma_f32_16x16x32_bf16 v[46:49], v[144:147], v[220:223], v[46:49]
	v_mfma_f32_16x16x32_bf16 v[42:45], v[172:175], v[220:223], v[42:45]
	v_mfma_f32_16x16x32_bf16 v[30:33], v[144:147], v[228:231], v[30:33]
	v_mfma_f32_16x16x32_bf16 v[26:29], v[172:175], v[228:231], v[26:29]
	v_mfma_f32_16x16x32_bf16 v[14:17], v[144:147], v[236:239], v[14:17]
	v_mfma_f32_16x16x32_bf16 v[10:13], v[172:175], v[236:239], v[10:13]
	v_mfma_f32_16x16x32_bf16 v[62:65], v[168:171], v[216:219], v[62:65]
	v_mfma_f32_16x16x32_bf16 v[58:61], v[192:195], v[216:219], v[58:61]
	v_mfma_f32_16x16x32_bf16 v[46:49], v[168:171], v[224:227], v[46:49]
	v_mfma_f32_16x16x32_bf16 v[42:45], v[192:195], v[224:227], v[42:45]
	v_mfma_f32_16x16x32_bf16 v[30:33], v[168:171], v[232:235], v[30:33]
	v_mfma_f32_16x16x32_bf16 v[26:29], v[192:195], v[232:235], v[26:29]
	v_mfma_f32_16x16x32_bf16 v[14:17], v[168:171], v[240:243], v[14:17]
	v_mfma_f32_16x16x32_bf16 v[10:13], v[192:195], v[240:243], v[10:13]
	s_setprio 0
	s_setprio 3
	v_mfma_f32_16x16x32_bf16 v[54:57], v[196:199], v[212:215], v[54:57]
	v_mfma_f32_16x16x32_bf16 v[50:53], v[204:207], v[212:215], v[50:53]
	v_mfma_f32_16x16x32_bf16 v[38:41], v[196:199], v[220:223], v[38:41]
	v_mfma_f32_16x16x32_bf16 v[34:37], v[204:207], v[220:223], v[34:37]
	v_mfma_f32_16x16x32_bf16 v[22:25], v[196:199], v[228:231], v[22:25]
	v_mfma_f32_16x16x32_bf16 v[18:21], v[204:207], v[228:231], v[18:21]
	v_mfma_f32_16x16x32_bf16 v[6:9], v[196:199], v[236:239], v[6:9]
	v_mfma_f32_16x16x32_bf16 v[2:5], v[204:207], v[236:239], v[2:5]
	v_mfma_f32_16x16x32_bf16 v[54:57], v[200:203], v[216:219], v[54:57]
	v_mfma_f32_16x16x32_bf16 v[50:53], v[208:211], v[216:219], v[50:53]
	v_mfma_f32_16x16x32_bf16 v[38:41], v[200:203], v[224:227], v[38:41]
	v_mfma_f32_16x16x32_bf16 v[34:37], v[208:211], v[224:227], v[34:37]
	v_mfma_f32_16x16x32_bf16 v[22:25], v[200:203], v[232:235], v[22:25]
	v_mfma_f32_16x16x32_bf16 v[18:21], v[208:211], v[232:235], v[18:21]
	v_mfma_f32_16x16x32_bf16 v[6:9], v[200:203], v[240:243], v[6:9]
	v_mfma_f32_16x16x32_bf16 v[2:5], v[208:211], v[240:243], v[2:5]
	s_setprio 0
	s_barrier
	s_add_i32 s61, s61, 2
	s_add_u32 s42, s42, 0x100
	s_addc_u32 s60, s60, 0
	s_add_u32 s74, s74, 0x100
	s_addc_u32 s75, s75, 0
	s_cmp_gt_u32 s61, 13
	s_cbranch_scc0 .LBB0_811
	v_lshl_add_u32 v232, s72, 8, v1
	v_ashrrev_i32_e32 v233, 31, v232
	v_lshlrev_b64 v[234:235], 6, v[232:233]
	v_lshl_add_u64 v[234:235], v[138:139], 0, v[234:235]
	global_load_dwordx4 v[192:195], v[234:235], off
	global_load_dwordx4 v[196:199], v[234:235], off offset:1024
	global_load_dwordx4 v[200:203], v[234:235], off offset:2048
	global_load_dwordx4 v[204:207], v[234:235], off offset:3072
	v_add_u32_e32 v232, 0x80, v232
	v_ashrrev_i32_e32 v233, 31, v232
	v_lshlrev_b64 v[234:235], 6, v[232:233]
	v_lshl_add_u64 v[234:235], v[138:139], 0, v[234:235]
	global_load_dwordx4 v[208:211], v[234:235], off
	global_load_dwordx4 v[212:215], v[234:235], off offset:1024
	global_load_dwordx4 v[216:219], v[234:235], off offset:2048
	global_load_dwordx4 v[220:223], v[234:235], off offset:3072
	v_xor_b32_e32 v176, 16, v182
	v_xor_b32_e32 v177, 32, v182
	v_lshlrev_b32_e32 v176, 2, v176
	v_lshlrev_b32_e32 v177, 2, v177
	s_and_b64 vcc, exec, s[6:7]
	s_cbranch_vccz .LBB0_814
	s_barrier
.LBB0_814:
	s_waitcnt vmcnt(0)
	v_add_f32_e32 v192, v192, v193
	v_add_f32_e32 v194, v194, v195
	v_add_f32_e32 v196, v196, v197
	v_add_f32_e32 v198, v198, v199
	v_add_f32_e32 v200, v200, v201
	v_add_f32_e32 v202, v202, v203
	v_add_f32_e32 v204, v204, v205
	v_add_f32_e32 v206, v206, v207
	v_add_f32_e32 v208, v208, v209
	v_add_f32_e32 v210, v210, v211
	v_add_f32_e32 v212, v212, v213
	v_add_f32_e32 v214, v214, v215
	v_add_f32_e32 v216, v216, v217
	v_add_f32_e32 v218, v218, v219
	v_add_f32_e32 v220, v220, v221
	v_add_f32_e32 v222, v222, v223
	v_add_f32_e32 v192, v192, v194
	v_add_f32_e32 v196, v196, v198
	v_add_f32_e32 v200, v200, v202
	v_add_f32_e32 v204, v204, v206
	v_add_f32_e32 v208, v208, v210
	v_add_f32_e32 v212, v212, v214
	v_add_f32_e32 v216, v216, v218
	v_add_f32_e32 v220, v220, v222
	ds_bpermute_b32 v224, v176, v192
	ds_bpermute_b32 v225, v176, v196
	ds_bpermute_b32 v226, v176, v200
	ds_bpermute_b32 v227, v176, v204
	ds_bpermute_b32 v228, v176, v208
	ds_bpermute_b32 v229, v176, v212
	ds_bpermute_b32 v230, v176, v216
	ds_bpermute_b32 v231, v176, v220
	s_waitcnt lgkmcnt(7)
	v_add_f32_e32 v192, v192, v224
	s_waitcnt lgkmcnt(6)
	v_add_f32_e32 v196, v196, v225
	s_waitcnt lgkmcnt(5)
	v_add_f32_e32 v200, v200, v226
	s_waitcnt lgkmcnt(4)
	v_add_f32_e32 v204, v204, v227
	s_waitcnt lgkmcnt(3)
	v_add_f32_e32 v208, v208, v228
	s_waitcnt lgkmcnt(2)
	v_add_f32_e32 v212, v212, v229
	s_waitcnt lgkmcnt(1)
	v_add_f32_e32 v216, v216, v230
	s_waitcnt lgkmcnt(0)
	v_add_f32_e32 v220, v220, v231
	ds_bpermute_b32 v224, v177, v192
	ds_bpermute_b32 v225, v177, v196
	ds_bpermute_b32 v226, v177, v200
	ds_bpermute_b32 v227, v177, v204
	ds_bpermute_b32 v228, v177, v208
	ds_bpermute_b32 v229, v177, v212
	ds_bpermute_b32 v230, v177, v216
	ds_bpermute_b32 v231, v177, v220
	s_waitcnt lgkmcnt(7)
	v_add_f32_e32 v192, v192, v224
	s_waitcnt lgkmcnt(6)
	v_add_f32_e32 v196, v196, v225
	s_waitcnt lgkmcnt(5)
	v_add_f32_e32 v200, v200, v226
	s_waitcnt lgkmcnt(4)
	v_add_f32_e32 v204, v204, v227
	s_waitcnt lgkmcnt(3)
	v_add_f32_e32 v208, v208, v228
	s_waitcnt lgkmcnt(2)
	v_add_f32_e32 v212, v212, v229
	s_waitcnt lgkmcnt(1)
	v_add_f32_e32 v216, v216, v230
	s_waitcnt lgkmcnt(0)
; __device__ __forceinline__ unsigned cvt_pk_bf16(float lo, float hi) { unsigned r; asm volatile("v_cvt_pk_bf16_f32 %0, %1, %2" : "=v"(r) : "v"(lo), "v"(hi)); return r; }
; __device__ __forceinline__ float row_rs4(const float* ssq, int row, int fq) {
;     const f32x4 a = *(const f32x4*)(ssq + (size_t)row * 16 + fq * 4);
;     float s = (a[0] + a[1]) + (a[2] + a[3]);
;     s += __shfl_xor(s, 16); s += __shfl_xor(s, 32);
;     return __builtin_amdgcn_rsqf(s * (1.0f / 1024.0f) + 1e-6f);
;     __device__ __forceinline__ void operator()(const f32x4 (&acc)[2][2][4][2], const Unit& u, int wr, int wc, int fr, int fq) const {
;         const int row0 = u.pm * BM + wr * 64 + fr, col0 = u.pn * BM + wc * 64 + 8 * fq;
; #pragma unroll
;         for (int ai = 0; ai < 2; ++ai)
; #pragma unroll
;             for (int m = 0; m < 4; ++m) {
;                 const int row = row0 + ai * HALF + m * 16; const float rs = row_rs4(ssq, row, fq);
; #pragma unroll
;                 for (int bj = 0; bj < 2; ++bj) {
;                     const f32x4 v0 = acc[ai][bj][m][0] * rs, v1 = acc[ai][bj][m][1] * rs;
;                     u32x4 w; w.x = cvt_pk_bf16(v0[0], v0[1]); w.y = cvt_pk_bf16(v0[2], v0[3]); w.z = cvt_pk_bf16(v1[0], v1[1]); w.w = cvt_pk_bf16(v1[2], v1[3]);
;                     *(u32x4*)(proj + (size_t)row * pitch + col0 + bj * 32) = w;
;                 }
	v_add_f32_e32 v220, v220, v231
	v_fmamk_f32 v192, v192, 0x3a800000, v179
	v_fmamk_f32 v196, v196, 0x3a800000, v179
	v_fmamk_f32 v200, v200, 0x3a800000, v179
	v_fmamk_f32 v204, v204, 0x3a800000, v179
	v_fmamk_f32 v208, v208, 0x3a800000, v179
	v_fmamk_f32 v212, v212, 0x3a800000, v179
	v_fmamk_f32 v216, v216, 0x3a800000, v179
	v_fmamk_f32 v220, v220, 0x3a800000, v179
	v_rsq_f32_e32 v192, v192
	v_rsq_f32_e32 v196, v196
	v_rsq_f32_e32 v200, v200
	v_rsq_f32_e32 v204, v204
	v_rsq_f32_e32 v208, v208
	v_rsq_f32_e32 v212, v212
	v_rsq_f32_e32 v216, v216
	v_rsq_f32_e32 v220, v220
	s_nop 0
	v_and_b32_e32 v147, 64, v182
	v_xor_b32_e32 v145, 16, v182
	v_add_u32_e32 v147, 64, v147
	v_cmp_lt_i32_e32 vcc, v145, v147
	v_lshl_add_u32 v144, s72, 8, v1
	v_lshl_or_b32 v146, s19, 8, v165
	v_cndmask_b32_e32 v145, v182, v145, vcc
	v_lshlrev_b32_e32 v167, 2, v145
	v_xor_b32_e32 v145, 32, v182
	v_cmp_lt_i32_e32 vcc, v145, v147
	v_ashrrev_i32_e32 v147, 31, v146
	s_mov_b64 s[72:73], -1
	v_cndmask_b32_e32 v145, v182, v145, vcc
	v_lshlrev_b32_e32 v168, 2, v145
	v_ashrrev_i32_e32 v145, 31, v144
	v_lshlrev_b64 v[170:171], 6, v[144:145]
	v_lshl_add_u64 v[170:171], v[138:139], 0, v[170:171]
	s_andn2_b64 vcc, exec, s[2:3]
	s_mov_b32 s42, 0x11808
	v_readlane_b32 s87, v254, 19
	s_nop 0
	v_mov_b32_e32 v170, v192
	s_nop 0
	v_pk_mul_f32 v[128:129], v[128:129], v[170:171] op_sel_hi:[1,0]
	v_pk_mul_f32 v[126:127], v[126:127], v[170:171] op_sel_hi:[1,0]
	v_pk_mul_f32 v[122:123], v[122:123], v[170:171] op_sel_hi:[1,0]
	v_pk_mul_f32 v[124:125], v[124:125], v[170:171] op_sel_hi:[1,0]
	v_cvt_pk_bf16_f32 v126, v126, v127
	v_cvt_pk_bf16_f32 v127, v128, v129
	v_cvt_pk_bf16_f32 v128, v122, v123
	v_mov_b64_e32 v[122:123], s[20:21]
	v_cvt_pk_bf16_f32 v129, v124, v125
	v_mad_i64_i32 v[172:173], s[34:35], v144, s92, v[122:123]
	v_lshlrev_b64 v[124:125], 1, v[146:147]
	v_lshl_add_u64 v[146:147], v[172:173], 0, v[124:125]
	v_pk_mul_f32 v[118:119], v[118:119], v[170:171] op_sel_hi:[1,0]
	global_store_dwordx4 v[146:147], v[126:129], off
	v_pk_mul_f32 v[120:121], v[120:121], v[170:171] op_sel_hi:[1,0]
	s_nop 0
	v_pk_mul_f32 v[126:127], v[116:117], v[170:171] op_sel_hi:[1,0]
	v_pk_mul_f32 v[116:117], v[114:115], v[170:171] op_sel_hi:[1,0]
	v_cvt_pk_bf16_f32 v114, v118, v119
	v_or_b32_e32 v118, 16, v144
	v_cvt_pk_bf16_f32 v115, v120, v121
	v_ashrrev_i32_e32 v119, 31, v118
	v_cvt_pk_bf16_f32 v116, v116, v117
	v_cvt_pk_bf16_f32 v117, v126, v127
	global_store_dwordx4 v[146:147], v[114:117], off offset:64
	s_nop 1
	v_lshlrev_b64 v[114:115], 6, v[118:119]
	v_lshl_add_u64 v[114:115], v[138:139], 0, v[114:115]
	s_nop 0
	v_mov_b32_e32 v114, v196
	s_nop 0
	v_pk_mul_f32 v[110:111], v[110:111], v[114:115] op_sel_hi:[1,0]
	v_pk_mul_f32 v[116:117], v[108:109], v[114:115] op_sel_hi:[1,0]
	v_pk_mul_f32 v[108:109], v[106:107], v[114:115] op_sel_hi:[1,0]
	v_cvt_pk_bf16_f32 v106, v110, v111
	v_mad_i64_i32 v[110:111], s[34:35], v118, s92, v[122:123]
	v_pk_mul_f32 v[112:113], v[112:113], v[114:115] op_sel_hi:[1,0]
	v_lshl_add_u64 v[110:111], v[110:111], 0, v[124:125]
	v_cvt_pk_bf16_f32 v107, v112, v113
	v_pk_mul_f32 v[102:103], v[102:103], v[114:115] op_sel_hi:[1,0]
	v_cvt_pk_bf16_f32 v108, v108, v109
	v_cvt_pk_bf16_f32 v109, v116, v117
	global_store_dwordx4 v[110:111], v[106:109], off
	v_pk_mul_f32 v[104:105], v[104:105], v[114:115] op_sel_hi:[1,0]
	s_nop 0
	v_pk_mul_f32 v[106:107], v[100:101], v[114:115] op_sel_hi:[1,0]
	v_pk_mul_f32 v[100:101], v[98:99], v[114:115] op_sel_hi:[1,0]
	v_cvt_pk_bf16_f32 v98, v102, v103
	v_or_b32_e32 v102, 32, v144
	v_cvt_pk_bf16_f32 v99, v104, v105
	v_ashrrev_i32_e32 v103, 31, v102
	v_cvt_pk_bf16_f32 v100, v100, v101
	v_cvt_pk_bf16_f32 v101, v106, v107
	global_store_dwordx4 v[110:111], v[98:101], off offset:64
	s_nop 1
	v_lshlrev_b64 v[98:99], 6, v[102:103]
	v_lshl_add_u64 v[98:99], v[138:139], 0, v[98:99]
	s_nop 0
	v_mov_b32_e32 v98, v200
	s_nop 0
	v_pk_mul_f32 v[94:95], v[94:95], v[98:99] op_sel_hi:[1,0]
	v_pk_mul_f32 v[100:101], v[92:93], v[98:99] op_sel_hi:[1,0]
	v_pk_mul_f32 v[92:93], v[90:91], v[98:99] op_sel_hi:[1,0]
	v_cvt_pk_bf16_f32 v90, v94, v95
	v_mad_i64_i32 v[94:95], s[34:35], v102, s92, v[122:123]
	v_pk_mul_f32 v[96:97], v[96:97], v[98:99] op_sel_hi:[1,0]
	v_lshl_add_u64 v[94:95], v[94:95], 0, v[124:125]
	v_cvt_pk_bf16_f32 v91, v96, v97
	v_pk_mul_f32 v[86:87], v[86:87], v[98:99] op_sel_hi:[1,0]
	v_cvt_pk_bf16_f32 v92, v92, v93
	v_cvt_pk_bf16_f32 v93, v100, v101
	global_store_dwordx4 v[94:95], v[90:93], off
	v_pk_mul_f32 v[88:89], v[88:89], v[98:99] op_sel_hi:[1,0]
	s_nop 0
	v_pk_mul_f32 v[90:91], v[84:85], v[98:99] op_sel_hi:[1,0]
	v_pk_mul_f32 v[84:85], v[82:83], v[98:99] op_sel_hi:[1,0]
	v_cvt_pk_bf16_f32 v82, v86, v87
	v_or_b32_e32 v86, 48, v144
	v_cvt_pk_bf16_f32 v83, v88, v89
	v_ashrrev_i32_e32 v87, 31, v86
	v_cvt_pk_bf16_f32 v84, v84, v85
	v_cvt_pk_bf16_f32 v85, v90, v91
	global_store_dwordx4 v[94:95], v[82:85], off offset:64
	s_nop 1
	v_lshlrev_b64 v[82:83], 6, v[86:87]
	v_lshl_add_u64 v[82:83], v[138:139], 0, v[82:83]
	s_nop 0
	v_mov_b32_e32 v82, v204
	s_nop 0
	v_pk_mul_f32 v[78:79], v[78:79], v[82:83] op_sel_hi:[1,0]
	v_pk_mul_f32 v[84:85], v[76:77], v[82:83] op_sel_hi:[1,0]
	v_pk_mul_f32 v[76:77], v[74:75], v[82:83] op_sel_hi:[1,0]
	v_cvt_pk_bf16_f32 v74, v78, v79
	v_mad_i64_i32 v[78:79], s[34:35], v86, s92, v[122:123]
	v_pk_mul_f32 v[80:81], v[80:81], v[82:83] op_sel_hi:[1,0]
; __device__ __forceinline__ unsigned cvt_pk_bf16(float lo, float hi) { unsigned r; asm volatile("v_cvt_pk_bf16_f32 %0, %1, %2" : "=v"(r) : "v"(lo), "v"(hi)); return r; }
; #define PG8_BAR __builtin_amdgcn_s_barrier()
;     ...
;         if (!has_next) break;
; #pragma unroll
;         for (int a = 0; a < 2; ++a)
; #pragma unroll
;             for (int b = 0; b < 2; ++b)
; #pragma unroll
;                 for (int m = 0; m < 4; ++m)
; #pragma unroll
;                     for (int n = 0; n < 2; ++n) acc[a][b][m][n] = (f32x4){0.f, 0.f, 0.f, 0.f};
;         cur = nxt; cA = nA; cB = nB; ++ui;
;         if constexpr (ALIGN_EPI) { if (wr == 1) PG8_BAR; }
;     __device__ __forceinline__ void operator()(const f32x4 (&acc)[2][2][4][2], const Unit& u, int wr, int wc, int fr, int fq) const {
;         const int row0 = u.pm * BM + wr * 64 + fr, col0 = u.pn * BM + wc * 64 + 8 * fq;
; #pragma unroll
;         for (int ai = 0; ai < 2; ++ai)
; #pragma unroll
;             for (int m = 0; m < 4; ++m) {
;                 const int row = row0 + ai * HALF + m * 16; const float rs = row_rs4(ssq, row, fq);
; #pragma unroll
;                 for (int bj = 0; bj < 2; ++bj) {
;                     const f32x4 v0 = acc[ai][bj][m][0] * rs, v1 = acc[ai][bj][m][1] * rs;
;                     u32x4 w; w.x = cvt_pk_bf16(v0[0], v0[1]); w.y = cvt_pk_bf16(v0[2], v0[3]); w.z = cvt_pk_bf16(v1[0], v1[1]); w.w = cvt_pk_bf16(v1[2], v1[3]);
;                     *(u32x4*)(proj + (size_t)row * pitch + col0 + bj * 32) = w;
;                 }
;             }
	v_lshl_add_u64 v[78:79], v[78:79], 0, v[124:125]
	v_cvt_pk_bf16_f32 v75, v80, v81
	v_pk_mul_f32 v[70:71], v[70:71], v[82:83] op_sel_hi:[1,0]
	v_cvt_pk_bf16_f32 v76, v76, v77
	v_cvt_pk_bf16_f32 v77, v84, v85
	global_store_dwordx4 v[78:79], v[74:77], off
	v_pk_mul_f32 v[72:73], v[72:73], v[82:83] op_sel_hi:[1,0]
	s_nop 0
	v_pk_mul_f32 v[74:75], v[68:69], v[82:83] op_sel_hi:[1,0]
	v_pk_mul_f32 v[68:69], v[66:67], v[82:83] op_sel_hi:[1,0]
	v_cvt_pk_bf16_f32 v66, v70, v71
	v_add_u32_e32 v70, 0x80, v144
	v_cvt_pk_bf16_f32 v67, v72, v73
	v_ashrrev_i32_e32 v71, 31, v70
	v_cvt_pk_bf16_f32 v68, v68, v69
	v_cvt_pk_bf16_f32 v69, v74, v75
	global_store_dwordx4 v[78:79], v[66:69], off offset:64
	s_nop 1
	v_lshlrev_b64 v[66:67], 6, v[70:71]
	v_lshl_add_u64 v[66:67], v[138:139], 0, v[66:67]
	s_nop 0
	v_mov_b32_e32 v66, v208
	s_nop 0
	v_pk_mul_f32 v[62:63], v[62:63], v[66:67] op_sel_hi:[1,0]
	v_pk_mul_f32 v[68:69], v[60:61], v[66:67] op_sel_hi:[1,0]
	v_pk_mul_f32 v[60:61], v[58:59], v[66:67] op_sel_hi:[1,0]
	v_cvt_pk_bf16_f32 v58, v62, v63
	v_mad_i64_i32 v[62:63], s[34:35], v70, s92, v[122:123]
	v_pk_mul_f32 v[64:65], v[64:65], v[66:67] op_sel_hi:[1,0]
	v_lshl_add_u64 v[62:63], v[62:63], 0, v[124:125]
	v_cvt_pk_bf16_f32 v59, v64, v65
	v_pk_mul_f32 v[54:55], v[54:55], v[66:67] op_sel_hi:[1,0]
	v_cvt_pk_bf16_f32 v60, v60, v61
	v_cvt_pk_bf16_f32 v61, v68, v69
	global_store_dwordx4 v[62:63], v[58:61], off
	v_pk_mul_f32 v[56:57], v[56:57], v[66:67] op_sel_hi:[1,0]
	s_nop 0
	v_pk_mul_f32 v[58:59], v[52:53], v[66:67] op_sel_hi:[1,0]
	v_pk_mul_f32 v[52:53], v[50:51], v[66:67] op_sel_hi:[1,0]
	v_cvt_pk_bf16_f32 v50, v54, v55
	v_add_u32_e32 v54, 0x90, v144
	v_cvt_pk_bf16_f32 v51, v56, v57
	v_ashrrev_i32_e32 v55, 31, v54
	v_cvt_pk_bf16_f32 v52, v52, v53
	v_cvt_pk_bf16_f32 v53, v58, v59
	global_store_dwordx4 v[62:63], v[50:53], off offset:64
	s_nop 1
	v_lshlrev_b64 v[50:51], 6, v[54:55]
	v_lshl_add_u64 v[50:51], v[138:139], 0, v[50:51]
	s_nop 0
	v_mov_b32_e32 v50, v212
	s_nop 0
	v_pk_mul_f32 v[46:47], v[46:47], v[50:51] op_sel_hi:[1,0]
	v_pk_mul_f32 v[52:53], v[44:45], v[50:51] op_sel_hi:[1,0]
	v_pk_mul_f32 v[44:45], v[42:43], v[50:51] op_sel_hi:[1,0]
	v_cvt_pk_bf16_f32 v42, v46, v47
	v_mad_i64_i32 v[46:47], s[34:35], v54, s92, v[122:123]
	v_pk_mul_f32 v[48:49], v[48:49], v[50:51] op_sel_hi:[1,0]
	v_lshl_add_u64 v[46:47], v[46:47], 0, v[124:125]
	v_cvt_pk_bf16_f32 v43, v48, v49
	v_pk_mul_f32 v[38:39], v[38:39], v[50:51] op_sel_hi:[1,0]
	v_cvt_pk_bf16_f32 v44, v44, v45
	v_cvt_pk_bf16_f32 v45, v52, v53
	global_store_dwordx4 v[46:47], v[42:45], off
	v_pk_mul_f32 v[40:41], v[40:41], v[50:51] op_sel_hi:[1,0]
	s_nop 0
	v_pk_mul_f32 v[42:43], v[36:37], v[50:51] op_sel_hi:[1,0]
	v_pk_mul_f32 v[36:37], v[34:35], v[50:51] op_sel_hi:[1,0]
	v_cvt_pk_bf16_f32 v34, v38, v39
	v_add_u32_e32 v38, 0xa0, v144
	v_cvt_pk_bf16_f32 v35, v40, v41
	v_ashrrev_i32_e32 v39, 31, v38
	v_cvt_pk_bf16_f32 v36, v36, v37
	v_cvt_pk_bf16_f32 v37, v42, v43
	global_store_dwordx4 v[46:47], v[34:37], off offset:64
	s_nop 1
	v_lshlrev_b64 v[34:35], 6, v[38:39]
	v_lshl_add_u64 v[34:35], v[138:139], 0, v[34:35]
	s_nop 0
	v_mov_b32_e32 v34, v216
	s_nop 0
	v_pk_mul_f32 v[30:31], v[30:31], v[34:35] op_sel_hi:[1,0]
	v_pk_mul_f32 v[36:37], v[28:29], v[34:35] op_sel_hi:[1,0]
	v_pk_mul_f32 v[28:29], v[26:27], v[34:35] op_sel_hi:[1,0]
	v_cvt_pk_bf16_f32 v26, v30, v31
	v_mad_i64_i32 v[30:31], s[34:35], v38, s92, v[122:123]
	v_pk_mul_f32 v[32:33], v[32:33], v[34:35] op_sel_hi:[1,0]
	v_lshl_add_u64 v[30:31], v[30:31], 0, v[124:125]
	v_cvt_pk_bf16_f32 v27, v32, v33
	v_pk_mul_f32 v[22:23], v[22:23], v[34:35] op_sel_hi:[1,0]
	v_cvt_pk_bf16_f32 v28, v28, v29
	v_cvt_pk_bf16_f32 v29, v36, v37
	global_store_dwordx4 v[30:31], v[26:29], off
	v_pk_mul_f32 v[24:25], v[24:25], v[34:35] op_sel_hi:[1,0]
	s_nop 0
	v_pk_mul_f32 v[26:27], v[20:21], v[34:35] op_sel_hi:[1,0]
	v_pk_mul_f32 v[20:21], v[18:19], v[34:35] op_sel_hi:[1,0]
	v_cvt_pk_bf16_f32 v18, v22, v23
	v_add_u32_e32 v22, 0xb0, v144
	v_cvt_pk_bf16_f32 v19, v24, v25
	v_ashrrev_i32_e32 v23, 31, v22
	v_cvt_pk_bf16_f32 v20, v20, v21
	v_cvt_pk_bf16_f32 v21, v26, v27
	global_store_dwordx4 v[30:31], v[18:21], off offset:64
	s_nop 1
	v_lshlrev_b64 v[18:19], 6, v[22:23]
	v_lshl_add_u64 v[18:19], v[138:139], 0, v[18:19]
	s_nop 0
	v_mov_b32_e32 v18, v220
	s_nop 0
	v_pk_mul_f32 v[14:15], v[14:15], v[18:19] op_sel_hi:[1,0]
	v_pk_mul_f32 v[20:21], v[12:13], v[18:19] op_sel_hi:[1,0]
	v_pk_mul_f32 v[12:13], v[10:11], v[18:19] op_sel_hi:[1,0]
	v_cvt_pk_bf16_f32 v10, v14, v15
	v_mad_i64_i32 v[14:15], s[34:35], v22, s92, v[122:123]
	v_pk_mul_f32 v[16:17], v[16:17], v[18:19] op_sel_hi:[1,0]
	v_lshl_add_u64 v[14:15], v[14:15], 0, v[124:125]
	v_cvt_pk_bf16_f32 v11, v16, v17
	v_cvt_pk_bf16_f32 v12, v12, v13
	v_cvt_pk_bf16_f32 v13, v20, v21
	global_store_dwordx4 v[14:15], v[10:13], off
	v_pk_mul_f32 v[8:9], v[8:9], v[18:19] op_sel_hi:[1,0]
	v_pk_mul_f32 v[6:7], v[6:7], v[18:19] op_sel_hi:[1,0]
	v_pk_mul_f32 v[10:11], v[4:5], v[18:19] op_sel_hi:[1,0]
	v_pk_mul_f32 v[4:5], v[2:3], v[18:19] op_sel_hi:[1,0]
	v_cvt_pk_bf16_f32 v2, v6, v7
	v_cvt_pk_bf16_f32 v3, v8, v9
	s_nop 0
	v_cvt_pk_bf16_f32 v4, v4, v5
	v_cvt_pk_bf16_f32 v5, v10, v11
	global_store_dwordx4 v[14:15], v[2:5], off offset:64
	s_cbranch_vccnz .LBB0_807
	s_andn2_b64 vcc, exec, s[4:5]
	s_cbranch_vccnz .LBB0_806
	s_barrier
	s_branch .LBB0_806

;     ...
;         for (int a = 0; a < 2; ++a)
; #pragma unroll
;             for (int b = 0; b < 2; ++b)
; #pragma unroll
;                 for (int m = 0; m < 4; ++m)
; #pragma unroll
;                     for (int n = 0; n < 2; ++n) acc[a][b][m][n] = (f32x4){0.f, 0.f, 0.f, 0.f};
;         cur = nxt; cA = nA; cB = nB; ++ui;
.LBB0_841:
	s_add_u32 s83, s78, 0x100
	s_addc_u32 vcc_lo, s79, 0
	s_add_u32 s78, s80, 0x80
	v_mov_b32_e32 v2, 0
	s_addc_u32 s79, s81, 0
	s_mov_b32 s80, 0
	s_waitcnt lgkmcnt(0)
	v_mov_b32_e32 v3, v2
	v_mov_b32_e32 v4, v2
	v_mov_b32_e32 v5, v2
	v_mov_b32_e32 v6, v2
	v_mov_b32_e32 v7, v2
	v_mov_b32_e32 v8, v2
	v_mov_b32_e32 v9, v2
	v_mov_b32_e32 v18, v2
	v_mov_b32_e32 v19, v2
	v_mov_b32_e32 v20, v2
	v_mov_b32_e32 v21, v2
	v_mov_b32_e32 v22, v2
	v_mov_b32_e32 v23, v2
	v_mov_b32_e32 v24, v2
	v_mov_b32_e32 v25, v2
	v_mov_b32_e32 v34, v2
	v_mov_b32_e32 v35, v2
	v_mov_b32_e32 v36, v2
	v_mov_b32_e32 v37, v2
	v_mov_b32_e32 v38, v2
	v_mov_b32_e32 v39, v2
	v_mov_b32_e32 v40, v2
	v_mov_b32_e32 v41, v2
	v_mov_b32_e32 v50, v2
	v_mov_b32_e32 v51, v2
	v_mov_b32_e32 v52, v2
	v_mov_b32_e32 v53, v2
	v_mov_b32_e32 v54, v2
	v_mov_b32_e32 v55, v2
	v_mov_b32_e32 v56, v2
	v_mov_b32_e32 v57, v2
	v_mov_b32_e32 v10, v2
	v_mov_b32_e32 v11, v2
	v_mov_b32_e32 v12, v2
	v_mov_b32_e32 v13, v2
	v_mov_b32_e32 v14, v2
	v_mov_b32_e32 v15, v2
	v_mov_b32_e32 v16, v2
	v_mov_b32_e32 v17, v2
	v_mov_b32_e32 v26, v2
	v_mov_b32_e32 v27, v2
	v_mov_b32_e32 v28, v2
	v_mov_b32_e32 v29, v2
	v_mov_b32_e32 v30, v2
	v_mov_b32_e32 v31, v2
	v_mov_b32_e32 v32, v2
	v_mov_b32_e32 v33, v2
	v_mov_b32_e32 v42, v2
	v_mov_b32_e32 v43, v2
	v_mov_b32_e32 v44, v2
	v_mov_b32_e32 v45, v2
	v_mov_b32_e32 v46, v2
	v_mov_b32_e32 v47, v2
	v_mov_b32_e32 v48, v2
	v_mov_b32_e32 v49, v2
	v_mov_b32_e32 v58, v2
	v_mov_b32_e32 v59, v2
	v_mov_b32_e32 v60, v2
	v_mov_b32_e32 v61, v2
	v_mov_b32_e32 v62, v2
	v_mov_b32_e32 v63, v2
	v_mov_b32_e32 v64, v2
	v_mov_b32_e32 v65, v2
	v_mov_b32_e32 v66, v2
	v_mov_b32_e32 v67, v2
	v_mov_b32_e32 v68, v2
	v_mov_b32_e32 v69, v2
	v_mov_b32_e32 v70, v2
	v_mov_b32_e32 v71, v2
	v_mov_b32_e32 v72, v2
	v_mov_b32_e32 v73, v2
	v_mov_b32_e32 v82, v2
	v_mov_b32_e32 v83, v2
	v_mov_b32_e32 v84, v2
	v_mov_b32_e32 v85, v2
	v_mov_b32_e32 v86, v2
	v_mov_b32_e32 v87, v2
	v_mov_b32_e32 v88, v2
	v_mov_b32_e32 v89, v2
	v_mov_b32_e32 v98, v2
	v_mov_b32_e32 v99, v2
	v_mov_b32_e32 v100, v2
	v_mov_b32_e32 v101, v2
	v_mov_b32_e32 v102, v2
	v_mov_b32_e32 v103, v2
	v_mov_b32_e32 v104, v2
	v_mov_b32_e32 v105, v2
	v_mov_b32_e32 v114, v2
	v_mov_b32_e32 v115, v2
	v_mov_b32_e32 v116, v2
	v_mov_b32_e32 v117, v2
	v_mov_b32_e32 v118, v2
	v_mov_b32_e32 v119, v2
	v_mov_b32_e32 v120, v2
	v_mov_b32_e32 v121, v2
	v_mov_b32_e32 v74, v2
	v_mov_b32_e32 v75, v2
	v_mov_b32_e32 v76, v2
	v_mov_b32_e32 v77, v2
	v_mov_b32_e32 v78, v2
	v_mov_b32_e32 v79, v2
	v_mov_b32_e32 v80, v2
	v_mov_b32_e32 v81, v2
	v_mov_b32_e32 v90, v2
	v_mov_b32_e32 v91, v2
	v_mov_b32_e32 v92, v2
	v_mov_b32_e32 v93, v2
	v_mov_b32_e32 v94, v2
	v_mov_b32_e32 v95, v2
	v_mov_b32_e32 v96, v2
	v_mov_b32_e32 v97, v2
	v_mov_b32_e32 v106, v2
	v_mov_b32_e32 v107, v2
	v_mov_b32_e32 v108, v2
	v_mov_b32_e32 v109, v2
	v_mov_b32_e32 v110, v2
	v_mov_b32_e32 v111, v2
	v_mov_b32_e32 v112, v2
	v_mov_b32_e32 v113, v2
	v_mov_b32_e32 v122, v2
	v_mov_b32_e32 v123, v2
	v_mov_b32_e32 v124, v2
	v_mov_b32_e32 v125, v2
	v_mov_b32_e32 v126, v2
	v_mov_b32_e32 v127, v2
	v_mov_b32_e32 v128, v2
	v_mov_b32_e32 v129, v2
	s_waitcnt vmcnt(0)

;     ...
;         const bool has_next = S.next(ui + 1, nxt);
;         const char* nA = has_next ? (const char*)g.A + (size_t)nxt.pm * tstepA : cA; const char* nB = has_next ? (const char*)g.Bt + (size_t)nxt.pn * tstepB : cB;
;         for (int t = 0; t < nt; t += 2) {
;             const bool last = (t == nt - 2);
;             const char* a1 = cA + (size_t)(t + 1) * kstep;
;             const char* a2 = last ? nA : cA + (size_t)(t + 2) * kstep; const char* b2 = last ? nB : cB + (size_t)(t + 2) * kstep;
;     ...
;         for (int a = 0; a < 2; ++a)
; #pragma unroll
;             for (int b = 0; b < 2; ++b)
; #pragma unroll
;                 for (int m = 0; m < 4; ++m)
; #pragma unroll
;                     for (int n = 0; n < 2; ++n) acc[a][b][m][n] = (f32x4){0.f, 0.f, 0.f, 0.f};
.LBB0_876:
	s_ashr_i32 s11, s10, 31
	s_lshl_b64 s[12:13], s[10:11], 19
	s_add_u32 s12, s24, s12
	s_addc_u32 s13, s25, s13
	s_and_b64 s[16:17], s[2:3], exec
	s_cselect_b32 s11, s13, s35
	s_cselect_b32 s72, s12, s34
	s_ashr_i32 s9, s8, 31
	s_lshl_b64 s[16:17], s[8:9], 19
	s_add_u32 s16, s40, s16
	s_addc_u32 s17, s64, s17
	s_and_b64 s[26:27], s[2:3], exec
	s_cselect_b32 s9, s17, s31
	s_cselect_b32 s73, s16, s30
	s_add_u32 s74, s30, 0x100
	s_addc_u32 s75, s31, 0
	s_add_u32 s26, s34, 0x40080
	v_mov_b32_e32 v2, 0
	s_addc_u32 s27, s35, 0
	s_mov_b32 s76, -2
	v_mov_b32_e32 v3, v2
	v_mov_b32_e32 v4, v2
	v_mov_b32_e32 v5, v2
	v_mov_b32_e32 v14, v2
	v_mov_b32_e32 v15, v2
	v_mov_b32_e32 v16, v2
	v_mov_b32_e32 v17, v2
	v_mov_b32_e32 v22, v2
	v_mov_b32_e32 v23, v2
	v_mov_b32_e32 v24, v2
	v_mov_b32_e32 v25, v2
	v_mov_b32_e32 v30, v2
	v_mov_b32_e32 v31, v2
	v_mov_b32_e32 v32, v2
	v_mov_b32_e32 v33, v2
	v_mov_b32_e32 v38, v2
	v_mov_b32_e32 v39, v2
	v_mov_b32_e32 v40, v2
	v_mov_b32_e32 v41, v2
	v_mov_b32_e32 v46, v2
	v_mov_b32_e32 v47, v2
	v_mov_b32_e32 v48, v2
	v_mov_b32_e32 v49, v2
	v_mov_b32_e32 v54, v2
	v_mov_b32_e32 v55, v2
	v_mov_b32_e32 v56, v2
	v_mov_b32_e32 v57, v2
	v_mov_b32_e32 v62, v2
	v_mov_b32_e32 v63, v2
	v_mov_b32_e32 v64, v2
	v_mov_b32_e32 v65, v2
	v_mov_b32_e32 v6, v2
	v_mov_b32_e32 v7, v2
	v_mov_b32_e32 v8, v2
	v_mov_b32_e32 v9, v2
	v_mov_b32_e32 v10, v2
	v_mov_b32_e32 v11, v2
	v_mov_b32_e32 v12, v2
	v_mov_b32_e32 v13, v2
	v_mov_b32_e32 v18, v2
	v_mov_b32_e32 v19, v2
	v_mov_b32_e32 v20, v2
	v_mov_b32_e32 v21, v2
	v_mov_b32_e32 v26, v2
	v_mov_b32_e32 v27, v2
	v_mov_b32_e32 v28, v2
	v_mov_b32_e32 v29, v2
	v_mov_b32_e32 v34, v2
	v_mov_b32_e32 v35, v2
	v_mov_b32_e32 v36, v2
	v_mov_b32_e32 v37, v2
	v_mov_b32_e32 v42, v2
	v_mov_b32_e32 v43, v2
	v_mov_b32_e32 v44, v2
	v_mov_b32_e32 v45, v2
	v_mov_b32_e32 v50, v2
	v_mov_b32_e32 v51, v2
	v_mov_b32_e32 v52, v2
	v_mov_b32_e32 v53, v2
	v_mov_b32_e32 v58, v2
	v_mov_b32_e32 v59, v2
	v_mov_b32_e32 v60, v2
	v_mov_b32_e32 v61, v2
	v_mov_b32_e32 v70, v2
	v_mov_b32_e32 v71, v2
	v_mov_b32_e32 v72, v2
	v_mov_b32_e32 v73, v2
	v_mov_b32_e32 v78, v2
	v_mov_b32_e32 v79, v2
	v_mov_b32_e32 v80, v2
	v_mov_b32_e32 v81, v2
	v_mov_b32_e32 v86, v2
	v_mov_b32_e32 v87, v2
	v_mov_b32_e32 v88, v2
	v_mov_b32_e32 v89, v2
	v_mov_b32_e32 v94, v2
	v_mov_b32_e32 v95, v2
	v_mov_b32_e32 v96, v2
	v_mov_b32_e32 v97, v2
	v_mov_b32_e32 v102, v2
	v_mov_b32_e32 v103, v2
	v_mov_b32_e32 v104, v2
	v_mov_b32_e32 v105, v2
	v_mov_b32_e32 v110, v2
	v_mov_b32_e32 v111, v2
	v_mov_b32_e32 v112, v2
	v_mov_b32_e32 v113, v2
	v_mov_b32_e32 v122, v2
	v_mov_b32_e32 v123, v2
	v_mov_b32_e32 v124, v2
	v_mov_b32_e32 v125, v2
	v_mov_b32_e32 v126, v2
	v_mov_b32_e32 v127, v2
	v_mov_b32_e32 v128, v2
	v_mov_b32_e32 v129, v2
	v_mov_b32_e32 v66, v2
	v_mov_b32_e32 v67, v2
	v_mov_b32_e32 v68, v2
	v_mov_b32_e32 v69, v2
	v_mov_b32_e32 v74, v2
	v_mov_b32_e32 v75, v2
	v_mov_b32_e32 v76, v2
	v_mov_b32_e32 v77, v2
	v_mov_b32_e32 v82, v2
	v_mov_b32_e32 v83, v2
	v_mov_b32_e32 v84, v2
	v_mov_b32_e32 v85, v2
	v_mov_b32_e32 v90, v2
	v_mov_b32_e32 v91, v2
	v_mov_b32_e32 v92, v2
	v_mov_b32_e32 v93, v2
	v_mov_b32_e32 v98, v2
	v_mov_b32_e32 v99, v2
	v_mov_b32_e32 v100, v2
	v_mov_b32_e32 v101, v2
	v_mov_b32_e32 v106, v2
	v_mov_b32_e32 v107, v2
	v_mov_b32_e32 v108, v2
	v_mov_b32_e32 v109, v2
	v_mov_b32_e32 v114, v2
	v_mov_b32_e32 v115, v2
	v_mov_b32_e32 v116, v2
	v_mov_b32_e32 v117, v2
	v_mov_b32_e32 v118, v2
	v_mov_b32_e32 v119, v2
	v_mov_b32_e32 v120, v2
	v_mov_b32_e32 v121, v2
	s_waitcnt vmcnt(0)

;     ...
;         const bool has_next = S.next(ui + 1, nxt);
;         const char* nA = has_next ? (const char*)g.A + (size_t)nxt.pm * tstepA : cA; const char* nB = has_next ? (const char*)g.Bt + (size_t)nxt.pn * tstepB : cB;
;         for (int t = 0; t < nt; t += 2) {
;             const bool last = (t == nt - 2);
;             const char* a1 = cA + (size_t)(t + 1) * kstep;
;             const char* a2 = last ? nA : cA + (size_t)(t + 2) * kstep; const char* b2 = last ? nB : cB + (size_t)(t + 2) * kstep;
;     ...
;         for (int a = 0; a < 2; ++a)
; #pragma unroll
;             for (int b = 0; b < 2; ++b)
; #pragma unroll
;                 for (int m = 0; m < 4; ++m)
; #pragma unroll
;                     for (int n = 0; n < 2; ++n) acc[a][b][m][n] = (f32x4){0.f, 0.f, 0.f, 0.f};
.LBB0_898:
	s_ashr_i32 s11, s10, 31
	s_lshl_b64 s[16:17], s[10:11], 19
	s_add_u32 s16, s34, s16
	s_addc_u32 s17, s19, s17
	s_and_b64 s[4:5], s[4:5], exec
	s_cselect_b32 s11, s17, s27
	s_cselect_b32 s61, s16, s26
	s_add_u32 s74, s26, 0x100
	v_mov_b32_e32 v2, 0
	s_addc_u32 s75, s27, 0
	s_mov_b32 s76, -2
	v_mov_b32_e32 v3, v2
	v_mov_b32_e32 v4, v2
	v_mov_b32_e32 v5, v2
	v_mov_b32_e32 v6, v2
	v_mov_b32_e32 v7, v2
	v_mov_b32_e32 v8, v2
	v_mov_b32_e32 v9, v2
	v_mov_b32_e32 v18, v2
	v_mov_b32_e32 v19, v2
	v_mov_b32_e32 v20, v2
	v_mov_b32_e32 v21, v2
	v_mov_b32_e32 v22, v2
	v_mov_b32_e32 v23, v2
	v_mov_b32_e32 v24, v2
	v_mov_b32_e32 v25, v2
	v_mov_b32_e32 v34, v2
	v_mov_b32_e32 v35, v2
	v_mov_b32_e32 v36, v2
	v_mov_b32_e32 v37, v2
	v_mov_b32_e32 v38, v2
	v_mov_b32_e32 v39, v2
	v_mov_b32_e32 v40, v2
	v_mov_b32_e32 v41, v2
	v_mov_b32_e32 v50, v2
	v_mov_b32_e32 v51, v2
	v_mov_b32_e32 v52, v2
	v_mov_b32_e32 v53, v2
	v_mov_b32_e32 v54, v2
	v_mov_b32_e32 v55, v2
	v_mov_b32_e32 v56, v2
	v_mov_b32_e32 v57, v2
	v_mov_b32_e32 v10, v2
	v_mov_b32_e32 v11, v2
	v_mov_b32_e32 v12, v2
	v_mov_b32_e32 v13, v2
	v_mov_b32_e32 v14, v2
	v_mov_b32_e32 v15, v2
	v_mov_b32_e32 v16, v2
	v_mov_b32_e32 v17, v2
	v_mov_b32_e32 v26, v2
	v_mov_b32_e32 v27, v2
	v_mov_b32_e32 v28, v2
	v_mov_b32_e32 v29, v2
	v_mov_b32_e32 v30, v2
	v_mov_b32_e32 v31, v2
	v_mov_b32_e32 v32, v2
	v_mov_b32_e32 v33, v2
	v_mov_b32_e32 v42, v2
	v_mov_b32_e32 v43, v2
	v_mov_b32_e32 v44, v2
	v_mov_b32_e32 v45, v2
	v_mov_b32_e32 v46, v2
	v_mov_b32_e32 v47, v2
	v_mov_b32_e32 v48, v2
	v_mov_b32_e32 v49, v2
	v_mov_b32_e32 v58, v2
	v_mov_b32_e32 v59, v2
	v_mov_b32_e32 v60, v2
	v_mov_b32_e32 v61, v2
	v_mov_b32_e32 v62, v2
	v_mov_b32_e32 v63, v2
	v_mov_b32_e32 v64, v2
	v_mov_b32_e32 v65, v2
	v_mov_b32_e32 v66, v2
	v_mov_b32_e32 v67, v2
	v_mov_b32_e32 v68, v2
	v_mov_b32_e32 v69, v2
	v_mov_b32_e32 v70, v2
	v_mov_b32_e32 v71, v2
	v_mov_b32_e32 v72, v2
	v_mov_b32_e32 v73, v2
	v_mov_b32_e32 v82, v2
	v_mov_b32_e32 v83, v2
	v_mov_b32_e32 v84, v2
	v_mov_b32_e32 v85, v2
	v_mov_b32_e32 v86, v2
	v_mov_b32_e32 v87, v2
	v_mov_b32_e32 v88, v2
	v_mov_b32_e32 v89, v2
	v_mov_b32_e32 v98, v2
	v_mov_b32_e32 v99, v2
	v_mov_b32_e32 v100, v2
	v_mov_b32_e32 v101, v2
	v_mov_b32_e32 v102, v2
	v_mov_b32_e32 v103, v2
	v_mov_b32_e32 v104, v2
	v_mov_b32_e32 v105, v2
	v_mov_b32_e32 v114, v2
	v_mov_b32_e32 v115, v2
	v_mov_b32_e32 v116, v2
	v_mov_b32_e32 v117, v2
	v_mov_b32_e32 v118, v2
	v_mov_b32_e32 v119, v2
	v_mov_b32_e32 v120, v2
	v_mov_b32_e32 v121, v2
	v_mov_b32_e32 v74, v2
	v_mov_b32_e32 v75, v2
	v_mov_b32_e32 v76, v2
	v_mov_b32_e32 v77, v2
	v_mov_b32_e32 v78, v2
	v_mov_b32_e32 v79, v2
	v_mov_b32_e32 v80, v2
	v_mov_b32_e32 v81, v2
	v_mov_b32_e32 v90, v2
	v_mov_b32_e32 v91, v2
	v_mov_b32_e32 v92, v2
	v_mov_b32_e32 v93, v2
	v_mov_b32_e32 v94, v2
	v_mov_b32_e32 v95, v2
	v_mov_b32_e32 v96, v2
	v_mov_b32_e32 v97, v2
	v_mov_b32_e32 v106, v2
	v_mov_b32_e32 v107, v2
	v_mov_b32_e32 v108, v2
	v_mov_b32_e32 v109, v2
	v_mov_b32_e32 v110, v2
	v_mov_b32_e32 v111, v2
	v_mov_b32_e32 v112, v2
	v_mov_b32_e32 v113, v2
	v_mov_b32_e32 v122, v2
	v_mov_b32_e32 v123, v2
	v_mov_b32_e32 v124, v2
	v_mov_b32_e32 v125, v2
	v_mov_b32_e32 v126, v2
	v_mov_b32_e32 v127, v2
	v_mov_b32_e32 v128, v2
	v_mov_b32_e32 v129, v2
	s_waitcnt vmcnt(0)

; __global__ void __launch_bounds__(512) mega(Params p, int ph_lo, int ph_hi) {
;     ...
;     for (int ph = ph_lo; ph < ph_hi; ++ph) {
;     ...
;             } else if (kind == K_MIX1) {
;                 phase_attn(lds, proj, layer, NSEQ, ctl + layer * 16);
.LBB0_1025:
	v_readlane_b32 s2, v254, 1
	s_waitcnt lgkmcnt(0)
	s_add_i32 s40, s70, 1
	s_mov_b32 s2, 0x40040040
	s_mov_b32 s3, 0x400
	s_bitcmp1_b64 s[2:3], s40
	s_cbranch_scc0 .Lmy_noskip_mix1
	s_add_i32 s40, s40, 1
.Lmy_noskip_mix1:
	v_readlane_b32 s3, v254, 2
	s_cmp_ge_i32 s40, s3
	s_mov_b64 s[2:3], -1
	s_cbranch_scc0 .LBB0_1026
	s_getpc_b64 s[98:99]
